# v49 + GEMM K-loop hand-off: drop the duplicate lgkmcnt(0) between the barrier and the first MFMA of each burst (the pre-barrier wait already covers the fragment reads)
# speedup vs baseline: 1.0059x; 1.0059x over previous
; #define PG8_STAGE(bufoff, gbase, voff) do { _Pragma("unroll") for (int _i = 0; _i < 2; ++_i) \
;         __builtin_amdgcn_global_load_lds((const unsigned*)((const char*)(gbase) + (voff)[_i]), (PG8_LAS unsigned*)(lds + (bufoff) + ldsw + _i * 8192), 16, 0, 0); } while (0)
; #define PG8_LDA(dst, b, h) do { _Pragma("unroll") for (int m = 0; m < 4; ++m) _Pragma("unroll") for (int k = 0; k < 2; ++k) dst[m][k] = *(const PG8_LAS bf16x8*)(lds + PG8_SA(b, h) + aoff + m * 2048 + k * 1024); } while (0)
; #define PG8_LDB(dst, b, h) do { _Pragma("unroll") for (int n = 0; n < 2; ++n) _Pragma("unroll") for (int k = 0; k < 2; ++k) dst[n][k] = *(const PG8_LAS bf16x8*)(lds + PG8_SB(b, h) + boff + n * 2048 + k * 1024); } while (0)
; #define PG8_MMA(ai, bj, At, Bt) do { __builtin_amdgcn_s_setprio(1); _Pragma("unroll") for (int m = 0; m < 4; ++m) _Pragma("unroll") for (int n = 0; n < 2; ++n) _Pragma("unroll") for (int k = 0; k < 2; ++k) \
;         acc[ai][bj][m][n] = __builtin_amdgcn_mfma_f32_16x16x32_bf16(Bt[n][k], At[m][k], acc[ai][bj][m][n], 0, 0, 0); __builtin_amdgcn_s_setprio(0); } while (0)
; #define PG8_WAIT_V(n) asm volatile("s_waitcnt vmcnt(" #n ")" ::: "memory")
; #define PG8_BAR __builtin_amdgcn_s_barrier()
; template <class Epi, class Sched, bool ALIGN_EPI = false, bool SP2 = false>
; __device__ __forceinline__ void gemm_phase(PG8_LAS unsigned char* lds, const Gemm g, const Sched& S, const Epi& E) {
;     ...
;         for (int t = 0; t < nt; t += 2) {
;             const bool last = (t == nt - 2);
;             const char* a1 = cA + (size_t)(t + 1) * kstep;
;             const char* a2 = last ? nA : cA + (size_t)(t + 2) * kstep; const char* b2 = last ? nB : cB + (size_t)(t + 2) * kstep;
;             const char* a3 = a2 + kstep; const char* b3 = b2 + kstep;
;             if (last && has_next) S.a_ready(nxt);
;             if constexpr (SP2) {
;             PG8_LDB(B0, 0, 0); PG8_LDB(B1, 0, 1); PG8_SCHED; PG8_LDA(At, 0, 0); PG8_STAGE(PG8_SA(1, 1), a1 + hstep, voffA);
;             PG8_WAIT_V(8); PG8_WAIT_L(0); PG8_BAR; PG8_MMA(0, 0, At, B0); PG8_MMA(0, 1, At, B1); PG8_BAR; PG8_SCHED;
;             PG8_LDA(At, 0, 1); PG8_STAGE(PG8_SB(0, 0), b2, voffB); PG8_STAGE(PG8_SB(0, 1), b2 + hstep, voffB); PG8_STAGE(PG8_SA(0, 0), a2, voffA);
;             PG8_WAIT_V(8); PG8_WAIT_L(0); PG8_BAR; PG8_MMA(1, 0, At, B0); PG8_MMA(1, 1, At, B1); PG8_BAR; PG8_SCHED;
.LBB0_152:
	ds_read_b128 v[166:169], v154
	ds_read_b128 v[170:173], v154 offset:1024
	ds_read_b128 v[174:177], v154 offset:2048
	ds_read_b128 v[178:181], v154 offset:3072
	ds_read_b128 v[182:185], v155
	ds_read_b128 v[186:189], v155 offset:1024
	ds_read_b128 v[190:193], v155 offset:2048
	ds_read_b128 v[196:199], v155 offset:3072
	s_add_u32 s52, s88, 0xfffc0080
	s_addc_u32 s53, s89, -1
	s_cmp_eq_u32 s51, 12
	s_cselect_b32 s87, s21, s53
	s_cselect_b32 s86, s37, s52
	s_cselect_b32 s85, s19, s50
	s_cselect_b32 s84, s48, s49
	v_lshl_add_u64 v[150:151], s[88:89], 0, v[138:139]
	s_add_i32 m0, s38, 0xc000
	ds_read_b128 v[200:203], v156
	ds_read_b128 v[204:207], v156 offset:1024
	ds_read_b128 v[208:211], v156 offset:2048
	ds_read_b128 v[212:215], v156 offset:3072
	ds_read_b128 v[216:219], v156 offset:4096
	ds_read_b128 v[220:223], v156 offset:5120
	ds_read_b128 v[224:227], v156 offset:6144
	ds_read_b128 v[228:231], v156 offset:7168
	global_load_lds_dwordx4 v[150:151], off
	v_lshl_add_u64 v[150:151], s[88:89], 0, v[140:141]
	s_add_i32 m0, s38, 0xe000
	s_nop 0
	global_load_lds_dwordx4 v[150:151], off
	s_waitcnt vmcnt(8)
	s_waitcnt lgkmcnt(0)
	s_barrier
	s_setprio 1
	v_mfma_f32_16x16x32_bf16 v[126:129], v[166:169], v[200:203], v[126:129]
	v_mfma_f32_16x16x32_bf16 v[122:125], v[174:177], v[200:203], v[122:125]
	v_mfma_f32_16x16x32_bf16 v[110:113], v[166:169], v[208:211], v[110:113]
	v_mfma_f32_16x16x32_bf16 v[106:109], v[174:177], v[208:211], v[106:109]
	v_mfma_f32_16x16x32_bf16 v[94:97], v[166:169], v[216:219], v[94:97]
	v_mfma_f32_16x16x32_bf16 v[90:93], v[174:177], v[216:219], v[90:93]
	v_mfma_f32_16x16x32_bf16 v[78:81], v[166:169], v[224:227], v[78:81]
	v_mfma_f32_16x16x32_bf16 v[74:77], v[174:177], v[224:227], v[74:77]
	v_mfma_f32_16x16x32_bf16 v[126:129], v[170:173], v[204:207], v[126:129]
	v_mfma_f32_16x16x32_bf16 v[122:125], v[178:181], v[204:207], v[122:125]
	v_mfma_f32_16x16x32_bf16 v[110:113], v[170:173], v[212:215], v[110:113]
	v_mfma_f32_16x16x32_bf16 v[106:109], v[178:181], v[212:215], v[106:109]
	v_mfma_f32_16x16x32_bf16 v[94:97], v[170:173], v[220:223], v[94:97]
	v_mfma_f32_16x16x32_bf16 v[90:93], v[178:181], v[220:223], v[90:93]
	v_mfma_f32_16x16x32_bf16 v[78:81], v[170:173], v[228:231], v[78:81]
	v_mfma_f32_16x16x32_bf16 v[74:77], v[178:181], v[228:231], v[74:77]
	s_setprio 0
	s_setprio 1
	v_mfma_f32_16x16x32_bf16 v[118:121], v[182:185], v[200:203], v[118:121]
	v_mfma_f32_16x16x32_bf16 v[114:117], v[190:193], v[200:203], v[114:117]
	v_mfma_f32_16x16x32_bf16 v[102:105], v[182:185], v[208:211], v[102:105]
	v_mfma_f32_16x16x32_bf16 v[98:101], v[190:193], v[208:211], v[98:101]
	v_mfma_f32_16x16x32_bf16 v[86:89], v[182:185], v[216:219], v[86:89]
	v_mfma_f32_16x16x32_bf16 v[82:85], v[190:193], v[216:219], v[82:85]
	v_mfma_f32_16x16x32_bf16 v[70:73], v[182:185], v[224:227], v[70:73]
	v_mfma_f32_16x16x32_bf16 v[66:69], v[190:193], v[224:227], v[66:69]
	v_mfma_f32_16x16x32_bf16 v[118:121], v[186:189], v[204:207], v[118:121]
	v_mfma_f32_16x16x32_bf16 v[114:117], v[196:199], v[204:207], v[114:117]
	v_mfma_f32_16x16x32_bf16 v[102:105], v[186:189], v[212:215], v[102:105]
	v_mfma_f32_16x16x32_bf16 v[98:101], v[196:199], v[212:215], v[98:101]
	v_mfma_f32_16x16x32_bf16 v[86:89], v[186:189], v[220:223], v[86:89]
	v_mfma_f32_16x16x32_bf16 v[82:85], v[196:199], v[220:223], v[82:85]
	v_mfma_f32_16x16x32_bf16 v[70:73], v[186:189], v[228:231], v[70:73]
	v_mfma_f32_16x16x32_bf16 v[66:69], v[196:199], v[228:231], v[66:69]
	s_setprio 0
	s_barrier
	s_add_i32 s52, s46, s3
	v_lshl_add_u64 v[150:151], s[84:85], 0, v[132:133]
	s_mov_b32 m0, s52
	ds_read_b128 v[200:203], v156 offset:16384
	ds_read_b128 v[204:207], v156 offset:17408
	ds_read_b128 v[208:211], v156 offset:18432
	ds_read_b128 v[212:215], v156 offset:19456
	ds_read_b128 v[216:219], v156 offset:20480
	ds_read_b128 v[220:223], v156 offset:21504
	ds_read_b128 v[224:227], v156 offset:22528
	ds_read_b128 v[228:231], v156 offset:23552
	global_load_lds_dwordx4 v[150:151], off
	s_add_i32 m0, s52, 0x2000
	s_add_u32 s52, s84, 0x40000
	v_lshl_add_u64 v[232:233], s[84:85], 0, v[136:137]
	s_addc_u32 s53, s85, 0
	s_add_i32 s54, s47, s3
	global_load_lds_dwordx4 v[232:233], off
	v_lshl_add_u64 v[234:235], s[52:53], 0, v[132:133]
	s_mov_b32 m0, s54
	v_lshl_add_u64 v[236:237], s[86:87], 0, v[134:135]
	global_load_lds_dwordx4 v[234:235], off
	v_lshl_add_u64 v[234:235], s[52:53], 0, v[136:137]
	s_add_i32 m0, s54, 0x2000
	s_nop 0
	global_load_lds_dwordx4 v[234:235], off
	v_lshl_add_u64 v[234:235], s[86:87], 0, v[130:131]
	s_mov_b32 m0, s38
	s_nop 0
	global_load_lds_dwordx4 v[234:235], off
	s_mov_b32 m0, s39
	s_nop 0
	global_load_lds_dwordx4 v[236:237], off
	s_waitcnt vmcnt(8)
	s_waitcnt lgkmcnt(0)
	s_barrier
; #define PG8_STAGE(bufoff, gbase, voff) do { _Pragma("unroll") for (int _i = 0; _i < 2; ++_i) \
;         __builtin_amdgcn_global_load_lds((const unsigned*)((const char*)(gbase) + (voff)[_i]), (PG8_LAS unsigned*)(lds + (bufoff) + ldsw + _i * 8192), 16, 0, 0); } while (0)
; #define PG8_LDA(dst, b, h) do { _Pragma("unroll") for (int m = 0; m < 4; ++m) _Pragma("unroll") for (int k = 0; k < 2; ++k) dst[m][k] = *(const PG8_LAS bf16x8*)(lds + PG8_SA(b, h) + aoff + m * 2048 + k * 1024); } while (0)
; #define PG8_LDB(dst, b, h) do { _Pragma("unroll") for (int n = 0; n < 2; ++n) _Pragma("unroll") for (int k = 0; k < 2; ++k) dst[n][k] = *(const PG8_LAS bf16x8*)(lds + PG8_SB(b, h) + boff + n * 2048 + k * 1024); } while (0)
; #define PG8_MMA(ai, bj, At, Bt) do { __builtin_amdgcn_s_setprio(1); _Pragma("unroll") for (int m = 0; m < 4; ++m) _Pragma("unroll") for (int n = 0; n < 2; ++n) _Pragma("unroll") for (int k = 0; k < 2; ++k) \
;         acc[ai][bj][m][n] = __builtin_amdgcn_mfma_f32_16x16x32_bf16(Bt[n][k], At[m][k], acc[ai][bj][m][n], 0, 0, 0); __builtin_amdgcn_s_setprio(0); } while (0)
; #define PG8_WAIT_V(n) asm volatile("s_waitcnt vmcnt(" #n ")" ::: "memory")
; #define PG8_WAIT_L(n) asm volatile("s_waitcnt lgkmcnt(" #n ")" ::: "memory")
; #define PG8_BAR __builtin_amdgcn_s_barrier()
; #define PG8_SCHED __builtin_amdgcn_sched_barrier(0)
; template <class Epi, class Sched, bool ALIGN_EPI = false, bool SP2 = false>
; __device__ __forceinline__ void gemm_phase(PG8_LAS unsigned char* lds, const Gemm g, const Sched& S, const Epi& E) {
;     ...
;             PG8_WAIT_V(8); PG8_WAIT_L(0); PG8_BAR; PG8_MMA(1, 0, At, B0); PG8_MMA(1, 1, At, B1); PG8_BAR; PG8_SCHED;
;             PG8_LDB(B0, 1, 0); PG8_LDB(B1, 1, 1); PG8_SCHED; PG8_LDA(At, 1, 0); PG8_STAGE(PG8_SA(0, 1), a2 + hstep, voffA);
;             PG8_WAIT_V(8); PG8_WAIT_L(0); PG8_BAR; PG8_MMA(0, 0, At, B0); PG8_MMA(0, 1, At, B1); PG8_BAR; PG8_SCHED;
	s_setprio 1
	v_mfma_f32_16x16x32_bf16 v[62:65], v[166:169], v[200:203], v[62:65]
	v_mfma_f32_16x16x32_bf16 v[58:61], v[174:177], v[200:203], v[58:61]
	v_mfma_f32_16x16x32_bf16 v[46:49], v[166:169], v[208:211], v[46:49]
	v_mfma_f32_16x16x32_bf16 v[42:45], v[174:177], v[208:211], v[42:45]
	v_mfma_f32_16x16x32_bf16 v[30:33], v[166:169], v[216:219], v[30:33]
	v_mfma_f32_16x16x32_bf16 v[26:29], v[174:177], v[216:219], v[26:29]
	v_mfma_f32_16x16x32_bf16 v[14:17], v[166:169], v[224:227], v[14:17]
	v_mfma_f32_16x16x32_bf16 v[10:13], v[174:177], v[224:227], v[10:13]
	v_mfma_f32_16x16x32_bf16 v[62:65], v[170:173], v[204:207], v[62:65]
	v_mfma_f32_16x16x32_bf16 v[58:61], v[178:181], v[204:207], v[58:61]
	v_mfma_f32_16x16x32_bf16 v[46:49], v[170:173], v[212:215], v[46:49]
	v_mfma_f32_16x16x32_bf16 v[42:45], v[178:181], v[212:215], v[42:45]
	v_mfma_f32_16x16x32_bf16 v[30:33], v[170:173], v[220:223], v[30:33]
	v_mfma_f32_16x16x32_bf16 v[26:29], v[178:181], v[220:223], v[26:29]
	v_mfma_f32_16x16x32_bf16 v[14:17], v[170:173], v[228:231], v[14:17]
	v_mfma_f32_16x16x32_bf16 v[10:13], v[178:181], v[228:231], v[10:13]
	s_setprio 0
	s_setprio 1
	v_mfma_f32_16x16x32_bf16 v[54:57], v[182:185], v[200:203], v[54:57]
	v_mfma_f32_16x16x32_bf16 v[50:53], v[190:193], v[200:203], v[50:53]
	v_mfma_f32_16x16x32_bf16 v[38:41], v[182:185], v[208:211], v[38:41]
	v_mfma_f32_16x16x32_bf16 v[34:37], v[190:193], v[208:211], v[34:37]
	v_mfma_f32_16x16x32_bf16 v[22:25], v[182:185], v[216:219], v[22:25]
	v_mfma_f32_16x16x32_bf16 v[18:21], v[190:193], v[216:219], v[18:21]
	v_mfma_f32_16x16x32_bf16 v[6:9], v[182:185], v[224:227], v[6:9]
	v_mfma_f32_16x16x32_bf16 v[2:5], v[190:193], v[224:227], v[2:5]
	v_mfma_f32_16x16x32_bf16 v[54:57], v[186:189], v[204:207], v[54:57]
	v_mfma_f32_16x16x32_bf16 v[50:53], v[196:199], v[204:207], v[50:53]
	v_mfma_f32_16x16x32_bf16 v[38:41], v[186:189], v[212:215], v[38:41]
	v_mfma_f32_16x16x32_bf16 v[34:37], v[196:199], v[212:215], v[34:37]
	v_mfma_f32_16x16x32_bf16 v[22:25], v[186:189], v[220:223], v[22:25]
	v_mfma_f32_16x16x32_bf16 v[18:21], v[196:199], v[220:223], v[18:21]
	v_mfma_f32_16x16x32_bf16 v[6:9], v[186:189], v[228:231], v[6:9]
	v_mfma_f32_16x16x32_bf16 v[2:5], v[196:199], v[228:231], v[2:5]
	s_setprio 0
	s_barrier
	s_add_i32 s54, 0, 0x18000
	v_add_u32_e32 v147, s54, v152
	s_add_i32 s55, 0, 0x1c000
	ds_read_b128 v[166:169], v147
	ds_read_b128 v[170:173], v147 offset:1024
	ds_read_b128 v[174:177], v147 offset:2048
	ds_read_b128 v[178:181], v147 offset:3072
	v_add_u32_e32 v147, s55, v152
	ds_read_b128 v[182:185], v147
	ds_read_b128 v[186:189], v147 offset:1024
	ds_read_b128 v[190:193], v147 offset:2048
	ds_read_b128 v[196:199], v147 offset:3072
	s_add_u32 s52, s86, 0x40000
	s_addc_u32 s53, s87, 0
	s_mov_b32 m0, s40
	v_lshl_add_u64 v[238:239], s[52:53], 0, v[130:131]
	ds_read_b128 v[200:203], v156 offset:32768
	ds_read_b128 v[204:207], v156 offset:33792
	ds_read_b128 v[208:211], v156 offset:34816
	ds_read_b128 v[212:215], v156 offset:35840
	ds_read_b128 v[216:219], v156 offset:36864
	ds_read_b128 v[220:223], v156 offset:37888
	ds_read_b128 v[224:227], v156 offset:38912
	ds_read_b128 v[228:231], v156 offset:39936
	global_load_lds_dwordx4 v[238:239], off
	v_lshl_add_u64 v[238:239], s[52:53], 0, v[134:135]
	s_mov_b32 m0, s41
	s_nop 0
	global_load_lds_dwordx4 v[238:239], off
	s_waitcnt vmcnt(8)
	s_waitcnt lgkmcnt(0)
	s_barrier
	s_setprio 1
	v_mfma_f32_16x16x32_bf16 v[126:129], v[166:169], v[200:203], v[126:129]
	v_mfma_f32_16x16x32_bf16 v[122:125], v[174:177], v[200:203], v[122:125]
	v_mfma_f32_16x16x32_bf16 v[110:113], v[166:169], v[208:211], v[110:113]
	v_mfma_f32_16x16x32_bf16 v[106:109], v[174:177], v[208:211], v[106:109]
	v_mfma_f32_16x16x32_bf16 v[94:97], v[166:169], v[216:219], v[94:97]
	v_mfma_f32_16x16x32_bf16 v[90:93], v[174:177], v[216:219], v[90:93]
	v_mfma_f32_16x16x32_bf16 v[78:81], v[166:169], v[224:227], v[78:81]
	v_mfma_f32_16x16x32_bf16 v[74:77], v[174:177], v[224:227], v[74:77]
	v_mfma_f32_16x16x32_bf16 v[126:129], v[170:173], v[204:207], v[126:129]
	v_mfma_f32_16x16x32_bf16 v[122:125], v[178:181], v[204:207], v[122:125]
	v_mfma_f32_16x16x32_bf16 v[110:113], v[170:173], v[212:215], v[110:113]
	v_mfma_f32_16x16x32_bf16 v[106:109], v[178:181], v[212:215], v[106:109]
	v_mfma_f32_16x16x32_bf16 v[94:97], v[170:173], v[220:223], v[94:97]
	v_mfma_f32_16x16x32_bf16 v[90:93], v[178:181], v[220:223], v[90:93]
	v_mfma_f32_16x16x32_bf16 v[78:81], v[170:173], v[228:231], v[78:81]
	v_mfma_f32_16x16x32_bf16 v[74:77], v[178:181], v[228:231], v[74:77]
	s_setprio 0
	s_setprio 1
	v_mfma_f32_16x16x32_bf16 v[118:121], v[182:185], v[200:203], v[118:121]
	v_mfma_f32_16x16x32_bf16 v[114:117], v[190:193], v[200:203], v[114:117]
	v_mfma_f32_16x16x32_bf16 v[102:105], v[182:185], v[208:211], v[102:105]
	v_mfma_f32_16x16x32_bf16 v[98:101], v[190:193], v[208:211], v[98:101]
	v_mfma_f32_16x16x32_bf16 v[86:89], v[182:185], v[216:219], v[86:89]
	v_mfma_f32_16x16x32_bf16 v[82:85], v[190:193], v[216:219], v[82:85]
	v_mfma_f32_16x16x32_bf16 v[70:73], v[182:185], v[224:227], v[70:73]
	v_mfma_f32_16x16x32_bf16 v[66:69], v[190:193], v[224:227], v[66:69]
	v_mfma_f32_16x16x32_bf16 v[118:121], v[186:189], v[204:207], v[118:121]
	v_mfma_f32_16x16x32_bf16 v[114:117], v[196:199], v[204:207], v[114:117]
	v_mfma_f32_16x16x32_bf16 v[102:105], v[186:189], v[212:215], v[102:105]
	v_mfma_f32_16x16x32_bf16 v[98:101], v[196:199], v[212:215], v[98:101]
	v_mfma_f32_16x16x32_bf16 v[86:89], v[186:189], v[220:223], v[86:89]
	v_mfma_f32_16x16x32_bf16 v[82:85], v[196:199], v[220:223], v[82:85]
	v_mfma_f32_16x16x32_bf16 v[70:73], v[186:189], v[228:231], v[70:73]
	v_mfma_f32_16x16x32_bf16 v[66:69], v[196:199], v[228:231], v[66:69]
	s_setprio 0
	s_barrier
; #define PG8_STAGE(bufoff, gbase, voff) do { _Pragma("unroll") for (int _i = 0; _i < 2; ++_i) \
;         __builtin_amdgcn_global_load_lds((const unsigned*)((const char*)(gbase) + (voff)[_i]), (PG8_LAS unsigned*)(lds + (bufoff) + ldsw + _i * 8192), 16, 0, 0); } while (0)
; #define PG8_LDA(dst, b, h) do { _Pragma("unroll") for (int m = 0; m < 4; ++m) _Pragma("unroll") for (int k = 0; k < 2; ++k) dst[m][k] = *(const PG8_LAS bf16x8*)(lds + PG8_SA(b, h) + aoff + m * 2048 + k * 1024); } while (0)
; #define PG8_MMA(ai, bj, At, Bt) do { __builtin_amdgcn_s_setprio(1); _Pragma("unroll") for (int m = 0; m < 4; ++m) _Pragma("unroll") for (int n = 0; n < 2; ++n) _Pragma("unroll") for (int k = 0; k < 2; ++k) \
;         acc[ai][bj][m][n] = __builtin_amdgcn_mfma_f32_16x16x32_bf16(Bt[n][k], At[m][k], acc[ai][bj][m][n], 0, 0, 0); __builtin_amdgcn_s_setprio(0); } while (0)
; #define PG8_WAIT_V(n) asm volatile("s_waitcnt vmcnt(" #n ")" ::: "memory")
; #define PG8_WAIT_L(n) asm volatile("s_waitcnt lgkmcnt(" #n ")" ::: "memory")
; #define PG8_BAR __builtin_amdgcn_s_barrier()
; #define PG8_SCHED __builtin_amdgcn_sched_barrier(0)
; template <class Epi, class Sched, bool ALIGN_EPI = false, bool SP2 = false>
; __device__ __forceinline__ void gemm_phase(PG8_LAS unsigned char* lds, const Gemm g, const Sched& S, const Epi& E) {
;     ...
;         for (int t = 0; t < nt; t += 2) {
;             const bool last = (t == nt - 2);
;             const char* a1 = cA + (size_t)(t + 1) * kstep;
;             const char* a2 = last ? nA : cA + (size_t)(t + 2) * kstep; const char* b2 = last ? nB : cB + (size_t)(t + 2) * kstep;
;             const char* a3 = a2 + kstep; const char* b3 = b2 + kstep;
;     ...
;             PG8_LDA(At, 1, 1); PG8_STAGE(PG8_SB(1, 0), b3, voffB); PG8_STAGE(PG8_SB(1, 1), b3 + hstep, voffB); PG8_STAGE(PG8_SA(1, 0), a3, voffA);
;             PG8_WAIT_V(8); PG8_WAIT_L(0); PG8_BAR; PG8_MMA(1, 0, At, B0); PG8_MMA(1, 1, At, B1); PG8_BAR; PG8_SCHED;
	s_add_i32 s52, s54, s3
	v_lshl_add_u64 v[150:151], v[150:151], 0, s[14:15]
	s_mov_b32 m0, s52
	ds_read_b128 v[200:203], v156 offset:49152
	ds_read_b128 v[204:207], v156 offset:50176
	ds_read_b128 v[208:211], v156 offset:51200
	ds_read_b128 v[212:215], v156 offset:52224
	ds_read_b128 v[216:219], v156 offset:53248
	ds_read_b128 v[220:223], v156 offset:54272
	ds_read_b128 v[224:227], v156 offset:55296
	ds_read_b128 v[228:231], v156 offset:56320
	global_load_lds_dwordx4 v[150:151], off
	s_add_i32 m0, s52, 0x2000
	s_add_u32 s52, s84, 0x40080
	v_lshl_add_u64 v[150:151], v[232:233], 0, s[14:15]
	s_addc_u32 s53, s85, 0
	s_add_i32 s54, s55, s3
	global_load_lds_dwordx4 v[150:151], off
	v_lshl_add_u64 v[150:151], s[52:53], 0, v[132:133]
	s_mov_b32 m0, s54
	s_nop 0
	global_load_lds_dwordx4 v[150:151], off
	v_lshl_add_u64 v[150:151], s[52:53], 0, v[136:137]
	s_add_i32 m0, s54, 0x2000
	s_nop 0
	global_load_lds_dwordx4 v[150:151], off
	v_lshl_add_u64 v[150:151], v[234:235], 0, s[14:15]
	s_mov_b32 m0, s43
	s_nop 0
	global_load_lds_dwordx4 v[150:151], off
	v_lshl_add_u64 v[150:151], v[236:237], 0, s[14:15]
	s_mov_b32 m0, s44
	s_nop 0
	global_load_lds_dwordx4 v[150:151], off
	s_waitcnt vmcnt(8)
	s_waitcnt lgkmcnt(0)
	s_barrier
	s_setprio 1
	v_mfma_f32_16x16x32_bf16 v[62:65], v[166:169], v[200:203], v[62:65]
	v_mfma_f32_16x16x32_bf16 v[58:61], v[174:177], v[200:203], v[58:61]
	v_mfma_f32_16x16x32_bf16 v[46:49], v[166:169], v[208:211], v[46:49]
	v_mfma_f32_16x16x32_bf16 v[42:45], v[174:177], v[208:211], v[42:45]
	v_mfma_f32_16x16x32_bf16 v[30:33], v[166:169], v[216:219], v[30:33]
	v_mfma_f32_16x16x32_bf16 v[26:29], v[174:177], v[216:219], v[26:29]
	v_mfma_f32_16x16x32_bf16 v[14:17], v[166:169], v[224:227], v[14:17]
	v_mfma_f32_16x16x32_bf16 v[10:13], v[174:177], v[224:227], v[10:13]
	v_mfma_f32_16x16x32_bf16 v[62:65], v[170:173], v[204:207], v[62:65]
	v_mfma_f32_16x16x32_bf16 v[58:61], v[178:181], v[204:207], v[58:61]
	v_mfma_f32_16x16x32_bf16 v[46:49], v[170:173], v[212:215], v[46:49]
	v_mfma_f32_16x16x32_bf16 v[42:45], v[178:181], v[212:215], v[42:45]
	v_mfma_f32_16x16x32_bf16 v[30:33], v[170:173], v[220:223], v[30:33]
	v_mfma_f32_16x16x32_bf16 v[26:29], v[178:181], v[220:223], v[26:29]
	v_mfma_f32_16x16x32_bf16 v[14:17], v[170:173], v[228:231], v[14:17]
	v_mfma_f32_16x16x32_bf16 v[10:13], v[178:181], v[228:231], v[10:13]
	s_setprio 0
	s_setprio 1
	v_mfma_f32_16x16x32_bf16 v[54:57], v[182:185], v[200:203], v[54:57]
	v_mfma_f32_16x16x32_bf16 v[50:53], v[190:193], v[200:203], v[50:53]
	v_mfma_f32_16x16x32_bf16 v[38:41], v[182:185], v[208:211], v[38:41]
	v_mfma_f32_16x16x32_bf16 v[34:37], v[190:193], v[208:211], v[34:37]
	v_mfma_f32_16x16x32_bf16 v[22:25], v[182:185], v[216:219], v[22:25]
	v_mfma_f32_16x16x32_bf16 v[18:21], v[190:193], v[216:219], v[18:21]
	v_mfma_f32_16x16x32_bf16 v[6:9], v[182:185], v[224:227], v[6:9]
	v_mfma_f32_16x16x32_bf16 v[2:5], v[190:193], v[224:227], v[2:5]
	v_mfma_f32_16x16x32_bf16 v[54:57], v[186:189], v[204:207], v[54:57]
	v_mfma_f32_16x16x32_bf16 v[50:53], v[196:199], v[204:207], v[50:53]
	v_mfma_f32_16x16x32_bf16 v[38:41], v[186:189], v[212:215], v[38:41]
	v_mfma_f32_16x16x32_bf16 v[34:37], v[196:199], v[212:215], v[34:37]
	v_mfma_f32_16x16x32_bf16 v[22:25], v[186:189], v[220:223], v[22:25]
	v_mfma_f32_16x16x32_bf16 v[18:21], v[196:199], v[220:223], v[18:21]
	v_mfma_f32_16x16x32_bf16 v[6:9], v[186:189], v[228:231], v[6:9]
	v_mfma_f32_16x16x32_bf16 v[2:5], v[196:199], v[228:231], v[2:5]
	s_setprio 0
	s_barrier
	s_add_i32 s51, s51, 2
	s_add_u32 s88, s88, 0x100
	s_addc_u32 s89, s89, 0
	s_add_u32 s49, s49, 0x100
	s_addc_u32 s50, s50, 0
	s_cmp_gt_u32 s51, 13
	s_cbranch_scc0 .LBB0_152
	s_and_b64 vcc, exec, s[16:17]
	s_cbranch_vccz .LBB0_155
	s_barrier

; #define PG8_STAGE(bufoff, gbase, voff) do { _Pragma("unroll") for (int _i = 0; _i < 2; ++_i) \
;         __builtin_amdgcn_global_load_lds((const unsigned*)((const char*)(gbase) + (voff)[_i]), (PG8_LAS unsigned*)(lds + (bufoff) + ldsw + _i * 8192), 16, 0, 0); } while (0)
; #define PG8_LDA(dst, b, h) do { _Pragma("unroll") for (int m = 0; m < 4; ++m) _Pragma("unroll") for (int k = 0; k < 2; ++k) dst[m][k] = *(const PG8_LAS bf16x8*)(lds + PG8_SA(b, h) + aoff + m * 2048 + k * 1024); } while (0)
; #define PG8_LDB(dst, b, h) do { _Pragma("unroll") for (int n = 0; n < 2; ++n) _Pragma("unroll") for (int k = 0; k < 2; ++k) dst[n][k] = *(const PG8_LAS bf16x8*)(lds + PG8_SB(b, h) + boff + n * 2048 + k * 1024); } while (0)
; #define PG8_MMA(ai, bj, At, Bt) do { __builtin_amdgcn_s_setprio(1); _Pragma("unroll") for (int m = 0; m < 4; ++m) _Pragma("unroll") for (int n = 0; n < 2; ++n) _Pragma("unroll") for (int k = 0; k < 2; ++k) \
;         acc[ai][bj][m][n] = __builtin_amdgcn_mfma_f32_16x16x32_bf16(Bt[n][k], At[m][k], acc[ai][bj][m][n], 0, 0, 0); __builtin_amdgcn_s_setprio(0); } while (0)
; #define PG8_WAIT_V(n) asm volatile("s_waitcnt vmcnt(" #n ")" ::: "memory")
; #define PG8_BAR __builtin_amdgcn_s_barrier()
; template <class Epi, class Sched, bool ALIGN_EPI = false, bool SP2 = false>
; __device__ __forceinline__ void gemm_phase(PG8_LAS unsigned char* lds, const Gemm g, const Sched& S, const Epi& E) {
;     ...
;         for (int t = 0; t < nt; t += 2) {
;             const bool last = (t == nt - 2);
;             const char* a1 = cA + (size_t)(t + 1) * kstep;
;             const char* a2 = last ? nA : cA + (size_t)(t + 2) * kstep; const char* b2 = last ? nB : cB + (size_t)(t + 2) * kstep;
;             const char* a3 = a2 + kstep; const char* b3 = b2 + kstep;
;             if (last && has_next) S.a_ready(nxt);
;             if constexpr (SP2) {
;             PG8_LDB(B0, 0, 0); PG8_LDB(B1, 0, 1); PG8_SCHED; PG8_LDA(At, 0, 0); PG8_STAGE(PG8_SA(1, 1), a1 + hstep, voffA);
;             PG8_WAIT_V(8); PG8_WAIT_L(0); PG8_BAR; PG8_MMA(0, 0, At, B0); PG8_MMA(0, 1, At, B1); PG8_BAR; PG8_SCHED;
;             PG8_LDA(At, 0, 1); PG8_STAGE(PG8_SB(0, 0), b2, voffB); PG8_STAGE(PG8_SB(0, 1), b2 + hstep, voffB); PG8_STAGE(PG8_SA(0, 0), a2, voffA);
;             PG8_WAIT_V(8); PG8_WAIT_L(0); PG8_BAR; PG8_MMA(1, 0, At, B0); PG8_MMA(1, 1, At, B1); PG8_BAR; PG8_SCHED;
.LBB0_244:
	ds_read_b128 v[146:149], v152
	ds_read_b128 v[156:159], v152 offset:1024
	ds_read_b128 v[160:163], v152 offset:2048
	ds_read_b128 v[164:167], v152 offset:3072
	ds_read_b128 v[168:171], v153
	ds_read_b128 v[172:175], v153 offset:1024
	ds_read_b128 v[176:179], v153 offset:2048
	ds_read_b128 v[180:183], v153 offset:3072
	s_add_u32 s52, vcc_lo, 0xfff80080
	s_addc_u32 s53, vcc_hi, -1
	s_cmp_eq_u32 s51, 28
	s_cselect_b32 s89, s23, s53
	s_cselect_b32 s88, s36, s52
	s_cselect_b32 s87, s21, s50
	s_cselect_b32 s86, s37, s49
	v_lshl_add_u64 v[192:193], vcc, 0, v[138:139]
	s_add_i32 m0, s3, 0xc000
	ds_read_b128 v[184:187], v154
	ds_read_b128 v[188:191], v154 offset:1024
	ds_read_b128 v[196:199], v154 offset:2048
	ds_read_b128 v[200:203], v154 offset:3072
	ds_read_b128 v[204:207], v154 offset:4096
	ds_read_b128 v[208:211], v154 offset:5120
	ds_read_b128 v[212:215], v154 offset:6144
	ds_read_b128 v[216:219], v154 offset:7168
	global_load_lds_dwordx4 v[192:193], off
	v_lshl_add_u64 v[192:193], vcc, 0, v[140:141]
	s_add_i32 m0, s3, 0xe000
	s_nop 0
	global_load_lds_dwordx4 v[192:193], off
	s_waitcnt vmcnt(8)
	s_waitcnt lgkmcnt(0)
	s_barrier
	s_setprio 1
	v_mfma_f32_16x16x32_bf16 v[126:129], v[146:149], v[184:187], v[126:129]
	v_mfma_f32_16x16x32_bf16 v[122:125], v[160:163], v[184:187], v[122:125]
	v_mfma_f32_16x16x32_bf16 v[110:113], v[146:149], v[196:199], v[110:113]
	v_mfma_f32_16x16x32_bf16 v[106:109], v[160:163], v[196:199], v[106:109]
	v_mfma_f32_16x16x32_bf16 v[94:97], v[146:149], v[204:207], v[94:97]
	v_mfma_f32_16x16x32_bf16 v[90:93], v[160:163], v[204:207], v[90:93]
	v_mfma_f32_16x16x32_bf16 v[78:81], v[146:149], v[212:215], v[78:81]
	v_mfma_f32_16x16x32_bf16 v[74:77], v[160:163], v[212:215], v[74:77]
	v_mfma_f32_16x16x32_bf16 v[126:129], v[156:159], v[188:191], v[126:129]
	v_mfma_f32_16x16x32_bf16 v[122:125], v[164:167], v[188:191], v[122:125]
	v_mfma_f32_16x16x32_bf16 v[110:113], v[156:159], v[200:203], v[110:113]
	v_mfma_f32_16x16x32_bf16 v[106:109], v[164:167], v[200:203], v[106:109]
	v_mfma_f32_16x16x32_bf16 v[94:97], v[156:159], v[208:211], v[94:97]
	v_mfma_f32_16x16x32_bf16 v[90:93], v[164:167], v[208:211], v[90:93]
	v_mfma_f32_16x16x32_bf16 v[78:81], v[156:159], v[216:219], v[78:81]
	v_mfma_f32_16x16x32_bf16 v[74:77], v[164:167], v[216:219], v[74:77]
	s_setprio 0
	s_setprio 1
	v_mfma_f32_16x16x32_bf16 v[118:121], v[168:171], v[184:187], v[118:121]
	v_mfma_f32_16x16x32_bf16 v[114:117], v[176:179], v[184:187], v[114:117]
	v_mfma_f32_16x16x32_bf16 v[102:105], v[168:171], v[196:199], v[102:105]
	v_mfma_f32_16x16x32_bf16 v[98:101], v[176:179], v[196:199], v[98:101]
	v_mfma_f32_16x16x32_bf16 v[86:89], v[168:171], v[204:207], v[86:89]
	v_mfma_f32_16x16x32_bf16 v[82:85], v[176:179], v[204:207], v[82:85]
	v_mfma_f32_16x16x32_bf16 v[70:73], v[168:171], v[212:215], v[70:73]
	v_mfma_f32_16x16x32_bf16 v[66:69], v[176:179], v[212:215], v[66:69]
	v_mfma_f32_16x16x32_bf16 v[118:121], v[172:175], v[188:191], v[118:121]
	v_mfma_f32_16x16x32_bf16 v[114:117], v[180:183], v[188:191], v[114:117]
	v_mfma_f32_16x16x32_bf16 v[102:105], v[172:175], v[200:203], v[102:105]
	v_mfma_f32_16x16x32_bf16 v[98:101], v[180:183], v[200:203], v[98:101]
	v_mfma_f32_16x16x32_bf16 v[86:89], v[172:175], v[208:211], v[86:89]
	v_mfma_f32_16x16x32_bf16 v[82:85], v[180:183], v[208:211], v[82:85]
	v_mfma_f32_16x16x32_bf16 v[70:73], v[172:175], v[216:219], v[70:73]
	v_mfma_f32_16x16x32_bf16 v[66:69], v[180:183], v[216:219], v[66:69]
	s_setprio 0
	s_barrier
	s_add_i32 s52, s46, s2
	v_lshl_add_u64 v[192:193], s[86:87], 0, v[132:133]
	s_mov_b32 m0, s52
	ds_read_b128 v[184:187], v154 offset:16384
	ds_read_b128 v[188:191], v154 offset:17408
	ds_read_b128 v[196:199], v154 offset:18432
	ds_read_b128 v[200:203], v154 offset:19456
	ds_read_b128 v[204:207], v154 offset:20480
	ds_read_b128 v[208:211], v154 offset:21504
	ds_read_b128 v[212:215], v154 offset:22528
	ds_read_b128 v[216:219], v154 offset:23552
	global_load_lds_dwordx4 v[192:193], off
	s_add_i32 m0, s52, 0x2000
	s_add_u32 s52, s86, 0x80000
	v_lshl_add_u64 v[220:221], s[86:87], 0, v[136:137]
	s_addc_u32 s53, s87, 0
	s_add_i32 s54, s47, s2
	global_load_lds_dwordx4 v[220:221], off
	v_lshl_add_u64 v[222:223], s[52:53], 0, v[132:133]
	s_mov_b32 m0, s54
	v_lshl_add_u64 v[224:225], s[88:89], 0, v[134:135]
	global_load_lds_dwordx4 v[222:223], off
	v_lshl_add_u64 v[222:223], s[52:53], 0, v[136:137]
	s_add_i32 m0, s54, 0x2000
	s_nop 0
	global_load_lds_dwordx4 v[222:223], off
	v_lshl_add_u64 v[222:223], s[88:89], 0, v[130:131]
	s_mov_b32 m0, s3
	s_nop 0
	global_load_lds_dwordx4 v[222:223], off
	s_mov_b32 m0, s38
	s_nop 0
	global_load_lds_dwordx4 v[224:225], off
	s_waitcnt vmcnt(8)
	s_waitcnt lgkmcnt(0)
	s_barrier
; #define PG8_STAGE(bufoff, gbase, voff) do { _Pragma("unroll") for (int _i = 0; _i < 2; ++_i) \
;         __builtin_amdgcn_global_load_lds((const unsigned*)((const char*)(gbase) + (voff)[_i]), (PG8_LAS unsigned*)(lds + (bufoff) + ldsw + _i * 8192), 16, 0, 0); } while (0)
; #define PG8_LDA(dst, b, h) do { _Pragma("unroll") for (int m = 0; m < 4; ++m) _Pragma("unroll") for (int k = 0; k < 2; ++k) dst[m][k] = *(const PG8_LAS bf16x8*)(lds + PG8_SA(b, h) + aoff + m * 2048 + k * 1024); } while (0)
; #define PG8_LDB(dst, b, h) do { _Pragma("unroll") for (int n = 0; n < 2; ++n) _Pragma("unroll") for (int k = 0; k < 2; ++k) dst[n][k] = *(const PG8_LAS bf16x8*)(lds + PG8_SB(b, h) + boff + n * 2048 + k * 1024); } while (0)
; #define PG8_MMA(ai, bj, At, Bt) do { __builtin_amdgcn_s_setprio(1); _Pragma("unroll") for (int m = 0; m < 4; ++m) _Pragma("unroll") for (int n = 0; n < 2; ++n) _Pragma("unroll") for (int k = 0; k < 2; ++k) \
;         acc[ai][bj][m][n] = __builtin_amdgcn_mfma_f32_16x16x32_bf16(Bt[n][k], At[m][k], acc[ai][bj][m][n], 0, 0, 0); __builtin_amdgcn_s_setprio(0); } while (0)
; #define PG8_WAIT_V(n) asm volatile("s_waitcnt vmcnt(" #n ")" ::: "memory")
; #define PG8_WAIT_L(n) asm volatile("s_waitcnt lgkmcnt(" #n ")" ::: "memory")
; #define PG8_BAR __builtin_amdgcn_s_barrier()
; #define PG8_SCHED __builtin_amdgcn_sched_barrier(0)
; template <class Epi, class Sched, bool ALIGN_EPI = false, bool SP2 = false>
; __device__ __forceinline__ void gemm_phase(PG8_LAS unsigned char* lds, const Gemm g, const Sched& S, const Epi& E) {
;     ...
;             PG8_WAIT_V(8); PG8_WAIT_L(0); PG8_BAR; PG8_MMA(1, 0, At, B0); PG8_MMA(1, 1, At, B1); PG8_BAR; PG8_SCHED;
;             PG8_LDB(B0, 1, 0); PG8_LDB(B1, 1, 1); PG8_SCHED; PG8_LDA(At, 1, 0); PG8_STAGE(PG8_SA(0, 1), a2 + hstep, voffA);
;             PG8_WAIT_V(8); PG8_WAIT_L(0); PG8_BAR; PG8_MMA(0, 0, At, B0); PG8_MMA(0, 1, At, B1); PG8_BAR; PG8_SCHED;
	s_setprio 1
	v_mfma_f32_16x16x32_bf16 v[62:65], v[146:149], v[184:187], v[62:65]
	v_mfma_f32_16x16x32_bf16 v[58:61], v[160:163], v[184:187], v[58:61]
	v_mfma_f32_16x16x32_bf16 v[46:49], v[146:149], v[196:199], v[46:49]
	v_mfma_f32_16x16x32_bf16 v[42:45], v[160:163], v[196:199], v[42:45]
	v_mfma_f32_16x16x32_bf16 v[30:33], v[146:149], v[204:207], v[30:33]
	v_mfma_f32_16x16x32_bf16 v[26:29], v[160:163], v[204:207], v[26:29]
	v_mfma_f32_16x16x32_bf16 v[14:17], v[146:149], v[212:215], v[14:17]
	v_mfma_f32_16x16x32_bf16 v[10:13], v[160:163], v[212:215], v[10:13]
	v_mfma_f32_16x16x32_bf16 v[62:65], v[156:159], v[188:191], v[62:65]
	v_mfma_f32_16x16x32_bf16 v[58:61], v[164:167], v[188:191], v[58:61]
	v_mfma_f32_16x16x32_bf16 v[46:49], v[156:159], v[200:203], v[46:49]
	v_mfma_f32_16x16x32_bf16 v[42:45], v[164:167], v[200:203], v[42:45]
	v_mfma_f32_16x16x32_bf16 v[30:33], v[156:159], v[208:211], v[30:33]
	v_mfma_f32_16x16x32_bf16 v[26:29], v[164:167], v[208:211], v[26:29]
	v_mfma_f32_16x16x32_bf16 v[14:17], v[156:159], v[216:219], v[14:17]
	v_mfma_f32_16x16x32_bf16 v[10:13], v[164:167], v[216:219], v[10:13]
	s_setprio 0
	s_setprio 1
	v_mfma_f32_16x16x32_bf16 v[54:57], v[168:171], v[184:187], v[54:57]
	v_mfma_f32_16x16x32_bf16 v[50:53], v[176:179], v[184:187], v[50:53]
	v_mfma_f32_16x16x32_bf16 v[38:41], v[168:171], v[196:199], v[38:41]
	v_mfma_f32_16x16x32_bf16 v[34:37], v[176:179], v[196:199], v[34:37]
	v_mfma_f32_16x16x32_bf16 v[22:25], v[168:171], v[204:207], v[22:25]
	v_mfma_f32_16x16x32_bf16 v[18:21], v[176:179], v[204:207], v[18:21]
	v_mfma_f32_16x16x32_bf16 v[6:9], v[168:171], v[212:215], v[6:9]
	v_mfma_f32_16x16x32_bf16 v[2:5], v[176:179], v[212:215], v[2:5]
	v_mfma_f32_16x16x32_bf16 v[54:57], v[172:175], v[188:191], v[54:57]
	v_mfma_f32_16x16x32_bf16 v[50:53], v[180:183], v[188:191], v[50:53]
	v_mfma_f32_16x16x32_bf16 v[38:41], v[172:175], v[200:203], v[38:41]
	v_mfma_f32_16x16x32_bf16 v[34:37], v[180:183], v[200:203], v[34:37]
	v_mfma_f32_16x16x32_bf16 v[22:25], v[172:175], v[208:211], v[22:25]
	v_mfma_f32_16x16x32_bf16 v[18:21], v[180:183], v[208:211], v[18:21]
	v_mfma_f32_16x16x32_bf16 v[6:9], v[172:175], v[216:219], v[6:9]
	v_mfma_f32_16x16x32_bf16 v[2:5], v[180:183], v[216:219], v[2:5]
	s_setprio 0
	s_barrier
	s_add_i32 s54, 0, 0x18000
	s_add_i32 s55, 0, 0x1c000
	v_add_u32_e32 v164, s54, v150
	v_add_u32_e32 v180, s55, v150
	ds_read_b128 v[146:149], v164
	ds_read_b128 v[156:159], v164 offset:1024
	ds_read_b128 v[160:163], v164 offset:2048
	ds_read_b128 v[164:167], v164 offset:3072
	ds_read_b128 v[168:171], v180
	ds_read_b128 v[172:175], v180 offset:1024
	ds_read_b128 v[176:179], v180 offset:2048
	ds_read_b128 v[180:183], v180 offset:3072
	s_add_u32 s52, s88, 0x80000
	s_addc_u32 s53, s89, 0
	s_mov_b32 m0, s39
	v_lshl_add_u64 v[226:227], s[52:53], 0, v[130:131]
	ds_read_b128 v[184:187], v154 offset:32768
	ds_read_b128 v[188:191], v154 offset:33792
	ds_read_b128 v[196:199], v154 offset:34816
	ds_read_b128 v[200:203], v154 offset:35840
	ds_read_b128 v[204:207], v154 offset:36864
	ds_read_b128 v[208:211], v154 offset:37888
	ds_read_b128 v[212:215], v154 offset:38912
	ds_read_b128 v[216:219], v154 offset:39936
	global_load_lds_dwordx4 v[226:227], off
	v_lshl_add_u64 v[226:227], s[52:53], 0, v[134:135]
	s_mov_b32 m0, s40
	s_nop 0
	global_load_lds_dwordx4 v[226:227], off
	s_waitcnt vmcnt(8)
	s_waitcnt lgkmcnt(0)
	s_barrier
	s_setprio 1
	v_mfma_f32_16x16x32_bf16 v[126:129], v[146:149], v[184:187], v[126:129]
	v_mfma_f32_16x16x32_bf16 v[122:125], v[160:163], v[184:187], v[122:125]
	v_mfma_f32_16x16x32_bf16 v[110:113], v[146:149], v[196:199], v[110:113]
	v_mfma_f32_16x16x32_bf16 v[106:109], v[160:163], v[196:199], v[106:109]
	v_mfma_f32_16x16x32_bf16 v[94:97], v[146:149], v[204:207], v[94:97]
	v_mfma_f32_16x16x32_bf16 v[90:93], v[160:163], v[204:207], v[90:93]
	v_mfma_f32_16x16x32_bf16 v[78:81], v[146:149], v[212:215], v[78:81]
	v_mfma_f32_16x16x32_bf16 v[74:77], v[160:163], v[212:215], v[74:77]
	v_mfma_f32_16x16x32_bf16 v[126:129], v[156:159], v[188:191], v[126:129]
	v_mfma_f32_16x16x32_bf16 v[122:125], v[164:167], v[188:191], v[122:125]
	v_mfma_f32_16x16x32_bf16 v[110:113], v[156:159], v[200:203], v[110:113]
	v_mfma_f32_16x16x32_bf16 v[106:109], v[164:167], v[200:203], v[106:109]
	v_mfma_f32_16x16x32_bf16 v[94:97], v[156:159], v[208:211], v[94:97]
	v_mfma_f32_16x16x32_bf16 v[90:93], v[164:167], v[208:211], v[90:93]
	v_mfma_f32_16x16x32_bf16 v[78:81], v[156:159], v[216:219], v[78:81]
	v_mfma_f32_16x16x32_bf16 v[74:77], v[164:167], v[216:219], v[74:77]
	s_setprio 0
	s_setprio 1
	v_mfma_f32_16x16x32_bf16 v[118:121], v[168:171], v[184:187], v[118:121]
	v_mfma_f32_16x16x32_bf16 v[114:117], v[176:179], v[184:187], v[114:117]
	v_mfma_f32_16x16x32_bf16 v[102:105], v[168:171], v[196:199], v[102:105]
	v_mfma_f32_16x16x32_bf16 v[98:101], v[176:179], v[196:199], v[98:101]
	v_mfma_f32_16x16x32_bf16 v[86:89], v[168:171], v[204:207], v[86:89]
	v_mfma_f32_16x16x32_bf16 v[82:85], v[176:179], v[204:207], v[82:85]
	v_mfma_f32_16x16x32_bf16 v[70:73], v[168:171], v[212:215], v[70:73]
	v_mfma_f32_16x16x32_bf16 v[66:69], v[176:179], v[212:215], v[66:69]
	v_mfma_f32_16x16x32_bf16 v[118:121], v[172:175], v[188:191], v[118:121]
	v_mfma_f32_16x16x32_bf16 v[114:117], v[180:183], v[188:191], v[114:117]
	v_mfma_f32_16x16x32_bf16 v[102:105], v[172:175], v[200:203], v[102:105]
	v_mfma_f32_16x16x32_bf16 v[98:101], v[180:183], v[200:203], v[98:101]
	v_mfma_f32_16x16x32_bf16 v[86:89], v[172:175], v[208:211], v[86:89]
	v_mfma_f32_16x16x32_bf16 v[82:85], v[180:183], v[208:211], v[82:85]
	v_mfma_f32_16x16x32_bf16 v[70:73], v[172:175], v[216:219], v[70:73]
	v_mfma_f32_16x16x32_bf16 v[66:69], v[180:183], v[216:219], v[66:69]
	s_setprio 0
	s_barrier
; #define PG8_STAGE(bufoff, gbase, voff) do { _Pragma("unroll") for (int _i = 0; _i < 2; ++_i) \
;         __builtin_amdgcn_global_load_lds((const unsigned*)((const char*)(gbase) + (voff)[_i]), (PG8_LAS unsigned*)(lds + (bufoff) + ldsw + _i * 8192), 16, 0, 0); } while (0)
; #define PG8_LDA(dst, b, h) do { _Pragma("unroll") for (int m = 0; m < 4; ++m) _Pragma("unroll") for (int k = 0; k < 2; ++k) dst[m][k] = *(const PG8_LAS bf16x8*)(lds + PG8_SA(b, h) + aoff + m * 2048 + k * 1024); } while (0)
; #define PG8_MMA(ai, bj, At, Bt) do { __builtin_amdgcn_s_setprio(1); _Pragma("unroll") for (int m = 0; m < 4; ++m) _Pragma("unroll") for (int n = 0; n < 2; ++n) _Pragma("unroll") for (int k = 0; k < 2; ++k) \
;         acc[ai][bj][m][n] = __builtin_amdgcn_mfma_f32_16x16x32_bf16(Bt[n][k], At[m][k], acc[ai][bj][m][n], 0, 0, 0); __builtin_amdgcn_s_setprio(0); } while (0)
; #define PG8_WAIT_V(n) asm volatile("s_waitcnt vmcnt(" #n ")" ::: "memory")
; #define PG8_WAIT_L(n) asm volatile("s_waitcnt lgkmcnt(" #n ")" ::: "memory")
; #define PG8_BAR __builtin_amdgcn_s_barrier()
; #define PG8_SCHED __builtin_amdgcn_sched_barrier(0)
; template <class Epi, class Sched, bool ALIGN_EPI = false, bool SP2 = false>
; __device__ __forceinline__ void gemm_phase(PG8_LAS unsigned char* lds, const Gemm g, const Sched& S, const Epi& E) {
;     ...
;         for (int t = 0; t < nt; t += 2) {
;             const bool last = (t == nt - 2);
;             const char* a1 = cA + (size_t)(t + 1) * kstep;
;             const char* a2 = last ? nA : cA + (size_t)(t + 2) * kstep; const char* b2 = last ? nB : cB + (size_t)(t + 2) * kstep;
;             const char* a3 = a2 + kstep; const char* b3 = b2 + kstep;
;     ...
;             PG8_LDA(At, 1, 1); PG8_STAGE(PG8_SB(1, 0), b3, voffB); PG8_STAGE(PG8_SB(1, 1), b3 + hstep, voffB); PG8_STAGE(PG8_SA(1, 0), a3, voffA);
;             PG8_WAIT_V(8); PG8_WAIT_L(0); PG8_BAR; PG8_MMA(1, 0, At, B0); PG8_MMA(1, 1, At, B1); PG8_BAR; PG8_SCHED;
	s_add_i32 s52, s54, s2
	v_lshl_add_u64 v[192:193], v[192:193], 0, s[16:17]
	s_mov_b32 m0, s52
	ds_read_b128 v[184:187], v154 offset:49152
	ds_read_b128 v[188:191], v154 offset:50176
	ds_read_b128 v[196:199], v154 offset:51200
	ds_read_b128 v[200:203], v154 offset:52224
	ds_read_b128 v[204:207], v154 offset:53248
	ds_read_b128 v[208:211], v154 offset:54272
	ds_read_b128 v[212:215], v154 offset:55296
	ds_read_b128 v[216:219], v154 offset:56320
	global_load_lds_dwordx4 v[192:193], off
	s_add_i32 m0, s52, 0x2000
	s_add_u32 s52, s86, 0x80080
	v_lshl_add_u64 v[192:193], v[220:221], 0, s[16:17]
	s_addc_u32 s53, s87, 0
	s_add_i32 s54, s55, s2
	global_load_lds_dwordx4 v[192:193], off
	v_lshl_add_u64 v[192:193], s[52:53], 0, v[132:133]
	s_mov_b32 m0, s54
	s_nop 0
	global_load_lds_dwordx4 v[192:193], off
	v_lshl_add_u64 v[192:193], s[52:53], 0, v[136:137]
	s_add_i32 m0, s54, 0x2000
	s_nop 0
	global_load_lds_dwordx4 v[192:193], off
	v_lshl_add_u64 v[192:193], v[222:223], 0, s[16:17]
	s_mov_b32 m0, s42
	s_nop 0
	global_load_lds_dwordx4 v[192:193], off
	v_lshl_add_u64 v[192:193], v[224:225], 0, s[16:17]
	s_mov_b32 m0, s43
	s_nop 0
	global_load_lds_dwordx4 v[192:193], off
	s_waitcnt vmcnt(8)
	s_waitcnt lgkmcnt(0)
	s_barrier
	s_setprio 1
	v_mfma_f32_16x16x32_bf16 v[62:65], v[146:149], v[184:187], v[62:65]
	v_mfma_f32_16x16x32_bf16 v[58:61], v[160:163], v[184:187], v[58:61]
	v_mfma_f32_16x16x32_bf16 v[46:49], v[146:149], v[196:199], v[46:49]
	v_mfma_f32_16x16x32_bf16 v[42:45], v[160:163], v[196:199], v[42:45]
	v_mfma_f32_16x16x32_bf16 v[30:33], v[146:149], v[204:207], v[30:33]
	v_mfma_f32_16x16x32_bf16 v[26:29], v[160:163], v[204:207], v[26:29]
	v_mfma_f32_16x16x32_bf16 v[14:17], v[146:149], v[212:215], v[14:17]
	v_mfma_f32_16x16x32_bf16 v[10:13], v[160:163], v[212:215], v[10:13]
	v_mfma_f32_16x16x32_bf16 v[62:65], v[156:159], v[188:191], v[62:65]
	v_mfma_f32_16x16x32_bf16 v[58:61], v[164:167], v[188:191], v[58:61]
	v_mfma_f32_16x16x32_bf16 v[46:49], v[156:159], v[200:203], v[46:49]
	v_mfma_f32_16x16x32_bf16 v[42:45], v[164:167], v[200:203], v[42:45]
	v_mfma_f32_16x16x32_bf16 v[30:33], v[156:159], v[208:211], v[30:33]
	v_mfma_f32_16x16x32_bf16 v[26:29], v[164:167], v[208:211], v[26:29]
	v_mfma_f32_16x16x32_bf16 v[14:17], v[156:159], v[216:219], v[14:17]
	v_mfma_f32_16x16x32_bf16 v[10:13], v[164:167], v[216:219], v[10:13]
	s_setprio 0
	s_setprio 1
	v_mfma_f32_16x16x32_bf16 v[54:57], v[168:171], v[184:187], v[54:57]
	v_mfma_f32_16x16x32_bf16 v[50:53], v[176:179], v[184:187], v[50:53]
	v_mfma_f32_16x16x32_bf16 v[38:41], v[168:171], v[196:199], v[38:41]
	v_mfma_f32_16x16x32_bf16 v[34:37], v[176:179], v[196:199], v[34:37]
	v_mfma_f32_16x16x32_bf16 v[22:25], v[168:171], v[204:207], v[22:25]
	v_mfma_f32_16x16x32_bf16 v[18:21], v[176:179], v[204:207], v[18:21]
	v_mfma_f32_16x16x32_bf16 v[6:9], v[168:171], v[212:215], v[6:9]
	v_mfma_f32_16x16x32_bf16 v[2:5], v[176:179], v[212:215], v[2:5]
	v_mfma_f32_16x16x32_bf16 v[54:57], v[172:175], v[188:191], v[54:57]
	v_mfma_f32_16x16x32_bf16 v[50:53], v[180:183], v[188:191], v[50:53]
	v_mfma_f32_16x16x32_bf16 v[38:41], v[172:175], v[200:203], v[38:41]
	v_mfma_f32_16x16x32_bf16 v[34:37], v[180:183], v[200:203], v[34:37]
	v_mfma_f32_16x16x32_bf16 v[22:25], v[172:175], v[208:211], v[22:25]
	v_mfma_f32_16x16x32_bf16 v[18:21], v[180:183], v[208:211], v[18:21]
	v_mfma_f32_16x16x32_bf16 v[6:9], v[172:175], v[216:219], v[6:9]
	v_mfma_f32_16x16x32_bf16 v[2:5], v[180:183], v[216:219], v[2:5]
	s_setprio 0
	s_barrier
	s_add_i32 s51, s51, 2
	s_add_u32 vcc_lo, vcc_lo, 0x100
	s_addc_u32 vcc_hi, vcc_hi, 0
	s_add_u32 s49, s49, 0x100
	s_addc_u32 s50, s50, 0
	s_cmp_gt_u32 s51, 29
	s_cbranch_scc0 .LBB0_244
	s_and_b64 vcc, exec, s[18:19]
	s_cbranch_vccz .LBB0_247
	s_barrier

; #define PG8_STAGE(bufoff, gbase, voff) do { _Pragma("unroll") for (int _i = 0; _i < 2; ++_i) \
;         __builtin_amdgcn_global_load_lds((const unsigned*)((const char*)(gbase) + (voff)[_i]), (PG8_LAS unsigned*)(lds + (bufoff) + ldsw + _i * 8192), 16, 0, 0); } while (0)
; #define PG8_LDA(dst, b, h) do { _Pragma("unroll") for (int m = 0; m < 4; ++m) _Pragma("unroll") for (int k = 0; k < 2; ++k) dst[m][k] = *(const PG8_LAS bf16x8*)(lds + PG8_SA(b, h) + aoff + m * 2048 + k * 1024); } while (0)
; #define PG8_LDB(dst, b, h) do { _Pragma("unroll") for (int n = 0; n < 2; ++n) _Pragma("unroll") for (int k = 0; k < 2; ++k) dst[n][k] = *(const PG8_LAS bf16x8*)(lds + PG8_SB(b, h) + boff + n * 2048 + k * 1024); } while (0)
; #define PG8_MMA(ai, bj, At, Bt) do { __builtin_amdgcn_s_setprio(1); _Pragma("unroll") for (int m = 0; m < 4; ++m) _Pragma("unroll") for (int n = 0; n < 2; ++n) _Pragma("unroll") for (int k = 0; k < 2; ++k) \
;         acc[ai][bj][m][n] = __builtin_amdgcn_mfma_f32_16x16x32_bf16(Bt[n][k], At[m][k], acc[ai][bj][m][n], 0, 0, 0); __builtin_amdgcn_s_setprio(0); } while (0)
; #define PG8_WAIT_V(n) asm volatile("s_waitcnt vmcnt(" #n ")" ::: "memory")
; #define PG8_BAR __builtin_amdgcn_s_barrier()
; template <class Epi, class Sched, bool ALIGN_EPI = false, bool SP2 = false>
; __device__ __forceinline__ void gemm_phase(PG8_LAS unsigned char* lds, const Gemm g, const Sched& S, const Epi& E) {
;     ...
;         for (int t = 0; t < nt; t += 2) {
;             const bool last = (t == nt - 2);
;             const char* a1 = cA + (size_t)(t + 1) * kstep;
;             const char* a2 = last ? nA : cA + (size_t)(t + 2) * kstep; const char* b2 = last ? nB : cB + (size_t)(t + 2) * kstep;
;             const char* a3 = a2 + kstep; const char* b3 = b2 + kstep;
;             if (last && has_next) S.a_ready(nxt);
;             if constexpr (SP2) {
;             PG8_LDB(B0, 0, 0); PG8_LDB(B1, 0, 1); PG8_SCHED; PG8_LDA(At, 0, 0); PG8_STAGE(PG8_SA(1, 1), a1 + hstep, voffA);
;             PG8_WAIT_V(8); PG8_WAIT_L(0); PG8_BAR; PG8_MMA(0, 0, At, B0); PG8_MMA(0, 1, At, B1); PG8_BAR; PG8_SCHED;
;             PG8_LDA(At, 0, 1); PG8_STAGE(PG8_SB(0, 0), b2, voffB); PG8_STAGE(PG8_SB(0, 1), b2 + hstep, voffB); PG8_STAGE(PG8_SA(0, 0), a2, voffA);
;             PG8_WAIT_V(8); PG8_WAIT_L(0); PG8_BAR; PG8_MMA(1, 0, At, B0); PG8_MMA(1, 1, At, B1); PG8_BAR; PG8_SCHED;
.LBB0_374:
	ds_read_b128 v[164:167], v154
	ds_read_b128 v[168:171], v154 offset:1024
	ds_read_b128 v[172:175], v154 offset:2048
	ds_read_b128 v[176:179], v154 offset:3072
	ds_read_b128 v[180:183], v155
	ds_read_b128 v[184:187], v155 offset:1024
	ds_read_b128 v[188:191], v155 offset:2048
	ds_read_b128 v[196:199], v155 offset:3072
	s_add_u32 s54, s70, 0xfffc0080
	s_addc_u32 s55, s71, -1
	s_cmp_eq_u32 s53, 12
	s_cselect_b32 s87, s21, s55
	s_cselect_b32 s86, s49, s54
	s_cselect_b32 s85, s19, s52
	s_cselect_b32 s84, s50, s51
	v_lshl_add_u64 v[150:151], s[70:71], 0, v[138:139]
	s_add_i32 m0, s37, 0xc000
	ds_read_b128 v[200:203], v156
	ds_read_b128 v[204:207], v156 offset:1024
	ds_read_b128 v[208:211], v156 offset:2048
	ds_read_b128 v[212:215], v156 offset:3072
	ds_read_b128 v[216:219], v156 offset:4096
	ds_read_b128 v[220:223], v156 offset:5120
	ds_read_b128 v[224:227], v156 offset:6144
	ds_read_b128 v[228:231], v156 offset:7168
	global_load_lds_dwordx4 v[150:151], off
	v_lshl_add_u64 v[150:151], s[70:71], 0, v[140:141]
	s_add_i32 m0, s37, 0xe000
	s_nop 0
	global_load_lds_dwordx4 v[150:151], off
	s_waitcnt vmcnt(8)
	s_waitcnt lgkmcnt(0)
	s_barrier
	s_setprio 1
	v_mfma_f32_16x16x32_bf16 v[126:129], v[164:167], v[200:203], v[126:129]
	v_mfma_f32_16x16x32_bf16 v[122:125], v[172:175], v[200:203], v[122:125]
	v_mfma_f32_16x16x32_bf16 v[114:117], v[164:167], v[208:211], v[114:117]
	v_mfma_f32_16x16x32_bf16 v[106:109], v[172:175], v[208:211], v[106:109]
	v_mfma_f32_16x16x32_bf16 v[98:101], v[164:167], v[216:219], v[98:101]
	v_mfma_f32_16x16x32_bf16 v[90:93], v[172:175], v[216:219], v[90:93]
	v_mfma_f32_16x16x32_bf16 v[82:85], v[164:167], v[224:227], v[82:85]
	v_mfma_f32_16x16x32_bf16 v[74:77], v[172:175], v[224:227], v[74:77]
	v_mfma_f32_16x16x32_bf16 v[126:129], v[168:171], v[204:207], v[126:129]
	v_mfma_f32_16x16x32_bf16 v[122:125], v[176:179], v[204:207], v[122:125]
	v_mfma_f32_16x16x32_bf16 v[114:117], v[168:171], v[212:215], v[114:117]
	v_mfma_f32_16x16x32_bf16 v[106:109], v[176:179], v[212:215], v[106:109]
	v_mfma_f32_16x16x32_bf16 v[98:101], v[168:171], v[220:223], v[98:101]
	v_mfma_f32_16x16x32_bf16 v[90:93], v[176:179], v[220:223], v[90:93]
	v_mfma_f32_16x16x32_bf16 v[82:85], v[168:171], v[228:231], v[82:85]
	v_mfma_f32_16x16x32_bf16 v[74:77], v[176:179], v[228:231], v[74:77]
	s_setprio 0
	s_setprio 1
	v_mfma_f32_16x16x32_bf16 v[118:121], v[180:183], v[200:203], v[118:121]
	v_mfma_f32_16x16x32_bf16 v[110:113], v[188:191], v[200:203], v[110:113]
	v_mfma_f32_16x16x32_bf16 v[102:105], v[180:183], v[208:211], v[102:105]
	v_mfma_f32_16x16x32_bf16 v[94:97], v[188:191], v[208:211], v[94:97]
	v_mfma_f32_16x16x32_bf16 v[86:89], v[180:183], v[216:219], v[86:89]
	v_mfma_f32_16x16x32_bf16 v[78:81], v[188:191], v[216:219], v[78:81]
	v_mfma_f32_16x16x32_bf16 v[70:73], v[180:183], v[224:227], v[70:73]
	v_mfma_f32_16x16x32_bf16 v[66:69], v[188:191], v[224:227], v[66:69]
	v_mfma_f32_16x16x32_bf16 v[118:121], v[184:187], v[204:207], v[118:121]
	v_mfma_f32_16x16x32_bf16 v[110:113], v[196:199], v[204:207], v[110:113]
	v_mfma_f32_16x16x32_bf16 v[102:105], v[184:187], v[212:215], v[102:105]
	v_mfma_f32_16x16x32_bf16 v[94:97], v[196:199], v[212:215], v[94:97]
	v_mfma_f32_16x16x32_bf16 v[86:89], v[184:187], v[220:223], v[86:89]
	v_mfma_f32_16x16x32_bf16 v[78:81], v[196:199], v[220:223], v[78:81]
	v_mfma_f32_16x16x32_bf16 v[70:73], v[184:187], v[228:231], v[70:73]
	v_mfma_f32_16x16x32_bf16 v[66:69], v[196:199], v[228:231], v[66:69]
	s_setprio 0
	s_barrier
	s_add_i32 s54, s45, s2
	v_lshl_add_u64 v[150:151], s[84:85], 0, v[134:135]
	s_mov_b32 m0, s54
	ds_read_b128 v[200:203], v156 offset:16384
	ds_read_b128 v[204:207], v156 offset:17408
	ds_read_b128 v[208:211], v156 offset:18432
	ds_read_b128 v[212:215], v156 offset:19456
	ds_read_b128 v[216:219], v156 offset:20480
	ds_read_b128 v[220:223], v156 offset:21504
	ds_read_b128 v[224:227], v156 offset:22528
	ds_read_b128 v[228:231], v156 offset:23552
	global_load_lds_dwordx4 v[150:151], off
	s_add_i32 m0, s54, 0x2000
	s_add_u32 s54, s84, 0x40000
	v_lshl_add_u64 v[192:193], s[84:85], 0, v[130:131]
	s_addc_u32 s55, s85, 0
	s_add_i32 s56, s46, s2
	global_load_lds_dwordx4 v[192:193], off
	v_lshl_add_u64 v[232:233], s[54:55], 0, v[134:135]
	s_mov_b32 m0, s56
	v_lshl_add_u64 v[234:235], s[86:87], 0, v[132:133]
	global_load_lds_dwordx4 v[232:233], off
	v_lshl_add_u64 v[232:233], s[54:55], 0, v[130:131]
	s_add_i32 m0, s56, 0x2000
	s_nop 0
	global_load_lds_dwordx4 v[232:233], off
	v_lshl_add_u64 v[232:233], s[86:87], 0, v[136:137]
	s_mov_b32 m0, s37
	s_nop 0
	global_load_lds_dwordx4 v[232:233], off
	s_mov_b32 m0, s38
	s_nop 0
	global_load_lds_dwordx4 v[234:235], off
	s_waitcnt vmcnt(8)
	s_waitcnt lgkmcnt(0)
	s_barrier
; #define PG8_STAGE(bufoff, gbase, voff) do { _Pragma("unroll") for (int _i = 0; _i < 2; ++_i) \
;         __builtin_amdgcn_global_load_lds((const unsigned*)((const char*)(gbase) + (voff)[_i]), (PG8_LAS unsigned*)(lds + (bufoff) + ldsw + _i * 8192), 16, 0, 0); } while (0)
; #define PG8_LDA(dst, b, h) do { _Pragma("unroll") for (int m = 0; m < 4; ++m) _Pragma("unroll") for (int k = 0; k < 2; ++k) dst[m][k] = *(const PG8_LAS bf16x8*)(lds + PG8_SA(b, h) + aoff + m * 2048 + k * 1024); } while (0)
; #define PG8_LDB(dst, b, h) do { _Pragma("unroll") for (int n = 0; n < 2; ++n) _Pragma("unroll") for (int k = 0; k < 2; ++k) dst[n][k] = *(const PG8_LAS bf16x8*)(lds + PG8_SB(b, h) + boff + n * 2048 + k * 1024); } while (0)
; #define PG8_MMA(ai, bj, At, Bt) do { __builtin_amdgcn_s_setprio(1); _Pragma("unroll") for (int m = 0; m < 4; ++m) _Pragma("unroll") for (int n = 0; n < 2; ++n) _Pragma("unroll") for (int k = 0; k < 2; ++k) \
;         acc[ai][bj][m][n] = __builtin_amdgcn_mfma_f32_16x16x32_bf16(Bt[n][k], At[m][k], acc[ai][bj][m][n], 0, 0, 0); __builtin_amdgcn_s_setprio(0); } while (0)
; #define PG8_WAIT_V(n) asm volatile("s_waitcnt vmcnt(" #n ")" ::: "memory")
; #define PG8_WAIT_L(n) asm volatile("s_waitcnt lgkmcnt(" #n ")" ::: "memory")
; #define PG8_BAR __builtin_amdgcn_s_barrier()
; #define PG8_SCHED __builtin_amdgcn_sched_barrier(0)
; template <class Epi, class Sched, bool ALIGN_EPI = false, bool SP2 = false>
; __device__ __forceinline__ void gemm_phase(PG8_LAS unsigned char* lds, const Gemm g, const Sched& S, const Epi& E) {
;     ...
;             PG8_WAIT_V(8); PG8_WAIT_L(0); PG8_BAR; PG8_MMA(1, 0, At, B0); PG8_MMA(1, 1, At, B1); PG8_BAR; PG8_SCHED;
;             PG8_LDB(B0, 1, 0); PG8_LDB(B1, 1, 1); PG8_SCHED; PG8_LDA(At, 1, 0); PG8_STAGE(PG8_SA(0, 1), a2 + hstep, voffA);
;             PG8_WAIT_V(8); PG8_WAIT_L(0); PG8_BAR; PG8_MMA(0, 0, At, B0); PG8_MMA(0, 1, At, B1); PG8_BAR; PG8_SCHED;
	s_setprio 1
	v_mfma_f32_16x16x32_bf16 v[62:65], v[164:167], v[200:203], v[62:65]
	v_mfma_f32_16x16x32_bf16 v[58:61], v[172:175], v[200:203], v[58:61]
	v_mfma_f32_16x16x32_bf16 v[50:53], v[164:167], v[208:211], v[50:53]
	v_mfma_f32_16x16x32_bf16 v[42:45], v[172:175], v[208:211], v[42:45]
	v_mfma_f32_16x16x32_bf16 v[34:37], v[164:167], v[216:219], v[34:37]
	v_mfma_f32_16x16x32_bf16 v[26:29], v[172:175], v[216:219], v[26:29]
	v_mfma_f32_16x16x32_bf16 v[18:21], v[164:167], v[224:227], v[18:21]
	v_mfma_f32_16x16x32_bf16 v[10:13], v[172:175], v[224:227], v[10:13]
	v_mfma_f32_16x16x32_bf16 v[62:65], v[168:171], v[204:207], v[62:65]
	v_mfma_f32_16x16x32_bf16 v[58:61], v[176:179], v[204:207], v[58:61]
	v_mfma_f32_16x16x32_bf16 v[50:53], v[168:171], v[212:215], v[50:53]
	v_mfma_f32_16x16x32_bf16 v[42:45], v[176:179], v[212:215], v[42:45]
	v_mfma_f32_16x16x32_bf16 v[34:37], v[168:171], v[220:223], v[34:37]
	v_mfma_f32_16x16x32_bf16 v[26:29], v[176:179], v[220:223], v[26:29]
	v_mfma_f32_16x16x32_bf16 v[18:21], v[168:171], v[228:231], v[18:21]
	v_mfma_f32_16x16x32_bf16 v[10:13], v[176:179], v[228:231], v[10:13]
	s_setprio 0
	s_setprio 1
	v_mfma_f32_16x16x32_bf16 v[54:57], v[180:183], v[200:203], v[54:57]
	v_mfma_f32_16x16x32_bf16 v[46:49], v[188:191], v[200:203], v[46:49]
	v_mfma_f32_16x16x32_bf16 v[38:41], v[180:183], v[208:211], v[38:41]
	v_mfma_f32_16x16x32_bf16 v[30:33], v[188:191], v[208:211], v[30:33]
	v_mfma_f32_16x16x32_bf16 v[22:25], v[180:183], v[216:219], v[22:25]
	v_mfma_f32_16x16x32_bf16 v[14:17], v[188:191], v[216:219], v[14:17]
	v_mfma_f32_16x16x32_bf16 v[6:9], v[180:183], v[224:227], v[6:9]
	v_mfma_f32_16x16x32_bf16 v[2:5], v[188:191], v[224:227], v[2:5]
	v_mfma_f32_16x16x32_bf16 v[54:57], v[184:187], v[204:207], v[54:57]
	v_mfma_f32_16x16x32_bf16 v[46:49], v[196:199], v[204:207], v[46:49]
	v_mfma_f32_16x16x32_bf16 v[38:41], v[184:187], v[212:215], v[38:41]
	v_mfma_f32_16x16x32_bf16 v[30:33], v[196:199], v[212:215], v[30:33]
	v_mfma_f32_16x16x32_bf16 v[22:25], v[184:187], v[220:223], v[22:25]
	v_mfma_f32_16x16x32_bf16 v[14:17], v[196:199], v[220:223], v[14:17]
	v_mfma_f32_16x16x32_bf16 v[6:9], v[184:187], v[228:231], v[6:9]
	v_mfma_f32_16x16x32_bf16 v[2:5], v[196:199], v[228:231], v[2:5]
	s_setprio 0
	s_barrier
	s_add_i32 s56, 0, 0x18000
	v_add_u32_e32 v149, s56, v152
	s_add_i32 s57, 0, 0x1c000
	ds_read_b128 v[164:167], v149
	ds_read_b128 v[168:171], v149 offset:1024
	ds_read_b128 v[172:175], v149 offset:2048
	ds_read_b128 v[176:179], v149 offset:3072
	v_add_u32_e32 v149, s57, v152
	ds_read_b128 v[180:183], v149
	ds_read_b128 v[184:187], v149 offset:1024
	ds_read_b128 v[188:191], v149 offset:2048
	ds_read_b128 v[196:199], v149 offset:3072
	s_add_u32 s54, s86, 0x40000
	s_addc_u32 s55, s87, 0
	s_mov_b32 m0, s39
	v_lshl_add_u64 v[236:237], s[54:55], 0, v[136:137]
	ds_read_b128 v[200:203], v156 offset:32768
	ds_read_b128 v[204:207], v156 offset:33792
	ds_read_b128 v[208:211], v156 offset:34816
	ds_read_b128 v[212:215], v156 offset:35840
	ds_read_b128 v[216:219], v156 offset:36864
	ds_read_b128 v[220:223], v156 offset:37888
	ds_read_b128 v[224:227], v156 offset:38912
	ds_read_b128 v[228:231], v156 offset:39936
	global_load_lds_dwordx4 v[236:237], off
	v_lshl_add_u64 v[236:237], s[54:55], 0, v[132:133]
	s_mov_b32 m0, s40
	s_nop 0
	global_load_lds_dwordx4 v[236:237], off
	s_waitcnt vmcnt(8)
	s_waitcnt lgkmcnt(0)
	s_barrier
	s_setprio 1
	v_mfma_f32_16x16x32_bf16 v[126:129], v[164:167], v[200:203], v[126:129]
	v_mfma_f32_16x16x32_bf16 v[122:125], v[172:175], v[200:203], v[122:125]
	v_mfma_f32_16x16x32_bf16 v[114:117], v[164:167], v[208:211], v[114:117]
	v_mfma_f32_16x16x32_bf16 v[106:109], v[172:175], v[208:211], v[106:109]
	v_mfma_f32_16x16x32_bf16 v[98:101], v[164:167], v[216:219], v[98:101]
	v_mfma_f32_16x16x32_bf16 v[90:93], v[172:175], v[216:219], v[90:93]
	v_mfma_f32_16x16x32_bf16 v[82:85], v[164:167], v[224:227], v[82:85]
	v_mfma_f32_16x16x32_bf16 v[74:77], v[172:175], v[224:227], v[74:77]
	v_mfma_f32_16x16x32_bf16 v[126:129], v[168:171], v[204:207], v[126:129]
	v_mfma_f32_16x16x32_bf16 v[122:125], v[176:179], v[204:207], v[122:125]
	v_mfma_f32_16x16x32_bf16 v[114:117], v[168:171], v[212:215], v[114:117]
	v_mfma_f32_16x16x32_bf16 v[106:109], v[176:179], v[212:215], v[106:109]
	v_mfma_f32_16x16x32_bf16 v[98:101], v[168:171], v[220:223], v[98:101]
	v_mfma_f32_16x16x32_bf16 v[90:93], v[176:179], v[220:223], v[90:93]
	v_mfma_f32_16x16x32_bf16 v[82:85], v[168:171], v[228:231], v[82:85]
	v_mfma_f32_16x16x32_bf16 v[74:77], v[176:179], v[228:231], v[74:77]
	s_setprio 0
	s_setprio 1
	v_mfma_f32_16x16x32_bf16 v[118:121], v[180:183], v[200:203], v[118:121]
	v_mfma_f32_16x16x32_bf16 v[110:113], v[188:191], v[200:203], v[110:113]
	v_mfma_f32_16x16x32_bf16 v[102:105], v[180:183], v[208:211], v[102:105]
	v_mfma_f32_16x16x32_bf16 v[94:97], v[188:191], v[208:211], v[94:97]
	v_mfma_f32_16x16x32_bf16 v[86:89], v[180:183], v[216:219], v[86:89]
	v_mfma_f32_16x16x32_bf16 v[78:81], v[188:191], v[216:219], v[78:81]
	v_mfma_f32_16x16x32_bf16 v[70:73], v[180:183], v[224:227], v[70:73]
	v_mfma_f32_16x16x32_bf16 v[66:69], v[188:191], v[224:227], v[66:69]
	v_mfma_f32_16x16x32_bf16 v[118:121], v[184:187], v[204:207], v[118:121]
	v_mfma_f32_16x16x32_bf16 v[110:113], v[196:199], v[204:207], v[110:113]
	v_mfma_f32_16x16x32_bf16 v[102:105], v[184:187], v[212:215], v[102:105]
	v_mfma_f32_16x16x32_bf16 v[94:97], v[196:199], v[212:215], v[94:97]
	v_mfma_f32_16x16x32_bf16 v[86:89], v[184:187], v[220:223], v[86:89]
	v_mfma_f32_16x16x32_bf16 v[78:81], v[196:199], v[220:223], v[78:81]
	v_mfma_f32_16x16x32_bf16 v[70:73], v[184:187], v[228:231], v[70:73]
	v_mfma_f32_16x16x32_bf16 v[66:69], v[196:199], v[228:231], v[66:69]
	s_setprio 0
	s_barrier
; #define PG8_STAGE(bufoff, gbase, voff) do { _Pragma("unroll") for (int _i = 0; _i < 2; ++_i) \
;         __builtin_amdgcn_global_load_lds((const unsigned*)((const char*)(gbase) + (voff)[_i]), (PG8_LAS unsigned*)(lds + (bufoff) + ldsw + _i * 8192), 16, 0, 0); } while (0)
; #define PG8_LDA(dst, b, h) do { _Pragma("unroll") for (int m = 0; m < 4; ++m) _Pragma("unroll") for (int k = 0; k < 2; ++k) dst[m][k] = *(const PG8_LAS bf16x8*)(lds + PG8_SA(b, h) + aoff + m * 2048 + k * 1024); } while (0)
; #define PG8_MMA(ai, bj, At, Bt) do { __builtin_amdgcn_s_setprio(1); _Pragma("unroll") for (int m = 0; m < 4; ++m) _Pragma("unroll") for (int n = 0; n < 2; ++n) _Pragma("unroll") for (int k = 0; k < 2; ++k) \
;         acc[ai][bj][m][n] = __builtin_amdgcn_mfma_f32_16x16x32_bf16(Bt[n][k], At[m][k], acc[ai][bj][m][n], 0, 0, 0); __builtin_amdgcn_s_setprio(0); } while (0)
; #define PG8_WAIT_V(n) asm volatile("s_waitcnt vmcnt(" #n ")" ::: "memory")
; #define PG8_WAIT_L(n) asm volatile("s_waitcnt lgkmcnt(" #n ")" ::: "memory")
; #define PG8_BAR __builtin_amdgcn_s_barrier()
; #define PG8_SCHED __builtin_amdgcn_sched_barrier(0)
; template <class Epi, class Sched, bool ALIGN_EPI = false, bool SP2 = false>
; __device__ __forceinline__ void gemm_phase(PG8_LAS unsigned char* lds, const Gemm g, const Sched& S, const Epi& E) {
;     ...
;         for (int t = 0; t < nt; t += 2) {
;             const bool last = (t == nt - 2);
;             const char* a1 = cA + (size_t)(t + 1) * kstep;
;             const char* a2 = last ? nA : cA + (size_t)(t + 2) * kstep; const char* b2 = last ? nB : cB + (size_t)(t + 2) * kstep;
;             const char* a3 = a2 + kstep; const char* b3 = b2 + kstep;
;     ...
;             PG8_LDA(At, 1, 1); PG8_STAGE(PG8_SB(1, 0), b3, voffB); PG8_STAGE(PG8_SB(1, 1), b3 + hstep, voffB); PG8_STAGE(PG8_SA(1, 0), a3, voffA);
;             PG8_WAIT_V(8); PG8_WAIT_L(0); PG8_BAR; PG8_MMA(1, 0, At, B0); PG8_MMA(1, 1, At, B1); PG8_BAR; PG8_SCHED;
	s_add_i32 s54, s56, s2
	v_lshl_add_u64 v[150:151], v[150:151], 0, s[14:15]
	s_mov_b32 m0, s54
	ds_read_b128 v[200:203], v156 offset:49152
	ds_read_b128 v[204:207], v156 offset:50176
	ds_read_b128 v[208:211], v156 offset:51200
	ds_read_b128 v[212:215], v156 offset:52224
	ds_read_b128 v[216:219], v156 offset:53248
	ds_read_b128 v[220:223], v156 offset:54272
	ds_read_b128 v[224:227], v156 offset:55296
	ds_read_b128 v[228:231], v156 offset:56320
	global_load_lds_dwordx4 v[150:151], off
	s_add_i32 m0, s54, 0x2000
	s_add_u32 s54, s84, 0x40080
	v_lshl_add_u64 v[150:151], v[192:193], 0, s[14:15]
	s_addc_u32 s55, s85, 0
	s_add_i32 s56, s57, s2
	global_load_lds_dwordx4 v[150:151], off
	v_lshl_add_u64 v[150:151], s[54:55], 0, v[134:135]
	s_mov_b32 m0, s56
	s_nop 0
	global_load_lds_dwordx4 v[150:151], off
	v_lshl_add_u64 v[150:151], s[54:55], 0, v[130:131]
	s_add_i32 m0, s56, 0x2000
	s_nop 0
	global_load_lds_dwordx4 v[150:151], off
	v_lshl_add_u64 v[150:151], v[232:233], 0, s[14:15]
	s_mov_b32 m0, s42
	s_nop 0
	global_load_lds_dwordx4 v[150:151], off
	v_lshl_add_u64 v[150:151], v[234:235], 0, s[14:15]
	s_mov_b32 m0, s43
	s_nop 0
	global_load_lds_dwordx4 v[150:151], off
	s_waitcnt vmcnt(8)
	s_waitcnt lgkmcnt(0)
	s_barrier
	s_setprio 1
	v_mfma_f32_16x16x32_bf16 v[62:65], v[164:167], v[200:203], v[62:65]
	v_mfma_f32_16x16x32_bf16 v[58:61], v[172:175], v[200:203], v[58:61]
	v_mfma_f32_16x16x32_bf16 v[50:53], v[164:167], v[208:211], v[50:53]
	v_mfma_f32_16x16x32_bf16 v[42:45], v[172:175], v[208:211], v[42:45]
	v_mfma_f32_16x16x32_bf16 v[34:37], v[164:167], v[216:219], v[34:37]
	v_mfma_f32_16x16x32_bf16 v[26:29], v[172:175], v[216:219], v[26:29]
	v_mfma_f32_16x16x32_bf16 v[18:21], v[164:167], v[224:227], v[18:21]
	v_mfma_f32_16x16x32_bf16 v[10:13], v[172:175], v[224:227], v[10:13]
	v_mfma_f32_16x16x32_bf16 v[62:65], v[168:171], v[204:207], v[62:65]
	v_mfma_f32_16x16x32_bf16 v[58:61], v[176:179], v[204:207], v[58:61]
	v_mfma_f32_16x16x32_bf16 v[50:53], v[168:171], v[212:215], v[50:53]
	v_mfma_f32_16x16x32_bf16 v[42:45], v[176:179], v[212:215], v[42:45]
	v_mfma_f32_16x16x32_bf16 v[34:37], v[168:171], v[220:223], v[34:37]
	v_mfma_f32_16x16x32_bf16 v[26:29], v[176:179], v[220:223], v[26:29]
	v_mfma_f32_16x16x32_bf16 v[18:21], v[168:171], v[228:231], v[18:21]
	v_mfma_f32_16x16x32_bf16 v[10:13], v[176:179], v[228:231], v[10:13]
	s_setprio 0
	s_setprio 1
	v_mfma_f32_16x16x32_bf16 v[54:57], v[180:183], v[200:203], v[54:57]
	v_mfma_f32_16x16x32_bf16 v[46:49], v[188:191], v[200:203], v[46:49]
	v_mfma_f32_16x16x32_bf16 v[38:41], v[180:183], v[208:211], v[38:41]
	v_mfma_f32_16x16x32_bf16 v[30:33], v[188:191], v[208:211], v[30:33]
	v_mfma_f32_16x16x32_bf16 v[22:25], v[180:183], v[216:219], v[22:25]
	v_mfma_f32_16x16x32_bf16 v[14:17], v[188:191], v[216:219], v[14:17]
	v_mfma_f32_16x16x32_bf16 v[6:9], v[180:183], v[224:227], v[6:9]
	v_mfma_f32_16x16x32_bf16 v[2:5], v[188:191], v[224:227], v[2:5]
	v_mfma_f32_16x16x32_bf16 v[54:57], v[184:187], v[204:207], v[54:57]
	v_mfma_f32_16x16x32_bf16 v[46:49], v[196:199], v[204:207], v[46:49]
	v_mfma_f32_16x16x32_bf16 v[38:41], v[184:187], v[212:215], v[38:41]
	v_mfma_f32_16x16x32_bf16 v[30:33], v[196:199], v[212:215], v[30:33]
	v_mfma_f32_16x16x32_bf16 v[22:25], v[184:187], v[220:223], v[22:25]
	v_mfma_f32_16x16x32_bf16 v[14:17], v[196:199], v[220:223], v[14:17]
	v_mfma_f32_16x16x32_bf16 v[6:9], v[184:187], v[228:231], v[6:9]
	v_mfma_f32_16x16x32_bf16 v[2:5], v[196:199], v[228:231], v[2:5]
	s_setprio 0
	s_barrier
	s_add_i32 s53, s53, 2
	s_add_u32 s70, s70, 0x100
	s_addc_u32 s71, s71, 0
	s_add_u32 s51, s51, 0x100
	s_addc_u32 s52, s52, 0
	s_cmp_gt_u32 s53, 13
	s_cbranch_scc0 .LBB0_374
	s_and_b64 vcc, exec, s[16:17]
	s_cbranch_vccz .LBB0_377
	s_barrier

; #define PG8_STAGE(bufoff, gbase, voff) do { _Pragma("unroll") for (int _i = 0; _i < 2; ++_i) \
;         __builtin_amdgcn_global_load_lds((const unsigned*)((const char*)(gbase) + (voff)[_i]), (PG8_LAS unsigned*)(lds + (bufoff) + ldsw + _i * 8192), 16, 0, 0); } while (0)
; #define PG8_LDA(dst, b, h) do { _Pragma("unroll") for (int m = 0; m < 4; ++m) _Pragma("unroll") for (int k = 0; k < 2; ++k) dst[m][k] = *(const PG8_LAS bf16x8*)(lds + PG8_SA(b, h) + aoff + m * 2048 + k * 1024); } while (0)
; #define PG8_LDB(dst, b, h) do { _Pragma("unroll") for (int n = 0; n < 2; ++n) _Pragma("unroll") for (int k = 0; k < 2; ++k) dst[n][k] = *(const PG8_LAS bf16x8*)(lds + PG8_SB(b, h) + boff + n * 2048 + k * 1024); } while (0)
; #define PG8_MMA(ai, bj, At, Bt) do { __builtin_amdgcn_s_setprio(1); _Pragma("unroll") for (int m = 0; m < 4; ++m) _Pragma("unroll") for (int n = 0; n < 2; ++n) _Pragma("unroll") for (int k = 0; k < 2; ++k) \
;         acc[ai][bj][m][n] = __builtin_amdgcn_mfma_f32_16x16x32_bf16(Bt[n][k], At[m][k], acc[ai][bj][m][n], 0, 0, 0); __builtin_amdgcn_s_setprio(0); } while (0)
; #define PG8_WAIT_V(n) asm volatile("s_waitcnt vmcnt(" #n ")" ::: "memory")
; #define PG8_BAR __builtin_amdgcn_s_barrier()
; template <class Epi, class Sched, bool ALIGN_EPI = false, bool SP2 = false>
; __device__ __forceinline__ void gemm_phase(PG8_LAS unsigned char* lds, const Gemm g, const Sched& S, const Epi& E) {
;     ...
;         for (int t = 0; t < nt; t += 2) {
;             const bool last = (t == nt - 2);
;             const char* a1 = cA + (size_t)(t + 1) * kstep;
;             const char* a2 = last ? nA : cA + (size_t)(t + 2) * kstep; const char* b2 = last ? nB : cB + (size_t)(t + 2) * kstep;
;             const char* a3 = a2 + kstep; const char* b3 = b2 + kstep;
;             if (last && has_next) S.a_ready(nxt);
;             if constexpr (SP2) {
;             PG8_LDB(B0, 0, 0); PG8_LDB(B1, 0, 1); PG8_SCHED; PG8_LDA(At, 0, 0); PG8_STAGE(PG8_SA(1, 1), a1 + hstep, voffA);
;             PG8_WAIT_V(8); PG8_WAIT_L(0); PG8_BAR; PG8_MMA(0, 0, At, B0); PG8_MMA(0, 1, At, B1); PG8_BAR; PG8_SCHED;
;             PG8_LDA(At, 0, 1); PG8_STAGE(PG8_SB(0, 0), b2, voffB); PG8_STAGE(PG8_SB(0, 1), b2 + hstep, voffB); PG8_STAGE(PG8_SA(0, 0), a2, voffA);
;             PG8_WAIT_V(8); PG8_WAIT_L(0); PG8_BAR; PG8_MMA(1, 0, At, B0); PG8_MMA(1, 1, At, B1); PG8_BAR; PG8_SCHED;
.LBB0_808:
	ds_read_b128 v[146:149], v152
	ds_read_b128 v[156:159], v152 offset:1024
	ds_read_b128 v[160:163], v152 offset:2048
	ds_read_b128 v[164:167], v152 offset:3072
	ds_read_b128 v[168:171], v153
	ds_read_b128 v[172:175], v153 offset:1024
	ds_read_b128 v[176:179], v153 offset:2048
	ds_read_b128 v[180:183], v153 offset:3072
	s_add_u32 s56, s40, 0xfffc0080
	s_addc_u32 s57, s41, -1
	s_cmp_eq_u32 s55, 12
	s_cselect_b32 s59, s21, s57
	s_cselect_b32 s58, s37, s56
	s_cselect_b32 s57, s19, s54
	s_cselect_b32 s56, s52, s53
	v_lshl_add_u64 v[192:193], s[40:41], 0, v[138:139]
	s_add_i32 m0, s3, 0xc000
	ds_read_b128 v[184:187], v154
	ds_read_b128 v[188:191], v154 offset:1024
	ds_read_b128 v[196:199], v154 offset:2048
	ds_read_b128 v[200:203], v154 offset:3072
	ds_read_b128 v[204:207], v154 offset:4096
	ds_read_b128 v[208:211], v154 offset:5120
	ds_read_b128 v[212:215], v154 offset:6144
	ds_read_b128 v[216:219], v154 offset:7168
	global_load_lds_dwordx4 v[192:193], off
	v_lshl_add_u64 v[192:193], s[40:41], 0, v[140:141]
	s_add_i32 m0, s3, 0xe000
	s_nop 0
	global_load_lds_dwordx4 v[192:193], off
	s_waitcnt vmcnt(8)
	s_waitcnt lgkmcnt(0)
	s_barrier
	s_setprio 1
	v_mfma_f32_16x16x32_bf16 v[126:129], v[146:149], v[184:187], v[126:129]
	v_mfma_f32_16x16x32_bf16 v[122:125], v[160:163], v[184:187], v[122:125]
	v_mfma_f32_16x16x32_bf16 v[110:113], v[146:149], v[196:199], v[110:113]
	v_mfma_f32_16x16x32_bf16 v[106:109], v[160:163], v[196:199], v[106:109]
	v_mfma_f32_16x16x32_bf16 v[94:97], v[146:149], v[204:207], v[94:97]
	v_mfma_f32_16x16x32_bf16 v[90:93], v[160:163], v[204:207], v[90:93]
	v_mfma_f32_16x16x32_bf16 v[78:81], v[146:149], v[212:215], v[78:81]
	v_mfma_f32_16x16x32_bf16 v[74:77], v[160:163], v[212:215], v[74:77]
	v_mfma_f32_16x16x32_bf16 v[126:129], v[156:159], v[188:191], v[126:129]
	v_mfma_f32_16x16x32_bf16 v[122:125], v[164:167], v[188:191], v[122:125]
	v_mfma_f32_16x16x32_bf16 v[110:113], v[156:159], v[200:203], v[110:113]
	v_mfma_f32_16x16x32_bf16 v[106:109], v[164:167], v[200:203], v[106:109]
	v_mfma_f32_16x16x32_bf16 v[94:97], v[156:159], v[208:211], v[94:97]
	v_mfma_f32_16x16x32_bf16 v[90:93], v[164:167], v[208:211], v[90:93]
	v_mfma_f32_16x16x32_bf16 v[78:81], v[156:159], v[216:219], v[78:81]
	v_mfma_f32_16x16x32_bf16 v[74:77], v[164:167], v[216:219], v[74:77]
	s_setprio 0
	s_setprio 1
	v_mfma_f32_16x16x32_bf16 v[118:121], v[168:171], v[184:187], v[118:121]
	v_mfma_f32_16x16x32_bf16 v[114:117], v[176:179], v[184:187], v[114:117]
	v_mfma_f32_16x16x32_bf16 v[102:105], v[168:171], v[196:199], v[102:105]
	v_mfma_f32_16x16x32_bf16 v[98:101], v[176:179], v[196:199], v[98:101]
	v_mfma_f32_16x16x32_bf16 v[86:89], v[168:171], v[204:207], v[86:89]
	v_mfma_f32_16x16x32_bf16 v[82:85], v[176:179], v[204:207], v[82:85]
	v_mfma_f32_16x16x32_bf16 v[70:73], v[168:171], v[212:215], v[70:73]
	v_mfma_f32_16x16x32_bf16 v[66:69], v[176:179], v[212:215], v[66:69]
	v_mfma_f32_16x16x32_bf16 v[118:121], v[172:175], v[188:191], v[118:121]
	v_mfma_f32_16x16x32_bf16 v[114:117], v[180:183], v[188:191], v[114:117]
	v_mfma_f32_16x16x32_bf16 v[102:105], v[172:175], v[200:203], v[102:105]
	v_mfma_f32_16x16x32_bf16 v[98:101], v[180:183], v[200:203], v[98:101]
	v_mfma_f32_16x16x32_bf16 v[86:89], v[172:175], v[208:211], v[86:89]
	v_mfma_f32_16x16x32_bf16 v[82:85], v[180:183], v[208:211], v[82:85]
	v_mfma_f32_16x16x32_bf16 v[70:73], v[172:175], v[216:219], v[70:73]
	v_mfma_f32_16x16x32_bf16 v[66:69], v[180:183], v[216:219], v[66:69]
	s_setprio 0
	s_barrier
	s_add_i32 s60, s49, s2
	v_lshl_add_u64 v[192:193], s[56:57], 0, v[132:133]
	s_mov_b32 m0, s60
	ds_read_b128 v[184:187], v154 offset:16384
	ds_read_b128 v[188:191], v154 offset:17408
	ds_read_b128 v[196:199], v154 offset:18432
	ds_read_b128 v[200:203], v154 offset:19456
	ds_read_b128 v[204:207], v154 offset:20480
	ds_read_b128 v[208:211], v154 offset:21504
	ds_read_b128 v[212:215], v154 offset:22528
	ds_read_b128 v[216:219], v154 offset:23552
	global_load_lds_dwordx4 v[192:193], off
	s_add_i32 m0, s60, 0x2000
	s_add_u32 s60, s56, 0x40000
	v_lshl_add_u64 v[220:221], s[56:57], 0, v[136:137]
	s_addc_u32 s61, s57, 0
	s_add_i32 s62, s50, s2
	global_load_lds_dwordx4 v[220:221], off
	v_lshl_add_u64 v[222:223], s[60:61], 0, v[132:133]
	s_mov_b32 m0, s62
	v_lshl_add_u64 v[224:225], s[58:59], 0, v[134:135]
	global_load_lds_dwordx4 v[222:223], off
	v_lshl_add_u64 v[222:223], s[60:61], 0, v[136:137]
	s_add_i32 m0, s62, 0x2000
	s_nop 0
	global_load_lds_dwordx4 v[222:223], off
	v_lshl_add_u64 v[222:223], s[58:59], 0, v[130:131]
	s_mov_b32 m0, s3
	s_nop 0
	global_load_lds_dwordx4 v[222:223], off
	s_mov_b32 m0, s39
	s_nop 0
	global_load_lds_dwordx4 v[224:225], off
	s_waitcnt vmcnt(8)
	s_waitcnt lgkmcnt(0)
	s_barrier
; #define PG8_STAGE(bufoff, gbase, voff) do { _Pragma("unroll") for (int _i = 0; _i < 2; ++_i) \
;         __builtin_amdgcn_global_load_lds((const unsigned*)((const char*)(gbase) + (voff)[_i]), (PG8_LAS unsigned*)(lds + (bufoff) + ldsw + _i * 8192), 16, 0, 0); } while (0)
; #define PG8_LDA(dst, b, h) do { _Pragma("unroll") for (int m = 0; m < 4; ++m) _Pragma("unroll") for (int k = 0; k < 2; ++k) dst[m][k] = *(const PG8_LAS bf16x8*)(lds + PG8_SA(b, h) + aoff + m * 2048 + k * 1024); } while (0)
; #define PG8_LDB(dst, b, h) do { _Pragma("unroll") for (int n = 0; n < 2; ++n) _Pragma("unroll") for (int k = 0; k < 2; ++k) dst[n][k] = *(const PG8_LAS bf16x8*)(lds + PG8_SB(b, h) + boff + n * 2048 + k * 1024); } while (0)
; #define PG8_MMA(ai, bj, At, Bt) do { __builtin_amdgcn_s_setprio(1); _Pragma("unroll") for (int m = 0; m < 4; ++m) _Pragma("unroll") for (int n = 0; n < 2; ++n) _Pragma("unroll") for (int k = 0; k < 2; ++k) \
;         acc[ai][bj][m][n] = __builtin_amdgcn_mfma_f32_16x16x32_bf16(Bt[n][k], At[m][k], acc[ai][bj][m][n], 0, 0, 0); __builtin_amdgcn_s_setprio(0); } while (0)
; #define PG8_WAIT_V(n) asm volatile("s_waitcnt vmcnt(" #n ")" ::: "memory")
; #define PG8_WAIT_L(n) asm volatile("s_waitcnt lgkmcnt(" #n ")" ::: "memory")
; #define PG8_BAR __builtin_amdgcn_s_barrier()
; #define PG8_SCHED __builtin_amdgcn_sched_barrier(0)
; template <class Epi, class Sched, bool ALIGN_EPI = false, bool SP2 = false>
; __device__ __forceinline__ void gemm_phase(PG8_LAS unsigned char* lds, const Gemm g, const Sched& S, const Epi& E) {
;     ...
;             PG8_WAIT_V(8); PG8_WAIT_L(0); PG8_BAR; PG8_MMA(1, 0, At, B0); PG8_MMA(1, 1, At, B1); PG8_BAR; PG8_SCHED;
;             PG8_LDB(B0, 1, 0); PG8_LDB(B1, 1, 1); PG8_SCHED; PG8_LDA(At, 1, 0); PG8_STAGE(PG8_SA(0, 1), a2 + hstep, voffA);
;             PG8_WAIT_V(8); PG8_WAIT_L(0); PG8_BAR; PG8_MMA(0, 0, At, B0); PG8_MMA(0, 1, At, B1); PG8_BAR; PG8_SCHED;
	s_setprio 1
	v_mfma_f32_16x16x32_bf16 v[62:65], v[146:149], v[184:187], v[62:65]
	v_mfma_f32_16x16x32_bf16 v[58:61], v[160:163], v[184:187], v[58:61]
	v_mfma_f32_16x16x32_bf16 v[46:49], v[146:149], v[196:199], v[46:49]
	v_mfma_f32_16x16x32_bf16 v[42:45], v[160:163], v[196:199], v[42:45]
	v_mfma_f32_16x16x32_bf16 v[30:33], v[146:149], v[204:207], v[30:33]
	v_mfma_f32_16x16x32_bf16 v[26:29], v[160:163], v[204:207], v[26:29]
	v_mfma_f32_16x16x32_bf16 v[14:17], v[146:149], v[212:215], v[14:17]
	v_mfma_f32_16x16x32_bf16 v[10:13], v[160:163], v[212:215], v[10:13]
	v_mfma_f32_16x16x32_bf16 v[62:65], v[156:159], v[188:191], v[62:65]
	v_mfma_f32_16x16x32_bf16 v[58:61], v[164:167], v[188:191], v[58:61]
	v_mfma_f32_16x16x32_bf16 v[46:49], v[156:159], v[200:203], v[46:49]
	v_mfma_f32_16x16x32_bf16 v[42:45], v[164:167], v[200:203], v[42:45]
	v_mfma_f32_16x16x32_bf16 v[30:33], v[156:159], v[208:211], v[30:33]
	v_mfma_f32_16x16x32_bf16 v[26:29], v[164:167], v[208:211], v[26:29]
	v_mfma_f32_16x16x32_bf16 v[14:17], v[156:159], v[216:219], v[14:17]
	v_mfma_f32_16x16x32_bf16 v[10:13], v[164:167], v[216:219], v[10:13]
	s_setprio 0
	s_setprio 1
	v_mfma_f32_16x16x32_bf16 v[54:57], v[168:171], v[184:187], v[54:57]
	v_mfma_f32_16x16x32_bf16 v[50:53], v[176:179], v[184:187], v[50:53]
	v_mfma_f32_16x16x32_bf16 v[38:41], v[168:171], v[196:199], v[38:41]
	v_mfma_f32_16x16x32_bf16 v[34:37], v[176:179], v[196:199], v[34:37]
	v_mfma_f32_16x16x32_bf16 v[22:25], v[168:171], v[204:207], v[22:25]
	v_mfma_f32_16x16x32_bf16 v[18:21], v[176:179], v[204:207], v[18:21]
	v_mfma_f32_16x16x32_bf16 v[6:9], v[168:171], v[212:215], v[6:9]
	v_mfma_f32_16x16x32_bf16 v[2:5], v[176:179], v[212:215], v[2:5]
	v_mfma_f32_16x16x32_bf16 v[54:57], v[172:175], v[188:191], v[54:57]
	v_mfma_f32_16x16x32_bf16 v[50:53], v[180:183], v[188:191], v[50:53]
	v_mfma_f32_16x16x32_bf16 v[38:41], v[172:175], v[200:203], v[38:41]
	v_mfma_f32_16x16x32_bf16 v[34:37], v[180:183], v[200:203], v[34:37]
	v_mfma_f32_16x16x32_bf16 v[22:25], v[172:175], v[208:211], v[22:25]
	v_mfma_f32_16x16x32_bf16 v[18:21], v[180:183], v[208:211], v[18:21]
	v_mfma_f32_16x16x32_bf16 v[6:9], v[172:175], v[216:219], v[6:9]
	v_mfma_f32_16x16x32_bf16 v[2:5], v[180:183], v[216:219], v[2:5]
	s_setprio 0
	s_barrier
	s_add_i32 s60, 0, 0x18000
	s_add_i32 s61, 0, 0x1c000
	v_add_u32_e32 v164, s60, v150
	v_add_u32_e32 v180, s61, v150
	ds_read_b128 v[146:149], v164
	ds_read_b128 v[156:159], v164 offset:1024
	ds_read_b128 v[160:163], v164 offset:2048
	ds_read_b128 v[164:167], v164 offset:3072
	ds_read_b128 v[168:171], v180
	ds_read_b128 v[172:175], v180 offset:1024
	ds_read_b128 v[176:179], v180 offset:2048
	ds_read_b128 v[180:183], v180 offset:3072
	s_add_u32 s58, s58, 0x40000
	s_addc_u32 s59, s59, 0
	s_mov_b32 m0, s42
	v_lshl_add_u64 v[226:227], s[58:59], 0, v[130:131]
	ds_read_b128 v[184:187], v154 offset:32768
	ds_read_b128 v[188:191], v154 offset:33792
	ds_read_b128 v[196:199], v154 offset:34816
	ds_read_b128 v[200:203], v154 offset:35840
	ds_read_b128 v[204:207], v154 offset:36864
	ds_read_b128 v[208:211], v154 offset:37888
	ds_read_b128 v[212:215], v154 offset:38912
	ds_read_b128 v[216:219], v154 offset:39936
	global_load_lds_dwordx4 v[226:227], off
	v_lshl_add_u64 v[226:227], s[58:59], 0, v[134:135]
	s_mov_b32 m0, s43
	s_nop 0
	global_load_lds_dwordx4 v[226:227], off
	s_waitcnt vmcnt(8)
	s_waitcnt lgkmcnt(0)
	s_barrier
	s_setprio 1
	v_mfma_f32_16x16x32_bf16 v[126:129], v[146:149], v[184:187], v[126:129]
	v_mfma_f32_16x16x32_bf16 v[122:125], v[160:163], v[184:187], v[122:125]
	v_mfma_f32_16x16x32_bf16 v[110:113], v[146:149], v[196:199], v[110:113]
	v_mfma_f32_16x16x32_bf16 v[106:109], v[160:163], v[196:199], v[106:109]
	v_mfma_f32_16x16x32_bf16 v[94:97], v[146:149], v[204:207], v[94:97]
	v_mfma_f32_16x16x32_bf16 v[90:93], v[160:163], v[204:207], v[90:93]
	v_mfma_f32_16x16x32_bf16 v[78:81], v[146:149], v[212:215], v[78:81]
	v_mfma_f32_16x16x32_bf16 v[74:77], v[160:163], v[212:215], v[74:77]
	v_mfma_f32_16x16x32_bf16 v[126:129], v[156:159], v[188:191], v[126:129]
	v_mfma_f32_16x16x32_bf16 v[122:125], v[164:167], v[188:191], v[122:125]
	v_mfma_f32_16x16x32_bf16 v[110:113], v[156:159], v[200:203], v[110:113]
	v_mfma_f32_16x16x32_bf16 v[106:109], v[164:167], v[200:203], v[106:109]
	v_mfma_f32_16x16x32_bf16 v[94:97], v[156:159], v[208:211], v[94:97]
	v_mfma_f32_16x16x32_bf16 v[90:93], v[164:167], v[208:211], v[90:93]
	v_mfma_f32_16x16x32_bf16 v[78:81], v[156:159], v[216:219], v[78:81]
	v_mfma_f32_16x16x32_bf16 v[74:77], v[164:167], v[216:219], v[74:77]
	s_setprio 0
	s_setprio 1
	v_mfma_f32_16x16x32_bf16 v[118:121], v[168:171], v[184:187], v[118:121]
	v_mfma_f32_16x16x32_bf16 v[114:117], v[176:179], v[184:187], v[114:117]
	v_mfma_f32_16x16x32_bf16 v[102:105], v[168:171], v[196:199], v[102:105]
	v_mfma_f32_16x16x32_bf16 v[98:101], v[176:179], v[196:199], v[98:101]
	v_mfma_f32_16x16x32_bf16 v[86:89], v[168:171], v[204:207], v[86:89]
	v_mfma_f32_16x16x32_bf16 v[82:85], v[176:179], v[204:207], v[82:85]
	v_mfma_f32_16x16x32_bf16 v[70:73], v[168:171], v[212:215], v[70:73]
	v_mfma_f32_16x16x32_bf16 v[66:69], v[176:179], v[212:215], v[66:69]
	v_mfma_f32_16x16x32_bf16 v[118:121], v[172:175], v[188:191], v[118:121]
	v_mfma_f32_16x16x32_bf16 v[114:117], v[180:183], v[188:191], v[114:117]
	v_mfma_f32_16x16x32_bf16 v[102:105], v[172:175], v[200:203], v[102:105]
	v_mfma_f32_16x16x32_bf16 v[98:101], v[180:183], v[200:203], v[98:101]
	v_mfma_f32_16x16x32_bf16 v[86:89], v[172:175], v[208:211], v[86:89]
	v_mfma_f32_16x16x32_bf16 v[82:85], v[180:183], v[208:211], v[82:85]
	v_mfma_f32_16x16x32_bf16 v[70:73], v[172:175], v[216:219], v[70:73]
	v_mfma_f32_16x16x32_bf16 v[66:69], v[180:183], v[216:219], v[66:69]
	s_setprio 0
	s_barrier
; #define PG8_STAGE(bufoff, gbase, voff) do { _Pragma("unroll") for (int _i = 0; _i < 2; ++_i) \
;         __builtin_amdgcn_global_load_lds((const unsigned*)((const char*)(gbase) + (voff)[_i]), (PG8_LAS unsigned*)(lds + (bufoff) + ldsw + _i * 8192), 16, 0, 0); } while (0)
; #define PG8_LDA(dst, b, h) do { _Pragma("unroll") for (int m = 0; m < 4; ++m) _Pragma("unroll") for (int k = 0; k < 2; ++k) dst[m][k] = *(const PG8_LAS bf16x8*)(lds + PG8_SA(b, h) + aoff + m * 2048 + k * 1024); } while (0)
; #define PG8_MMA(ai, bj, At, Bt) do { __builtin_amdgcn_s_setprio(1); _Pragma("unroll") for (int m = 0; m < 4; ++m) _Pragma("unroll") for (int n = 0; n < 2; ++n) _Pragma("unroll") for (int k = 0; k < 2; ++k) \
;         acc[ai][bj][m][n] = __builtin_amdgcn_mfma_f32_16x16x32_bf16(Bt[n][k], At[m][k], acc[ai][bj][m][n], 0, 0, 0); __builtin_amdgcn_s_setprio(0); } while (0)
; #define PG8_WAIT_V(n) asm volatile("s_waitcnt vmcnt(" #n ")" ::: "memory")
; #define PG8_WAIT_L(n) asm volatile("s_waitcnt lgkmcnt(" #n ")" ::: "memory")
; #define PG8_BAR __builtin_amdgcn_s_barrier()
; #define PG8_SCHED __builtin_amdgcn_sched_barrier(0)
; template <class Epi, class Sched, bool ALIGN_EPI = false, bool SP2 = false>
; __device__ __forceinline__ void gemm_phase(PG8_LAS unsigned char* lds, const Gemm g, const Sched& S, const Epi& E) {
;     ...
;         for (int t = 0; t < nt; t += 2) {
;             const bool last = (t == nt - 2);
;             const char* a1 = cA + (size_t)(t + 1) * kstep;
;             const char* a2 = last ? nA : cA + (size_t)(t + 2) * kstep; const char* b2 = last ? nB : cB + (size_t)(t + 2) * kstep;
;             const char* a3 = a2 + kstep; const char* b3 = b2 + kstep;
;     ...
;             PG8_LDA(At, 1, 1); PG8_STAGE(PG8_SB(1, 0), b3, voffB); PG8_STAGE(PG8_SB(1, 1), b3 + hstep, voffB); PG8_STAGE(PG8_SA(1, 0), a3, voffA);
;             PG8_WAIT_V(8); PG8_WAIT_L(0); PG8_BAR; PG8_MMA(1, 0, At, B0); PG8_MMA(1, 1, At, B1); PG8_BAR; PG8_SCHED;
	s_add_i32 s58, s60, s2
	v_lshl_add_u64 v[192:193], v[192:193], 0, s[14:15]
	s_mov_b32 m0, s58
	ds_read_b128 v[184:187], v154 offset:49152
	ds_read_b128 v[188:191], v154 offset:50176
	ds_read_b128 v[196:199], v154 offset:51200
	ds_read_b128 v[200:203], v154 offset:52224
	ds_read_b128 v[204:207], v154 offset:53248
	ds_read_b128 v[208:211], v154 offset:54272
	ds_read_b128 v[212:215], v154 offset:55296
	ds_read_b128 v[216:219], v154 offset:56320
	global_load_lds_dwordx4 v[192:193], off
	s_add_i32 m0, s58, 0x2000
	s_add_u32 s56, s56, 0x40080
	v_lshl_add_u64 v[192:193], v[220:221], 0, s[14:15]
	s_addc_u32 s57, s57, 0
	s_add_i32 s58, s61, s2
	global_load_lds_dwordx4 v[192:193], off
	v_lshl_add_u64 v[192:193], s[56:57], 0, v[132:133]
	s_mov_b32 m0, s58
	s_nop 0
	global_load_lds_dwordx4 v[192:193], off
	v_lshl_add_u64 v[192:193], s[56:57], 0, v[136:137]
	s_add_i32 m0, s58, 0x2000
	s_nop 0
	global_load_lds_dwordx4 v[192:193], off
	v_lshl_add_u64 v[192:193], v[222:223], 0, s[14:15]
	s_mov_b32 m0, s45
	s_nop 0
	global_load_lds_dwordx4 v[192:193], off
	v_lshl_add_u64 v[192:193], v[224:225], 0, s[14:15]
	s_mov_b32 m0, s46
	s_nop 0
	global_load_lds_dwordx4 v[192:193], off
	s_waitcnt vmcnt(8)
	s_waitcnt lgkmcnt(0)
	s_barrier
	s_setprio 1
	v_mfma_f32_16x16x32_bf16 v[62:65], v[146:149], v[184:187], v[62:65]
	v_mfma_f32_16x16x32_bf16 v[58:61], v[160:163], v[184:187], v[58:61]
	v_mfma_f32_16x16x32_bf16 v[46:49], v[146:149], v[196:199], v[46:49]
	v_mfma_f32_16x16x32_bf16 v[42:45], v[160:163], v[196:199], v[42:45]
	v_mfma_f32_16x16x32_bf16 v[30:33], v[146:149], v[204:207], v[30:33]
	v_mfma_f32_16x16x32_bf16 v[26:29], v[160:163], v[204:207], v[26:29]
	v_mfma_f32_16x16x32_bf16 v[14:17], v[146:149], v[212:215], v[14:17]
	v_mfma_f32_16x16x32_bf16 v[10:13], v[160:163], v[212:215], v[10:13]
	v_mfma_f32_16x16x32_bf16 v[62:65], v[156:159], v[188:191], v[62:65]
	v_mfma_f32_16x16x32_bf16 v[58:61], v[164:167], v[188:191], v[58:61]
	v_mfma_f32_16x16x32_bf16 v[46:49], v[156:159], v[200:203], v[46:49]
	v_mfma_f32_16x16x32_bf16 v[42:45], v[164:167], v[200:203], v[42:45]
	v_mfma_f32_16x16x32_bf16 v[30:33], v[156:159], v[208:211], v[30:33]
	v_mfma_f32_16x16x32_bf16 v[26:29], v[164:167], v[208:211], v[26:29]
	v_mfma_f32_16x16x32_bf16 v[14:17], v[156:159], v[216:219], v[14:17]
	v_mfma_f32_16x16x32_bf16 v[10:13], v[164:167], v[216:219], v[10:13]
	s_setprio 0
	s_setprio 1
	v_mfma_f32_16x16x32_bf16 v[54:57], v[168:171], v[184:187], v[54:57]
	v_mfma_f32_16x16x32_bf16 v[50:53], v[176:179], v[184:187], v[50:53]
	v_mfma_f32_16x16x32_bf16 v[38:41], v[168:171], v[196:199], v[38:41]
	v_mfma_f32_16x16x32_bf16 v[34:37], v[176:179], v[196:199], v[34:37]
	v_mfma_f32_16x16x32_bf16 v[22:25], v[168:171], v[204:207], v[22:25]
	v_mfma_f32_16x16x32_bf16 v[18:21], v[176:179], v[204:207], v[18:21]
	v_mfma_f32_16x16x32_bf16 v[6:9], v[168:171], v[212:215], v[6:9]
	v_mfma_f32_16x16x32_bf16 v[2:5], v[176:179], v[212:215], v[2:5]
	v_mfma_f32_16x16x32_bf16 v[54:57], v[172:175], v[188:191], v[54:57]
	v_mfma_f32_16x16x32_bf16 v[50:53], v[180:183], v[188:191], v[50:53]
	v_mfma_f32_16x16x32_bf16 v[38:41], v[172:175], v[200:203], v[38:41]
	v_mfma_f32_16x16x32_bf16 v[34:37], v[180:183], v[200:203], v[34:37]
	v_mfma_f32_16x16x32_bf16 v[22:25], v[172:175], v[208:211], v[22:25]
	v_mfma_f32_16x16x32_bf16 v[18:21], v[180:183], v[208:211], v[18:21]
	v_mfma_f32_16x16x32_bf16 v[6:9], v[172:175], v[216:219], v[6:9]
	v_mfma_f32_16x16x32_bf16 v[2:5], v[180:183], v[216:219], v[2:5]
	s_setprio 0
	s_barrier
	s_add_i32 s55, s55, 2
	s_add_u32 s40, s40, 0x100
	s_addc_u32 s41, s41, 0
	s_add_u32 s53, s53, 0x100
	s_addc_u32 s54, s54, 0
	s_cmp_gt_u32 s55, 13
	s_cbranch_scc0 .LBB0_808
	s_and_b64 vcc, exec, s[16:17]
	s_cbranch_vccz .LBB0_811
	s_barrier

; #define PG8_STAGE(bufoff, gbase, voff) do { _Pragma("unroll") for (int _i = 0; _i < 2; ++_i) \
;         __builtin_amdgcn_global_load_lds((const unsigned*)((const char*)(gbase) + (voff)[_i]), (PG8_LAS unsigned*)(lds + (bufoff) + ldsw + _i * 8192), 16, 0, 0); } while (0)
; #define PG8_LDA(dst, b, h) do { _Pragma("unroll") for (int m = 0; m < 4; ++m) _Pragma("unroll") for (int k = 0; k < 2; ++k) dst[m][k] = *(const PG8_LAS bf16x8*)(lds + PG8_SA(b, h) + aoff + m * 2048 + k * 1024); } while (0)
; #define PG8_LDB(dst, b, h) do { _Pragma("unroll") for (int n = 0; n < 2; ++n) _Pragma("unroll") for (int k = 0; k < 2; ++k) dst[n][k] = *(const PG8_LAS bf16x8*)(lds + PG8_SB(b, h) + boff + n * 2048 + k * 1024); } while (0)
; #define PG8_MMA(ai, bj, At, Bt) do { __builtin_amdgcn_s_setprio(1); _Pragma("unroll") for (int m = 0; m < 4; ++m) _Pragma("unroll") for (int n = 0; n < 2; ++n) _Pragma("unroll") for (int k = 0; k < 2; ++k) \
;         acc[ai][bj][m][n] = __builtin_amdgcn_mfma_f32_16x16x32_bf16(Bt[n][k], At[m][k], acc[ai][bj][m][n], 0, 0, 0); __builtin_amdgcn_s_setprio(0); } while (0)
; #define PG8_WAIT_V(n) asm volatile("s_waitcnt vmcnt(" #n ")" ::: "memory")
; #define PG8_BAR __builtin_amdgcn_s_barrier()
; template <class Epi, class Sched, bool ALIGN_EPI = false, bool SP2 = false>
; __device__ __forceinline__ void gemm_phase(PG8_LAS unsigned char* lds, const Gemm g, const Sched& S, const Epi& E) {
;     ...
;         for (int t = 0; t < nt; t += 2) {
;             const bool last = (t == nt - 2);
;             const char* a1 = cA + (size_t)(t + 1) * kstep;
;             const char* a2 = last ? nA : cA + (size_t)(t + 2) * kstep; const char* b2 = last ? nB : cB + (size_t)(t + 2) * kstep;
;             const char* a3 = a2 + kstep; const char* b3 = b2 + kstep;
;             if (last && has_next) S.a_ready(nxt);
;             if constexpr (SP2) {
;             PG8_LDB(B0, 0, 0); PG8_LDB(B1, 0, 1); PG8_SCHED; PG8_LDA(At, 0, 0); PG8_STAGE(PG8_SA(1, 1), a1 + hstep, voffA);
;             PG8_WAIT_V(8); PG8_WAIT_L(0); PG8_BAR; PG8_MMA(0, 0, At, B0); PG8_MMA(0, 1, At, B1); PG8_BAR; PG8_SCHED;
;             PG8_LDA(At, 0, 1); PG8_STAGE(PG8_SB(0, 0), b2, voffB); PG8_STAGE(PG8_SB(0, 1), b2 + hstep, voffB); PG8_STAGE(PG8_SA(0, 0), a2, voffA);
;             PG8_WAIT_V(8); PG8_WAIT_L(0); PG8_BAR; PG8_MMA(1, 0, At, B0); PG8_MMA(1, 1, At, B1); PG8_BAR; PG8_SCHED;
.LBB0_946:
	ds_read_b128 v[166:169], v154
	ds_read_b128 v[170:173], v154 offset:1024
	ds_read_b128 v[174:177], v154 offset:2048
	ds_read_b128 v[178:181], v154 offset:3072
	ds_read_b128 v[182:185], v155
	ds_read_b128 v[186:189], v155 offset:1024
	ds_read_b128 v[190:193], v155 offset:2048
	ds_read_b128 v[196:199], v155 offset:3072
	s_add_u32 s36, s34, 0xfffc0080
	s_addc_u32 s37, s35, -1
	s_cmp_eq_u32 s55, 12
	s_cselect_b32 s39, s19, s37
	s_cselect_b32 s38, s51, s36
	s_cselect_b32 s37, s17, s54
	s_cselect_b32 s36, s52, s53
	v_lshl_add_u64 v[150:151], s[34:35], 0, v[138:139]
	s_add_i32 m0, s40, 0xc000
	ds_read_b128 v[200:203], v156
	ds_read_b128 v[204:207], v156 offset:1024
	ds_read_b128 v[208:211], v156 offset:2048
	ds_read_b128 v[212:215], v156 offset:3072
	ds_read_b128 v[216:219], v156 offset:4096
	ds_read_b128 v[220:223], v156 offset:5120
	ds_read_b128 v[224:227], v156 offset:6144
	ds_read_b128 v[228:231], v156 offset:7168
	global_load_lds_dwordx4 v[150:151], off
	v_lshl_add_u64 v[150:151], s[34:35], 0, v[140:141]
	s_add_i32 m0, s40, 0xe000
	s_nop 0
	global_load_lds_dwordx4 v[150:151], off
	s_waitcnt vmcnt(8)
	s_waitcnt lgkmcnt(0)
	s_barrier
	s_setprio 1
	v_mfma_f32_16x16x32_bf16 v[126:129], v[166:169], v[200:203], v[126:129]
	v_mfma_f32_16x16x32_bf16 v[122:125], v[174:177], v[200:203], v[122:125]
	v_mfma_f32_16x16x32_bf16 v[110:113], v[166:169], v[208:211], v[110:113]
	v_mfma_f32_16x16x32_bf16 v[106:109], v[174:177], v[208:211], v[106:109]
	v_mfma_f32_16x16x32_bf16 v[94:97], v[166:169], v[216:219], v[94:97]
	v_mfma_f32_16x16x32_bf16 v[90:93], v[174:177], v[216:219], v[90:93]
	v_mfma_f32_16x16x32_bf16 v[78:81], v[166:169], v[224:227], v[78:81]
	v_mfma_f32_16x16x32_bf16 v[74:77], v[174:177], v[224:227], v[74:77]
	v_mfma_f32_16x16x32_bf16 v[126:129], v[170:173], v[204:207], v[126:129]
	v_mfma_f32_16x16x32_bf16 v[122:125], v[178:181], v[204:207], v[122:125]
	v_mfma_f32_16x16x32_bf16 v[110:113], v[170:173], v[212:215], v[110:113]
	v_mfma_f32_16x16x32_bf16 v[106:109], v[178:181], v[212:215], v[106:109]
	v_mfma_f32_16x16x32_bf16 v[94:97], v[170:173], v[220:223], v[94:97]
	v_mfma_f32_16x16x32_bf16 v[90:93], v[178:181], v[220:223], v[90:93]
	v_mfma_f32_16x16x32_bf16 v[78:81], v[170:173], v[228:231], v[78:81]
	v_mfma_f32_16x16x32_bf16 v[74:77], v[178:181], v[228:231], v[74:77]
	s_setprio 0
	s_setprio 1
	v_mfma_f32_16x16x32_bf16 v[118:121], v[182:185], v[200:203], v[118:121]
	v_mfma_f32_16x16x32_bf16 v[114:117], v[190:193], v[200:203], v[114:117]
	v_mfma_f32_16x16x32_bf16 v[102:105], v[182:185], v[208:211], v[102:105]
	v_mfma_f32_16x16x32_bf16 v[98:101], v[190:193], v[208:211], v[98:101]
	v_mfma_f32_16x16x32_bf16 v[86:89], v[182:185], v[216:219], v[86:89]
	v_mfma_f32_16x16x32_bf16 v[82:85], v[190:193], v[216:219], v[82:85]
	v_mfma_f32_16x16x32_bf16 v[70:73], v[182:185], v[224:227], v[70:73]
	v_mfma_f32_16x16x32_bf16 v[66:69], v[190:193], v[224:227], v[66:69]
	v_mfma_f32_16x16x32_bf16 v[118:121], v[186:189], v[204:207], v[118:121]
	v_mfma_f32_16x16x32_bf16 v[114:117], v[196:199], v[204:207], v[114:117]
	v_mfma_f32_16x16x32_bf16 v[102:105], v[186:189], v[212:215], v[102:105]
	v_mfma_f32_16x16x32_bf16 v[98:101], v[196:199], v[212:215], v[98:101]
	v_mfma_f32_16x16x32_bf16 v[86:89], v[186:189], v[220:223], v[86:89]
	v_mfma_f32_16x16x32_bf16 v[82:85], v[196:199], v[220:223], v[82:85]
	v_mfma_f32_16x16x32_bf16 v[70:73], v[186:189], v[228:231], v[70:73]
	v_mfma_f32_16x16x32_bf16 v[66:69], v[196:199], v[228:231], v[66:69]
	s_setprio 0
	s_barrier
	s_add_i32 s56, s48, s3
	v_lshl_add_u64 v[150:151], s[36:37], 0, v[132:133]
	s_mov_b32 m0, s56
	ds_read_b128 v[200:203], v156 offset:16384
	ds_read_b128 v[204:207], v156 offset:17408
	ds_read_b128 v[208:211], v156 offset:18432
	ds_read_b128 v[212:215], v156 offset:19456
	ds_read_b128 v[216:219], v156 offset:20480
	ds_read_b128 v[220:223], v156 offset:21504
	ds_read_b128 v[224:227], v156 offset:22528
	ds_read_b128 v[228:231], v156 offset:23552
	global_load_lds_dwordx4 v[150:151], off
	s_add_i32 m0, s56, 0x2000
	s_add_u32 s56, s36, 0x40000
	v_lshl_add_u64 v[232:233], s[36:37], 0, v[136:137]
	s_addc_u32 s57, s37, 0
	s_add_i32 s58, s49, s3
	global_load_lds_dwordx4 v[232:233], off
	v_lshl_add_u64 v[234:235], s[56:57], 0, v[132:133]
	s_mov_b32 m0, s58
	v_lshl_add_u64 v[236:237], s[38:39], 0, v[134:135]
	global_load_lds_dwordx4 v[234:235], off
	v_lshl_add_u64 v[234:235], s[56:57], 0, v[136:137]
	s_add_i32 m0, s58, 0x2000
	s_nop 0
	global_load_lds_dwordx4 v[234:235], off
	v_lshl_add_u64 v[234:235], s[38:39], 0, v[130:131]
	s_mov_b32 m0, s40
	s_nop 0
	global_load_lds_dwordx4 v[234:235], off
	s_mov_b32 m0, s41
	s_nop 0
	global_load_lds_dwordx4 v[236:237], off
	s_waitcnt vmcnt(8)
	s_waitcnt lgkmcnt(0)
	s_barrier
; #define PG8_STAGE(bufoff, gbase, voff) do { _Pragma("unroll") for (int _i = 0; _i < 2; ++_i) \
;         __builtin_amdgcn_global_load_lds((const unsigned*)((const char*)(gbase) + (voff)[_i]), (PG8_LAS unsigned*)(lds + (bufoff) + ldsw + _i * 8192), 16, 0, 0); } while (0)
; #define PG8_LDA(dst, b, h) do { _Pragma("unroll") for (int m = 0; m < 4; ++m) _Pragma("unroll") for (int k = 0; k < 2; ++k) dst[m][k] = *(const PG8_LAS bf16x8*)(lds + PG8_SA(b, h) + aoff + m * 2048 + k * 1024); } while (0)
; #define PG8_LDB(dst, b, h) do { _Pragma("unroll") for (int n = 0; n < 2; ++n) _Pragma("unroll") for (int k = 0; k < 2; ++k) dst[n][k] = *(const PG8_LAS bf16x8*)(lds + PG8_SB(b, h) + boff + n * 2048 + k * 1024); } while (0)
; #define PG8_MMA(ai, bj, At, Bt) do { __builtin_amdgcn_s_setprio(1); _Pragma("unroll") for (int m = 0; m < 4; ++m) _Pragma("unroll") for (int n = 0; n < 2; ++n) _Pragma("unroll") for (int k = 0; k < 2; ++k) \
;         acc[ai][bj][m][n] = __builtin_amdgcn_mfma_f32_16x16x32_bf16(Bt[n][k], At[m][k], acc[ai][bj][m][n], 0, 0, 0); __builtin_amdgcn_s_setprio(0); } while (0)
; #define PG8_WAIT_V(n) asm volatile("s_waitcnt vmcnt(" #n ")" ::: "memory")
; #define PG8_WAIT_L(n) asm volatile("s_waitcnt lgkmcnt(" #n ")" ::: "memory")
; #define PG8_BAR __builtin_amdgcn_s_barrier()
; #define PG8_SCHED __builtin_amdgcn_sched_barrier(0)
; template <class Epi, class Sched, bool ALIGN_EPI = false, bool SP2 = false>
; __device__ __forceinline__ void gemm_phase(PG8_LAS unsigned char* lds, const Gemm g, const Sched& S, const Epi& E) {
;     ...
;             PG8_WAIT_V(8); PG8_WAIT_L(0); PG8_BAR; PG8_MMA(1, 0, At, B0); PG8_MMA(1, 1, At, B1); PG8_BAR; PG8_SCHED;
;             PG8_LDB(B0, 1, 0); PG8_LDB(B1, 1, 1); PG8_SCHED; PG8_LDA(At, 1, 0); PG8_STAGE(PG8_SA(0, 1), a2 + hstep, voffA);
;             PG8_WAIT_V(8); PG8_WAIT_L(0); PG8_BAR; PG8_MMA(0, 0, At, B0); PG8_MMA(0, 1, At, B1); PG8_BAR; PG8_SCHED;
	s_setprio 1
	v_mfma_f32_16x16x32_bf16 v[62:65], v[166:169], v[200:203], v[62:65]
	v_mfma_f32_16x16x32_bf16 v[58:61], v[174:177], v[200:203], v[58:61]
	v_mfma_f32_16x16x32_bf16 v[46:49], v[166:169], v[208:211], v[46:49]
	v_mfma_f32_16x16x32_bf16 v[42:45], v[174:177], v[208:211], v[42:45]
	v_mfma_f32_16x16x32_bf16 v[30:33], v[166:169], v[216:219], v[30:33]
	v_mfma_f32_16x16x32_bf16 v[26:29], v[174:177], v[216:219], v[26:29]
	v_mfma_f32_16x16x32_bf16 v[14:17], v[166:169], v[224:227], v[14:17]
	v_mfma_f32_16x16x32_bf16 v[10:13], v[174:177], v[224:227], v[10:13]
	v_mfma_f32_16x16x32_bf16 v[62:65], v[170:173], v[204:207], v[62:65]
	v_mfma_f32_16x16x32_bf16 v[58:61], v[178:181], v[204:207], v[58:61]
	v_mfma_f32_16x16x32_bf16 v[46:49], v[170:173], v[212:215], v[46:49]
	v_mfma_f32_16x16x32_bf16 v[42:45], v[178:181], v[212:215], v[42:45]
	v_mfma_f32_16x16x32_bf16 v[30:33], v[170:173], v[220:223], v[30:33]
	v_mfma_f32_16x16x32_bf16 v[26:29], v[178:181], v[220:223], v[26:29]
	v_mfma_f32_16x16x32_bf16 v[14:17], v[170:173], v[228:231], v[14:17]
	v_mfma_f32_16x16x32_bf16 v[10:13], v[178:181], v[228:231], v[10:13]
	s_setprio 0
	s_setprio 1
	v_mfma_f32_16x16x32_bf16 v[54:57], v[182:185], v[200:203], v[54:57]
	v_mfma_f32_16x16x32_bf16 v[50:53], v[190:193], v[200:203], v[50:53]
	v_mfma_f32_16x16x32_bf16 v[38:41], v[182:185], v[208:211], v[38:41]
	v_mfma_f32_16x16x32_bf16 v[34:37], v[190:193], v[208:211], v[34:37]
	v_mfma_f32_16x16x32_bf16 v[22:25], v[182:185], v[216:219], v[22:25]
	v_mfma_f32_16x16x32_bf16 v[18:21], v[190:193], v[216:219], v[18:21]
	v_mfma_f32_16x16x32_bf16 v[6:9], v[182:185], v[224:227], v[6:9]
	v_mfma_f32_16x16x32_bf16 v[2:5], v[190:193], v[224:227], v[2:5]
	v_mfma_f32_16x16x32_bf16 v[54:57], v[186:189], v[204:207], v[54:57]
	v_mfma_f32_16x16x32_bf16 v[50:53], v[196:199], v[204:207], v[50:53]
	v_mfma_f32_16x16x32_bf16 v[38:41], v[186:189], v[212:215], v[38:41]
	v_mfma_f32_16x16x32_bf16 v[34:37], v[196:199], v[212:215], v[34:37]
	v_mfma_f32_16x16x32_bf16 v[22:25], v[186:189], v[220:223], v[22:25]
	v_mfma_f32_16x16x32_bf16 v[18:21], v[196:199], v[220:223], v[18:21]
	v_mfma_f32_16x16x32_bf16 v[6:9], v[186:189], v[228:231], v[6:9]
	v_mfma_f32_16x16x32_bf16 v[2:5], v[196:199], v[228:231], v[2:5]
	s_setprio 0
	s_barrier
	s_add_i32 s56, 0, 0x18000
	v_add_u32_e32 v149, s56, v152
	s_add_i32 s57, 0, 0x1c000
	ds_read_b128 v[166:169], v149
	ds_read_b128 v[170:173], v149 offset:1024
	ds_read_b128 v[174:177], v149 offset:2048
	ds_read_b128 v[178:181], v149 offset:3072
	v_add_u32_e32 v149, s57, v152
	ds_read_b128 v[182:185], v149
	ds_read_b128 v[186:189], v149 offset:1024
	ds_read_b128 v[190:193], v149 offset:2048
	ds_read_b128 v[196:199], v149 offset:3072
	s_add_u32 s38, s38, 0x40000
	s_addc_u32 s39, s39, 0
	s_mov_b32 m0, s42
	v_lshl_add_u64 v[238:239], s[38:39], 0, v[130:131]
	ds_read_b128 v[200:203], v156 offset:32768
	ds_read_b128 v[204:207], v156 offset:33792
	ds_read_b128 v[208:211], v156 offset:34816
	ds_read_b128 v[212:215], v156 offset:35840
	ds_read_b128 v[216:219], v156 offset:36864
	ds_read_b128 v[220:223], v156 offset:37888
	ds_read_b128 v[224:227], v156 offset:38912
	ds_read_b128 v[228:231], v156 offset:39936
	global_load_lds_dwordx4 v[238:239], off
	v_lshl_add_u64 v[238:239], s[38:39], 0, v[134:135]
	s_mov_b32 m0, s43
	s_nop 0
	global_load_lds_dwordx4 v[238:239], off
	s_waitcnt vmcnt(8)
	s_waitcnt lgkmcnt(0)
	s_barrier
	s_setprio 1
	v_mfma_f32_16x16x32_bf16 v[126:129], v[166:169], v[200:203], v[126:129]
	v_mfma_f32_16x16x32_bf16 v[122:125], v[174:177], v[200:203], v[122:125]
	v_mfma_f32_16x16x32_bf16 v[110:113], v[166:169], v[208:211], v[110:113]
	v_mfma_f32_16x16x32_bf16 v[106:109], v[174:177], v[208:211], v[106:109]
	v_mfma_f32_16x16x32_bf16 v[94:97], v[166:169], v[216:219], v[94:97]
	v_mfma_f32_16x16x32_bf16 v[90:93], v[174:177], v[216:219], v[90:93]
	v_mfma_f32_16x16x32_bf16 v[78:81], v[166:169], v[224:227], v[78:81]
	v_mfma_f32_16x16x32_bf16 v[74:77], v[174:177], v[224:227], v[74:77]
	v_mfma_f32_16x16x32_bf16 v[126:129], v[170:173], v[204:207], v[126:129]
	v_mfma_f32_16x16x32_bf16 v[122:125], v[178:181], v[204:207], v[122:125]
	v_mfma_f32_16x16x32_bf16 v[110:113], v[170:173], v[212:215], v[110:113]
	v_mfma_f32_16x16x32_bf16 v[106:109], v[178:181], v[212:215], v[106:109]
	v_mfma_f32_16x16x32_bf16 v[94:97], v[170:173], v[220:223], v[94:97]
	v_mfma_f32_16x16x32_bf16 v[90:93], v[178:181], v[220:223], v[90:93]
	v_mfma_f32_16x16x32_bf16 v[78:81], v[170:173], v[228:231], v[78:81]
	v_mfma_f32_16x16x32_bf16 v[74:77], v[178:181], v[228:231], v[74:77]
	s_setprio 0
	s_setprio 1
	v_mfma_f32_16x16x32_bf16 v[118:121], v[182:185], v[200:203], v[118:121]
	v_mfma_f32_16x16x32_bf16 v[114:117], v[190:193], v[200:203], v[114:117]
	v_mfma_f32_16x16x32_bf16 v[102:105], v[182:185], v[208:211], v[102:105]
	v_mfma_f32_16x16x32_bf16 v[98:101], v[190:193], v[208:211], v[98:101]
	v_mfma_f32_16x16x32_bf16 v[86:89], v[182:185], v[216:219], v[86:89]
	v_mfma_f32_16x16x32_bf16 v[82:85], v[190:193], v[216:219], v[82:85]
	v_mfma_f32_16x16x32_bf16 v[70:73], v[182:185], v[224:227], v[70:73]
	v_mfma_f32_16x16x32_bf16 v[66:69], v[190:193], v[224:227], v[66:69]
	v_mfma_f32_16x16x32_bf16 v[118:121], v[186:189], v[204:207], v[118:121]
	v_mfma_f32_16x16x32_bf16 v[114:117], v[196:199], v[204:207], v[114:117]
	v_mfma_f32_16x16x32_bf16 v[102:105], v[186:189], v[212:215], v[102:105]
	v_mfma_f32_16x16x32_bf16 v[98:101], v[196:199], v[212:215], v[98:101]
	v_mfma_f32_16x16x32_bf16 v[86:89], v[186:189], v[220:223], v[86:89]
	v_mfma_f32_16x16x32_bf16 v[82:85], v[196:199], v[220:223], v[82:85]
	v_mfma_f32_16x16x32_bf16 v[70:73], v[186:189], v[228:231], v[70:73]
	v_mfma_f32_16x16x32_bf16 v[66:69], v[196:199], v[228:231], v[66:69]
	s_setprio 0
	s_barrier
; #define PG8_STAGE(bufoff, gbase, voff) do { _Pragma("unroll") for (int _i = 0; _i < 2; ++_i) \
;         __builtin_amdgcn_global_load_lds((const unsigned*)((const char*)(gbase) + (voff)[_i]), (PG8_LAS unsigned*)(lds + (bufoff) + ldsw + _i * 8192), 16, 0, 0); } while (0)
; #define PG8_LDA(dst, b, h) do { _Pragma("unroll") for (int m = 0; m < 4; ++m) _Pragma("unroll") for (int k = 0; k < 2; ++k) dst[m][k] = *(const PG8_LAS bf16x8*)(lds + PG8_SA(b, h) + aoff + m * 2048 + k * 1024); } while (0)
; #define PG8_MMA(ai, bj, At, Bt) do { __builtin_amdgcn_s_setprio(1); _Pragma("unroll") for (int m = 0; m < 4; ++m) _Pragma("unroll") for (int n = 0; n < 2; ++n) _Pragma("unroll") for (int k = 0; k < 2; ++k) \
;         acc[ai][bj][m][n] = __builtin_amdgcn_mfma_f32_16x16x32_bf16(Bt[n][k], At[m][k], acc[ai][bj][m][n], 0, 0, 0); __builtin_amdgcn_s_setprio(0); } while (0)
; #define PG8_WAIT_V(n) asm volatile("s_waitcnt vmcnt(" #n ")" ::: "memory")
; #define PG8_WAIT_L(n) asm volatile("s_waitcnt lgkmcnt(" #n ")" ::: "memory")
; #define PG8_BAR __builtin_amdgcn_s_barrier()
; #define PG8_SCHED __builtin_amdgcn_sched_barrier(0)
; template <class Epi, class Sched, bool ALIGN_EPI = false, bool SP2 = false>
; __device__ __forceinline__ void gemm_phase(PG8_LAS unsigned char* lds, const Gemm g, const Sched& S, const Epi& E) {
;     ...
;         for (int t = 0; t < nt; t += 2) {
;             const bool last = (t == nt - 2);
;             const char* a1 = cA + (size_t)(t + 1) * kstep;
;             const char* a2 = last ? nA : cA + (size_t)(t + 2) * kstep; const char* b2 = last ? nB : cB + (size_t)(t + 2) * kstep;
;             const char* a3 = a2 + kstep; const char* b3 = b2 + kstep;
;     ...
;             PG8_LDA(At, 1, 1); PG8_STAGE(PG8_SB(1, 0), b3, voffB); PG8_STAGE(PG8_SB(1, 1), b3 + hstep, voffB); PG8_STAGE(PG8_SA(1, 0), a3, voffA);
;             PG8_WAIT_V(8); PG8_WAIT_L(0); PG8_BAR; PG8_MMA(1, 0, At, B0); PG8_MMA(1, 1, At, B1); PG8_BAR; PG8_SCHED;
	s_add_i32 s38, s56, s3
	v_lshl_add_u64 v[150:151], v[150:151], 0, s[12:13]
	s_mov_b32 m0, s38
	ds_read_b128 v[200:203], v156 offset:49152
	ds_read_b128 v[204:207], v156 offset:50176
	ds_read_b128 v[208:211], v156 offset:51200
	ds_read_b128 v[212:215], v156 offset:52224
	ds_read_b128 v[216:219], v156 offset:53248
	ds_read_b128 v[220:223], v156 offset:54272
	ds_read_b128 v[224:227], v156 offset:55296
	ds_read_b128 v[228:231], v156 offset:56320
	global_load_lds_dwordx4 v[150:151], off
	s_add_i32 m0, s38, 0x2000
	s_add_u32 s36, s36, 0x40080
	v_lshl_add_u64 v[150:151], v[232:233], 0, s[12:13]
	s_addc_u32 s37, s37, 0
	s_add_i32 s38, s57, s3
	global_load_lds_dwordx4 v[150:151], off
	v_lshl_add_u64 v[150:151], s[36:37], 0, v[132:133]
	s_mov_b32 m0, s38
	s_nop 0
	global_load_lds_dwordx4 v[150:151], off
	v_lshl_add_u64 v[150:151], s[36:37], 0, v[136:137]
	s_add_i32 m0, s38, 0x2000
	s_nop 0
	global_load_lds_dwordx4 v[150:151], off
	v_lshl_add_u64 v[150:151], v[234:235], 0, s[12:13]
	s_mov_b32 m0, s45
	s_nop 0
	global_load_lds_dwordx4 v[150:151], off
	v_lshl_add_u64 v[150:151], v[236:237], 0, s[12:13]
	s_mov_b32 m0, s46
	s_nop 0
	global_load_lds_dwordx4 v[150:151], off
	s_waitcnt vmcnt(8)
	s_waitcnt lgkmcnt(0)
	s_barrier
	s_setprio 1
	v_mfma_f32_16x16x32_bf16 v[62:65], v[166:169], v[200:203], v[62:65]
	v_mfma_f32_16x16x32_bf16 v[58:61], v[174:177], v[200:203], v[58:61]
	v_mfma_f32_16x16x32_bf16 v[46:49], v[166:169], v[208:211], v[46:49]
	v_mfma_f32_16x16x32_bf16 v[42:45], v[174:177], v[208:211], v[42:45]
	v_mfma_f32_16x16x32_bf16 v[30:33], v[166:169], v[216:219], v[30:33]
	v_mfma_f32_16x16x32_bf16 v[26:29], v[174:177], v[216:219], v[26:29]
	v_mfma_f32_16x16x32_bf16 v[14:17], v[166:169], v[224:227], v[14:17]
	v_mfma_f32_16x16x32_bf16 v[10:13], v[174:177], v[224:227], v[10:13]
	v_mfma_f32_16x16x32_bf16 v[62:65], v[170:173], v[204:207], v[62:65]
	v_mfma_f32_16x16x32_bf16 v[58:61], v[178:181], v[204:207], v[58:61]
	v_mfma_f32_16x16x32_bf16 v[46:49], v[170:173], v[212:215], v[46:49]
	v_mfma_f32_16x16x32_bf16 v[42:45], v[178:181], v[212:215], v[42:45]
	v_mfma_f32_16x16x32_bf16 v[30:33], v[170:173], v[220:223], v[30:33]
	v_mfma_f32_16x16x32_bf16 v[26:29], v[178:181], v[220:223], v[26:29]
	v_mfma_f32_16x16x32_bf16 v[14:17], v[170:173], v[228:231], v[14:17]
	v_mfma_f32_16x16x32_bf16 v[10:13], v[178:181], v[228:231], v[10:13]
	s_setprio 0
	s_setprio 1
	v_mfma_f32_16x16x32_bf16 v[54:57], v[182:185], v[200:203], v[54:57]
	v_mfma_f32_16x16x32_bf16 v[50:53], v[190:193], v[200:203], v[50:53]
	v_mfma_f32_16x16x32_bf16 v[38:41], v[182:185], v[208:211], v[38:41]
	v_mfma_f32_16x16x32_bf16 v[34:37], v[190:193], v[208:211], v[34:37]
	v_mfma_f32_16x16x32_bf16 v[22:25], v[182:185], v[216:219], v[22:25]
	v_mfma_f32_16x16x32_bf16 v[18:21], v[190:193], v[216:219], v[18:21]
	v_mfma_f32_16x16x32_bf16 v[6:9], v[182:185], v[224:227], v[6:9]
	v_mfma_f32_16x16x32_bf16 v[2:5], v[190:193], v[224:227], v[2:5]
	v_mfma_f32_16x16x32_bf16 v[54:57], v[186:189], v[204:207], v[54:57]
	v_mfma_f32_16x16x32_bf16 v[50:53], v[196:199], v[204:207], v[50:53]
	v_mfma_f32_16x16x32_bf16 v[38:41], v[186:189], v[212:215], v[38:41]
	v_mfma_f32_16x16x32_bf16 v[34:37], v[196:199], v[212:215], v[34:37]
	v_mfma_f32_16x16x32_bf16 v[22:25], v[186:189], v[220:223], v[22:25]
	v_mfma_f32_16x16x32_bf16 v[18:21], v[196:199], v[220:223], v[18:21]
	v_mfma_f32_16x16x32_bf16 v[6:9], v[186:189], v[228:231], v[6:9]
	v_mfma_f32_16x16x32_bf16 v[2:5], v[196:199], v[228:231], v[2:5]
	s_setprio 0
	s_barrier
	s_add_i32 s55, s55, 2
	s_add_u32 s34, s34, 0x100
	s_addc_u32 s35, s35, 0
	s_add_u32 s53, s53, 0x100
	s_addc_u32 s54, s54, 0
	s_cmp_gt_u32 s55, 13
	s_cbranch_scc0 .LBB0_946
	s_and_b64 vcc, exec, s[14:15]
	s_cbranch_vccz .LBB0_949
	s_barrier

; #define PG8_STAGE(bufoff, gbase, voff) do { _Pragma("unroll") for (int _i = 0; _i < 2; ++_i) \
;         __builtin_amdgcn_global_load_lds((const unsigned*)((const char*)(gbase) + (voff)[_i]), (PG8_LAS unsigned*)(lds + (bufoff) + ldsw + _i * 8192), 16, 0, 0); } while (0)
; #define PG8_LDA(dst, b, h) do { _Pragma("unroll") for (int m = 0; m < 4; ++m) _Pragma("unroll") for (int k = 0; k < 2; ++k) dst[m][k] = *(const PG8_LAS bf16x8*)(lds + PG8_SA(b, h) + aoff + m * 2048 + k * 1024); } while (0)
; #define PG8_LDB(dst, b, h) do { _Pragma("unroll") for (int n = 0; n < 2; ++n) _Pragma("unroll") for (int k = 0; k < 2; ++k) dst[n][k] = *(const PG8_LAS bf16x8*)(lds + PG8_SB(b, h) + boff + n * 2048 + k * 1024); } while (0)
; #define PG8_MMA(ai, bj, At, Bt) do { __builtin_amdgcn_s_setprio(1); _Pragma("unroll") for (int m = 0; m < 4; ++m) _Pragma("unroll") for (int n = 0; n < 2; ++n) _Pragma("unroll") for (int k = 0; k < 2; ++k) \
;         acc[ai][bj][m][n] = __builtin_amdgcn_mfma_f32_16x16x32_bf16(Bt[n][k], At[m][k], acc[ai][bj][m][n], 0, 0, 0); __builtin_amdgcn_s_setprio(0); } while (0)
; #define PG8_WAIT_V(n) asm volatile("s_waitcnt vmcnt(" #n ")" ::: "memory")
; #define PG8_BAR __builtin_amdgcn_s_barrier()
; template <class Epi, class Sched, bool ALIGN_EPI = false, bool SP2 = false>
; __device__ __forceinline__ void gemm_phase(PG8_LAS unsigned char* lds, const Gemm g, const Sched& S, const Epi& E) {
;     ...
;         for (int t = 0; t < nt; t += 2) {
;             const bool last = (t == nt - 2);
;             const char* a1 = cA + (size_t)(t + 1) * kstep;
;             const char* a2 = last ? nA : cA + (size_t)(t + 2) * kstep; const char* b2 = last ? nB : cB + (size_t)(t + 2) * kstep;
;             const char* a3 = a2 + kstep; const char* b3 = b2 + kstep;
;             if (last && has_next) S.a_ready(nxt);
;             if constexpr (SP2) {
;             PG8_LDB(B0, 0, 0); PG8_LDB(B1, 0, 1); PG8_SCHED; PG8_LDA(At, 0, 0); PG8_STAGE(PG8_SA(1, 1), a1 + hstep, voffA);
;             PG8_WAIT_V(8); PG8_WAIT_L(0); PG8_BAR; PG8_MMA(0, 0, At, B0); PG8_MMA(0, 1, At, B1); PG8_BAR; PG8_SCHED;
;             PG8_LDA(At, 0, 1); PG8_STAGE(PG8_SB(0, 0), b2, voffB); PG8_STAGE(PG8_SB(0, 1), b2 + hstep, voffB); PG8_STAGE(PG8_SA(0, 0), a2, voffA);
;             PG8_WAIT_V(8); PG8_WAIT_L(0); PG8_BAR; PG8_MMA(1, 0, At, B0); PG8_MMA(1, 1, At, B1); PG8_BAR; PG8_SCHED;
.LBB0_1038:
	ds_read_b128 v[146:149], v152
	ds_read_b128 v[156:159], v152 offset:1024
	ds_read_b128 v[160:163], v152 offset:2048
	ds_read_b128 v[164:167], v152 offset:3072
	ds_read_b128 v[168:171], v153
	ds_read_b128 v[172:175], v153 offset:1024
	ds_read_b128 v[176:179], v153 offset:2048
	ds_read_b128 v[180:183], v153 offset:3072
	s_add_u32 s56, s40, 0xfff80080
	s_addc_u32 s57, s41, -1
	s_cmp_eq_u32 s55, 28
	s_cselect_b32 s59, s21, s57
	s_cselect_b32 s58, s37, s56
	s_cselect_b32 s57, s19, s54
	s_cselect_b32 s56, s52, s53
	v_lshl_add_u64 v[192:193], s[40:41], 0, v[138:139]
	s_add_i32 m0, s3, 0xc000
	ds_read_b128 v[184:187], v154
	ds_read_b128 v[188:191], v154 offset:1024
	ds_read_b128 v[196:199], v154 offset:2048
	ds_read_b128 v[200:203], v154 offset:3072
	ds_read_b128 v[204:207], v154 offset:4096
	ds_read_b128 v[208:211], v154 offset:5120
	ds_read_b128 v[212:215], v154 offset:6144
	ds_read_b128 v[216:219], v154 offset:7168
	global_load_lds_dwordx4 v[192:193], off
	v_lshl_add_u64 v[192:193], s[40:41], 0, v[140:141]
	s_add_i32 m0, s3, 0xe000
	s_nop 0
	global_load_lds_dwordx4 v[192:193], off
	s_waitcnt vmcnt(8)
	s_waitcnt lgkmcnt(0)
	s_barrier
	s_setprio 1
	v_mfma_f32_16x16x32_bf16 v[126:129], v[146:149], v[184:187], v[126:129]
	v_mfma_f32_16x16x32_bf16 v[122:125], v[160:163], v[184:187], v[122:125]
	v_mfma_f32_16x16x32_bf16 v[110:113], v[146:149], v[196:199], v[110:113]
	v_mfma_f32_16x16x32_bf16 v[106:109], v[160:163], v[196:199], v[106:109]
	v_mfma_f32_16x16x32_bf16 v[94:97], v[146:149], v[204:207], v[94:97]
	v_mfma_f32_16x16x32_bf16 v[90:93], v[160:163], v[204:207], v[90:93]
	v_mfma_f32_16x16x32_bf16 v[78:81], v[146:149], v[212:215], v[78:81]
	v_mfma_f32_16x16x32_bf16 v[74:77], v[160:163], v[212:215], v[74:77]
	v_mfma_f32_16x16x32_bf16 v[126:129], v[156:159], v[188:191], v[126:129]
	v_mfma_f32_16x16x32_bf16 v[122:125], v[164:167], v[188:191], v[122:125]
	v_mfma_f32_16x16x32_bf16 v[110:113], v[156:159], v[200:203], v[110:113]
	v_mfma_f32_16x16x32_bf16 v[106:109], v[164:167], v[200:203], v[106:109]
	v_mfma_f32_16x16x32_bf16 v[94:97], v[156:159], v[208:211], v[94:97]
	v_mfma_f32_16x16x32_bf16 v[90:93], v[164:167], v[208:211], v[90:93]
	v_mfma_f32_16x16x32_bf16 v[78:81], v[156:159], v[216:219], v[78:81]
	v_mfma_f32_16x16x32_bf16 v[74:77], v[164:167], v[216:219], v[74:77]
	s_setprio 0
	s_setprio 1
	v_mfma_f32_16x16x32_bf16 v[118:121], v[168:171], v[184:187], v[118:121]
	v_mfma_f32_16x16x32_bf16 v[114:117], v[176:179], v[184:187], v[114:117]
	v_mfma_f32_16x16x32_bf16 v[102:105], v[168:171], v[196:199], v[102:105]
	v_mfma_f32_16x16x32_bf16 v[98:101], v[176:179], v[196:199], v[98:101]
	v_mfma_f32_16x16x32_bf16 v[86:89], v[168:171], v[204:207], v[86:89]
	v_mfma_f32_16x16x32_bf16 v[82:85], v[176:179], v[204:207], v[82:85]
	v_mfma_f32_16x16x32_bf16 v[70:73], v[168:171], v[212:215], v[70:73]
	v_mfma_f32_16x16x32_bf16 v[66:69], v[176:179], v[212:215], v[66:69]
	v_mfma_f32_16x16x32_bf16 v[118:121], v[172:175], v[188:191], v[118:121]
	v_mfma_f32_16x16x32_bf16 v[114:117], v[180:183], v[188:191], v[114:117]
	v_mfma_f32_16x16x32_bf16 v[102:105], v[172:175], v[200:203], v[102:105]
	v_mfma_f32_16x16x32_bf16 v[98:101], v[180:183], v[200:203], v[98:101]
	v_mfma_f32_16x16x32_bf16 v[86:89], v[172:175], v[208:211], v[86:89]
	v_mfma_f32_16x16x32_bf16 v[82:85], v[180:183], v[208:211], v[82:85]
	v_mfma_f32_16x16x32_bf16 v[70:73], v[172:175], v[216:219], v[70:73]
	v_mfma_f32_16x16x32_bf16 v[66:69], v[180:183], v[216:219], v[66:69]
	s_setprio 0
	s_barrier
	s_add_i32 s60, s49, s2
	v_lshl_add_u64 v[192:193], s[56:57], 0, v[132:133]
	s_mov_b32 m0, s60
	ds_read_b128 v[184:187], v154 offset:16384
	ds_read_b128 v[188:191], v154 offset:17408
	ds_read_b128 v[196:199], v154 offset:18432
	ds_read_b128 v[200:203], v154 offset:19456
	ds_read_b128 v[204:207], v154 offset:20480
	ds_read_b128 v[208:211], v154 offset:21504
	ds_read_b128 v[212:215], v154 offset:22528
	ds_read_b128 v[216:219], v154 offset:23552
	global_load_lds_dwordx4 v[192:193], off
	s_add_i32 m0, s60, 0x2000
	s_add_u32 s60, s56, 0x80000
	v_lshl_add_u64 v[220:221], s[56:57], 0, v[136:137]
	s_addc_u32 s61, s57, 0
	s_add_i32 s62, s50, s2
	global_load_lds_dwordx4 v[220:221], off
	v_lshl_add_u64 v[222:223], s[60:61], 0, v[132:133]
	s_mov_b32 m0, s62
	v_lshl_add_u64 v[224:225], s[58:59], 0, v[134:135]
	global_load_lds_dwordx4 v[222:223], off
	v_lshl_add_u64 v[222:223], s[60:61], 0, v[136:137]
	s_add_i32 m0, s62, 0x2000
	s_nop 0
	global_load_lds_dwordx4 v[222:223], off
	v_lshl_add_u64 v[222:223], s[58:59], 0, v[130:131]
	s_mov_b32 m0, s3
	s_nop 0
	global_load_lds_dwordx4 v[222:223], off
	s_mov_b32 m0, s39
	s_nop 0
	global_load_lds_dwordx4 v[224:225], off
	s_waitcnt vmcnt(8)
	s_waitcnt lgkmcnt(0)
	s_barrier
; #define PG8_STAGE(bufoff, gbase, voff) do { _Pragma("unroll") for (int _i = 0; _i < 2; ++_i) \
;         __builtin_amdgcn_global_load_lds((const unsigned*)((const char*)(gbase) + (voff)[_i]), (PG8_LAS unsigned*)(lds + (bufoff) + ldsw + _i * 8192), 16, 0, 0); } while (0)
; #define PG8_LDA(dst, b, h) do { _Pragma("unroll") for (int m = 0; m < 4; ++m) _Pragma("unroll") for (int k = 0; k < 2; ++k) dst[m][k] = *(const PG8_LAS bf16x8*)(lds + PG8_SA(b, h) + aoff + m * 2048 + k * 1024); } while (0)
; #define PG8_LDB(dst, b, h) do { _Pragma("unroll") for (int n = 0; n < 2; ++n) _Pragma("unroll") for (int k = 0; k < 2; ++k) dst[n][k] = *(const PG8_LAS bf16x8*)(lds + PG8_SB(b, h) + boff + n * 2048 + k * 1024); } while (0)
; #define PG8_MMA(ai, bj, At, Bt) do { __builtin_amdgcn_s_setprio(1); _Pragma("unroll") for (int m = 0; m < 4; ++m) _Pragma("unroll") for (int n = 0; n < 2; ++n) _Pragma("unroll") for (int k = 0; k < 2; ++k) \
;         acc[ai][bj][m][n] = __builtin_amdgcn_mfma_f32_16x16x32_bf16(Bt[n][k], At[m][k], acc[ai][bj][m][n], 0, 0, 0); __builtin_amdgcn_s_setprio(0); } while (0)
; #define PG8_WAIT_V(n) asm volatile("s_waitcnt vmcnt(" #n ")" ::: "memory")
; #define PG8_WAIT_L(n) asm volatile("s_waitcnt lgkmcnt(" #n ")" ::: "memory")
; #define PG8_BAR __builtin_amdgcn_s_barrier()
; #define PG8_SCHED __builtin_amdgcn_sched_barrier(0)
; template <class Epi, class Sched, bool ALIGN_EPI = false, bool SP2 = false>
; __device__ __forceinline__ void gemm_phase(PG8_LAS unsigned char* lds, const Gemm g, const Sched& S, const Epi& E) {
;     ...
;             PG8_WAIT_V(8); PG8_WAIT_L(0); PG8_BAR; PG8_MMA(1, 0, At, B0); PG8_MMA(1, 1, At, B1); PG8_BAR; PG8_SCHED;
;             PG8_LDB(B0, 1, 0); PG8_LDB(B1, 1, 1); PG8_SCHED; PG8_LDA(At, 1, 0); PG8_STAGE(PG8_SA(0, 1), a2 + hstep, voffA);
;             PG8_WAIT_V(8); PG8_WAIT_L(0); PG8_BAR; PG8_MMA(0, 0, At, B0); PG8_MMA(0, 1, At, B1); PG8_BAR; PG8_SCHED;
	s_setprio 1
	v_mfma_f32_16x16x32_bf16 v[62:65], v[146:149], v[184:187], v[62:65]
	v_mfma_f32_16x16x32_bf16 v[58:61], v[160:163], v[184:187], v[58:61]
	v_mfma_f32_16x16x32_bf16 v[46:49], v[146:149], v[196:199], v[46:49]
	v_mfma_f32_16x16x32_bf16 v[42:45], v[160:163], v[196:199], v[42:45]
	v_mfma_f32_16x16x32_bf16 v[30:33], v[146:149], v[204:207], v[30:33]
	v_mfma_f32_16x16x32_bf16 v[26:29], v[160:163], v[204:207], v[26:29]
	v_mfma_f32_16x16x32_bf16 v[14:17], v[146:149], v[212:215], v[14:17]
	v_mfma_f32_16x16x32_bf16 v[10:13], v[160:163], v[212:215], v[10:13]
	v_mfma_f32_16x16x32_bf16 v[62:65], v[156:159], v[188:191], v[62:65]
	v_mfma_f32_16x16x32_bf16 v[58:61], v[164:167], v[188:191], v[58:61]
	v_mfma_f32_16x16x32_bf16 v[46:49], v[156:159], v[200:203], v[46:49]
	v_mfma_f32_16x16x32_bf16 v[42:45], v[164:167], v[200:203], v[42:45]
	v_mfma_f32_16x16x32_bf16 v[30:33], v[156:159], v[208:211], v[30:33]
	v_mfma_f32_16x16x32_bf16 v[26:29], v[164:167], v[208:211], v[26:29]
	v_mfma_f32_16x16x32_bf16 v[14:17], v[156:159], v[216:219], v[14:17]
	v_mfma_f32_16x16x32_bf16 v[10:13], v[164:167], v[216:219], v[10:13]
	s_setprio 0
	s_setprio 1
	v_mfma_f32_16x16x32_bf16 v[54:57], v[168:171], v[184:187], v[54:57]
	v_mfma_f32_16x16x32_bf16 v[50:53], v[176:179], v[184:187], v[50:53]
	v_mfma_f32_16x16x32_bf16 v[38:41], v[168:171], v[196:199], v[38:41]
	v_mfma_f32_16x16x32_bf16 v[34:37], v[176:179], v[196:199], v[34:37]
	v_mfma_f32_16x16x32_bf16 v[22:25], v[168:171], v[204:207], v[22:25]
	v_mfma_f32_16x16x32_bf16 v[18:21], v[176:179], v[204:207], v[18:21]
	v_mfma_f32_16x16x32_bf16 v[6:9], v[168:171], v[212:215], v[6:9]
	v_mfma_f32_16x16x32_bf16 v[2:5], v[176:179], v[212:215], v[2:5]
	v_mfma_f32_16x16x32_bf16 v[54:57], v[172:175], v[188:191], v[54:57]
	v_mfma_f32_16x16x32_bf16 v[50:53], v[180:183], v[188:191], v[50:53]
	v_mfma_f32_16x16x32_bf16 v[38:41], v[172:175], v[200:203], v[38:41]
	v_mfma_f32_16x16x32_bf16 v[34:37], v[180:183], v[200:203], v[34:37]
	v_mfma_f32_16x16x32_bf16 v[22:25], v[172:175], v[208:211], v[22:25]
	v_mfma_f32_16x16x32_bf16 v[18:21], v[180:183], v[208:211], v[18:21]
	v_mfma_f32_16x16x32_bf16 v[6:9], v[172:175], v[216:219], v[6:9]
	v_mfma_f32_16x16x32_bf16 v[2:5], v[180:183], v[216:219], v[2:5]
	s_setprio 0
	s_barrier
	s_add_i32 s60, 0, 0x18000
	s_add_i32 s61, 0, 0x1c000
	v_add_u32_e32 v164, s60, v150
	v_add_u32_e32 v180, s61, v150
	ds_read_b128 v[146:149], v164
	ds_read_b128 v[156:159], v164 offset:1024
	ds_read_b128 v[160:163], v164 offset:2048
	ds_read_b128 v[164:167], v164 offset:3072
	ds_read_b128 v[168:171], v180
	ds_read_b128 v[172:175], v180 offset:1024
	ds_read_b128 v[176:179], v180 offset:2048
	ds_read_b128 v[180:183], v180 offset:3072
	s_add_u32 s58, s58, 0x80000
	s_addc_u32 s59, s59, 0
	s_mov_b32 m0, s42
	v_lshl_add_u64 v[226:227], s[58:59], 0, v[130:131]
	ds_read_b128 v[184:187], v154 offset:32768
	ds_read_b128 v[188:191], v154 offset:33792
	ds_read_b128 v[196:199], v154 offset:34816
	ds_read_b128 v[200:203], v154 offset:35840
	ds_read_b128 v[204:207], v154 offset:36864
	ds_read_b128 v[208:211], v154 offset:37888
	ds_read_b128 v[212:215], v154 offset:38912
	ds_read_b128 v[216:219], v154 offset:39936
	global_load_lds_dwordx4 v[226:227], off
	v_lshl_add_u64 v[226:227], s[58:59], 0, v[134:135]
	s_mov_b32 m0, s43
	s_nop 0
	global_load_lds_dwordx4 v[226:227], off
	s_waitcnt vmcnt(8)
	s_waitcnt lgkmcnt(0)
	s_barrier
	s_setprio 1
	v_mfma_f32_16x16x32_bf16 v[126:129], v[146:149], v[184:187], v[126:129]
	v_mfma_f32_16x16x32_bf16 v[122:125], v[160:163], v[184:187], v[122:125]
	v_mfma_f32_16x16x32_bf16 v[110:113], v[146:149], v[196:199], v[110:113]
	v_mfma_f32_16x16x32_bf16 v[106:109], v[160:163], v[196:199], v[106:109]
	v_mfma_f32_16x16x32_bf16 v[94:97], v[146:149], v[204:207], v[94:97]
	v_mfma_f32_16x16x32_bf16 v[90:93], v[160:163], v[204:207], v[90:93]
	v_mfma_f32_16x16x32_bf16 v[78:81], v[146:149], v[212:215], v[78:81]
	v_mfma_f32_16x16x32_bf16 v[74:77], v[160:163], v[212:215], v[74:77]
	v_mfma_f32_16x16x32_bf16 v[126:129], v[156:159], v[188:191], v[126:129]
	v_mfma_f32_16x16x32_bf16 v[122:125], v[164:167], v[188:191], v[122:125]
	v_mfma_f32_16x16x32_bf16 v[110:113], v[156:159], v[200:203], v[110:113]
	v_mfma_f32_16x16x32_bf16 v[106:109], v[164:167], v[200:203], v[106:109]
	v_mfma_f32_16x16x32_bf16 v[94:97], v[156:159], v[208:211], v[94:97]
	v_mfma_f32_16x16x32_bf16 v[90:93], v[164:167], v[208:211], v[90:93]
	v_mfma_f32_16x16x32_bf16 v[78:81], v[156:159], v[216:219], v[78:81]
	v_mfma_f32_16x16x32_bf16 v[74:77], v[164:167], v[216:219], v[74:77]
	s_setprio 0
	s_setprio 1
	v_mfma_f32_16x16x32_bf16 v[118:121], v[168:171], v[184:187], v[118:121]
	v_mfma_f32_16x16x32_bf16 v[114:117], v[176:179], v[184:187], v[114:117]
	v_mfma_f32_16x16x32_bf16 v[102:105], v[168:171], v[196:199], v[102:105]
	v_mfma_f32_16x16x32_bf16 v[98:101], v[176:179], v[196:199], v[98:101]
	v_mfma_f32_16x16x32_bf16 v[86:89], v[168:171], v[204:207], v[86:89]
	v_mfma_f32_16x16x32_bf16 v[82:85], v[176:179], v[204:207], v[82:85]
	v_mfma_f32_16x16x32_bf16 v[70:73], v[168:171], v[212:215], v[70:73]
	v_mfma_f32_16x16x32_bf16 v[66:69], v[176:179], v[212:215], v[66:69]
	v_mfma_f32_16x16x32_bf16 v[118:121], v[172:175], v[188:191], v[118:121]
	v_mfma_f32_16x16x32_bf16 v[114:117], v[180:183], v[188:191], v[114:117]
	v_mfma_f32_16x16x32_bf16 v[102:105], v[172:175], v[200:203], v[102:105]
	v_mfma_f32_16x16x32_bf16 v[98:101], v[180:183], v[200:203], v[98:101]
	v_mfma_f32_16x16x32_bf16 v[86:89], v[172:175], v[208:211], v[86:89]
	v_mfma_f32_16x16x32_bf16 v[82:85], v[180:183], v[208:211], v[82:85]
	v_mfma_f32_16x16x32_bf16 v[70:73], v[172:175], v[216:219], v[70:73]
	v_mfma_f32_16x16x32_bf16 v[66:69], v[180:183], v[216:219], v[66:69]
	s_setprio 0
	s_barrier
; #define PG8_STAGE(bufoff, gbase, voff) do { _Pragma("unroll") for (int _i = 0; _i < 2; ++_i) \
;         __builtin_amdgcn_global_load_lds((const unsigned*)((const char*)(gbase) + (voff)[_i]), (PG8_LAS unsigned*)(lds + (bufoff) + ldsw + _i * 8192), 16, 0, 0); } while (0)
; #define PG8_LDA(dst, b, h) do { _Pragma("unroll") for (int m = 0; m < 4; ++m) _Pragma("unroll") for (int k = 0; k < 2; ++k) dst[m][k] = *(const PG8_LAS bf16x8*)(lds + PG8_SA(b, h) + aoff + m * 2048 + k * 1024); } while (0)
; #define PG8_MMA(ai, bj, At, Bt) do { __builtin_amdgcn_s_setprio(1); _Pragma("unroll") for (int m = 0; m < 4; ++m) _Pragma("unroll") for (int n = 0; n < 2; ++n) _Pragma("unroll") for (int k = 0; k < 2; ++k) \
;         acc[ai][bj][m][n] = __builtin_amdgcn_mfma_f32_16x16x32_bf16(Bt[n][k], At[m][k], acc[ai][bj][m][n], 0, 0, 0); __builtin_amdgcn_s_setprio(0); } while (0)
; #define PG8_WAIT_V(n) asm volatile("s_waitcnt vmcnt(" #n ")" ::: "memory")
; #define PG8_WAIT_L(n) asm volatile("s_waitcnt lgkmcnt(" #n ")" ::: "memory")
; #define PG8_BAR __builtin_amdgcn_s_barrier()
; #define PG8_SCHED __builtin_amdgcn_sched_barrier(0)
; template <class Epi, class Sched, bool ALIGN_EPI = false, bool SP2 = false>
; __device__ __forceinline__ void gemm_phase(PG8_LAS unsigned char* lds, const Gemm g, const Sched& S, const Epi& E) {
;     ...
;         for (int t = 0; t < nt; t += 2) {
;             const bool last = (t == nt - 2);
;             const char* a1 = cA + (size_t)(t + 1) * kstep;
;             const char* a2 = last ? nA : cA + (size_t)(t + 2) * kstep; const char* b2 = last ? nB : cB + (size_t)(t + 2) * kstep;
;             const char* a3 = a2 + kstep; const char* b3 = b2 + kstep;
;     ...
;             PG8_LDA(At, 1, 1); PG8_STAGE(PG8_SB(1, 0), b3, voffB); PG8_STAGE(PG8_SB(1, 1), b3 + hstep, voffB); PG8_STAGE(PG8_SA(1, 0), a3, voffA);
;             PG8_WAIT_V(8); PG8_WAIT_L(0); PG8_BAR; PG8_MMA(1, 0, At, B0); PG8_MMA(1, 1, At, B1); PG8_BAR; PG8_SCHED;
	s_add_i32 s58, s60, s2
	v_lshl_add_u64 v[192:193], v[192:193], 0, s[14:15]
	s_mov_b32 m0, s58
	ds_read_b128 v[184:187], v154 offset:49152
	ds_read_b128 v[188:191], v154 offset:50176
	ds_read_b128 v[196:199], v154 offset:51200
	ds_read_b128 v[200:203], v154 offset:52224
	ds_read_b128 v[204:207], v154 offset:53248
	ds_read_b128 v[208:211], v154 offset:54272
	ds_read_b128 v[212:215], v154 offset:55296
	ds_read_b128 v[216:219], v154 offset:56320
	global_load_lds_dwordx4 v[192:193], off
	s_add_i32 m0, s58, 0x2000
	s_add_u32 s56, s56, 0x80080
	v_lshl_add_u64 v[192:193], v[220:221], 0, s[14:15]
	s_addc_u32 s57, s57, 0
	s_add_i32 s58, s61, s2
	global_load_lds_dwordx4 v[192:193], off
	v_lshl_add_u64 v[192:193], s[56:57], 0, v[132:133]
	s_mov_b32 m0, s58
	s_nop 0
	global_load_lds_dwordx4 v[192:193], off
	v_lshl_add_u64 v[192:193], s[56:57], 0, v[136:137]
	s_add_i32 m0, s58, 0x2000
	s_nop 0
	global_load_lds_dwordx4 v[192:193], off
	v_lshl_add_u64 v[192:193], v[222:223], 0, s[14:15]
	s_mov_b32 m0, s45
	s_nop 0
	global_load_lds_dwordx4 v[192:193], off
	v_lshl_add_u64 v[192:193], v[224:225], 0, s[14:15]
	s_mov_b32 m0, s46
	s_nop 0
	global_load_lds_dwordx4 v[192:193], off
	s_waitcnt vmcnt(8)
	s_waitcnt lgkmcnt(0)
	s_barrier
	s_setprio 1
	v_mfma_f32_16x16x32_bf16 v[62:65], v[146:149], v[184:187], v[62:65]
	v_mfma_f32_16x16x32_bf16 v[58:61], v[160:163], v[184:187], v[58:61]
	v_mfma_f32_16x16x32_bf16 v[46:49], v[146:149], v[196:199], v[46:49]
	v_mfma_f32_16x16x32_bf16 v[42:45], v[160:163], v[196:199], v[42:45]
	v_mfma_f32_16x16x32_bf16 v[30:33], v[146:149], v[204:207], v[30:33]
	v_mfma_f32_16x16x32_bf16 v[26:29], v[160:163], v[204:207], v[26:29]
	v_mfma_f32_16x16x32_bf16 v[14:17], v[146:149], v[212:215], v[14:17]
	v_mfma_f32_16x16x32_bf16 v[10:13], v[160:163], v[212:215], v[10:13]
	v_mfma_f32_16x16x32_bf16 v[62:65], v[156:159], v[188:191], v[62:65]
	v_mfma_f32_16x16x32_bf16 v[58:61], v[164:167], v[188:191], v[58:61]
	v_mfma_f32_16x16x32_bf16 v[46:49], v[156:159], v[200:203], v[46:49]
	v_mfma_f32_16x16x32_bf16 v[42:45], v[164:167], v[200:203], v[42:45]
	v_mfma_f32_16x16x32_bf16 v[30:33], v[156:159], v[208:211], v[30:33]
	v_mfma_f32_16x16x32_bf16 v[26:29], v[164:167], v[208:211], v[26:29]
	v_mfma_f32_16x16x32_bf16 v[14:17], v[156:159], v[216:219], v[14:17]
	v_mfma_f32_16x16x32_bf16 v[10:13], v[164:167], v[216:219], v[10:13]
	s_setprio 0
	s_setprio 1
	v_mfma_f32_16x16x32_bf16 v[54:57], v[168:171], v[184:187], v[54:57]
	v_mfma_f32_16x16x32_bf16 v[50:53], v[176:179], v[184:187], v[50:53]
	v_mfma_f32_16x16x32_bf16 v[38:41], v[168:171], v[196:199], v[38:41]
	v_mfma_f32_16x16x32_bf16 v[34:37], v[176:179], v[196:199], v[34:37]
	v_mfma_f32_16x16x32_bf16 v[22:25], v[168:171], v[204:207], v[22:25]
	v_mfma_f32_16x16x32_bf16 v[18:21], v[176:179], v[204:207], v[18:21]
	v_mfma_f32_16x16x32_bf16 v[6:9], v[168:171], v[212:215], v[6:9]
	v_mfma_f32_16x16x32_bf16 v[2:5], v[176:179], v[212:215], v[2:5]
	v_mfma_f32_16x16x32_bf16 v[54:57], v[172:175], v[188:191], v[54:57]
	v_mfma_f32_16x16x32_bf16 v[50:53], v[180:183], v[188:191], v[50:53]
	v_mfma_f32_16x16x32_bf16 v[38:41], v[172:175], v[200:203], v[38:41]
	v_mfma_f32_16x16x32_bf16 v[34:37], v[180:183], v[200:203], v[34:37]
	v_mfma_f32_16x16x32_bf16 v[22:25], v[172:175], v[208:211], v[22:25]
	v_mfma_f32_16x16x32_bf16 v[18:21], v[180:183], v[208:211], v[18:21]
	v_mfma_f32_16x16x32_bf16 v[6:9], v[172:175], v[216:219], v[6:9]
	v_mfma_f32_16x16x32_bf16 v[2:5], v[180:183], v[216:219], v[2:5]
	s_setprio 0
	s_barrier
	s_add_i32 s55, s55, 2
	s_add_u32 s40, s40, 0x100
	s_addc_u32 s41, s41, 0
	s_add_u32 s53, s53, 0x100
	s_addc_u32 s54, s54, 0
	s_cmp_gt_u32 s55, 29
	s_cbranch_scc0 .LBB0_1038
	s_and_b64 vcc, exec, s[16:17]
	s_cbranch_vccz .LBB0_1041
	s_barrier

; #define PG8_STAGE(bufoff, gbase, voff) do { _Pragma("unroll") for (int _i = 0; _i < 2; ++_i) \
;         __builtin_amdgcn_global_load_lds((const unsigned*)((const char*)(gbase) + (voff)[_i]), (PG8_LAS unsigned*)(lds + (bufoff) + ldsw + _i * 8192), 16, 0, 0); } while (0)
; #define PG8_LDA(dst, b, h) do { _Pragma("unroll") for (int m = 0; m < 4; ++m) _Pragma("unroll") for (int k = 0; k < 2; ++k) dst[m][k] = *(const PG8_LAS bf16x8*)(lds + PG8_SA(b, h) + aoff + m * 2048 + k * 1024); } while (0)
; #define PG8_LDB(dst, b, h) do { _Pragma("unroll") for (int n = 0; n < 2; ++n) _Pragma("unroll") for (int k = 0; k < 2; ++k) dst[n][k] = *(const PG8_LAS bf16x8*)(lds + PG8_SB(b, h) + boff + n * 2048 + k * 1024); } while (0)
; #define PG8_MMA(ai, bj, At, Bt) do { __builtin_amdgcn_s_setprio(1); _Pragma("unroll") for (int m = 0; m < 4; ++m) _Pragma("unroll") for (int n = 0; n < 2; ++n) _Pragma("unroll") for (int k = 0; k < 2; ++k) \
;         acc[ai][bj][m][n] = __builtin_amdgcn_mfma_f32_16x16x32_bf16(Bt[n][k], At[m][k], acc[ai][bj][m][n], 0, 0, 0); __builtin_amdgcn_s_setprio(0); } while (0)
; #define PG8_WAIT_V(n) asm volatile("s_waitcnt vmcnt(" #n ")" ::: "memory")
; #define PG8_BAR __builtin_amdgcn_s_barrier()
; template <class Epi, class Sched, bool ALIGN_EPI = false, bool SP2 = false>
; __device__ __forceinline__ void gemm_phase(PG8_LAS unsigned char* lds, const Gemm g, const Sched& S, const Epi& E) {
;     ...
;         for (int t = 0; t < nt; t += 2) {
;             const bool last = (t == nt - 2);
;             const char* a1 = cA + (size_t)(t + 1) * kstep;
;             const char* a2 = last ? nA : cA + (size_t)(t + 2) * kstep; const char* b2 = last ? nB : cB + (size_t)(t + 2) * kstep;
;             const char* a3 = a2 + kstep; const char* b3 = b2 + kstep;
;             if (last && has_next) S.a_ready(nxt);
;             if constexpr (SP2) {
;             PG8_LDB(B0, 0, 0); PG8_LDB(B1, 0, 1); PG8_SCHED; PG8_LDA(At, 0, 0); PG8_STAGE(PG8_SA(1, 1), a1 + hstep, voffA);
;             PG8_WAIT_V(8); PG8_WAIT_L(0); PG8_BAR; PG8_MMA(0, 0, At, B0); PG8_MMA(0, 1, At, B1); PG8_BAR; PG8_SCHED;
;             PG8_LDA(At, 0, 1); PG8_STAGE(PG8_SB(0, 0), b2, voffB); PG8_STAGE(PG8_SB(0, 1), b2 + hstep, voffB); PG8_STAGE(PG8_SA(0, 0), a2, voffA);
;             PG8_WAIT_V(8); PG8_WAIT_L(0); PG8_BAR; PG8_MMA(1, 0, At, B0); PG8_MMA(1, 1, At, B1); PG8_BAR; PG8_SCHED;
.LBB0_1406:
	ds_read_b128 v[164:167], v154
	ds_read_b128 v[168:171], v154 offset:1024
	ds_read_b128 v[172:175], v154 offset:2048
	ds_read_b128 v[176:179], v154 offset:3072
	ds_read_b128 v[180:183], v155
	ds_read_b128 v[184:187], v155 offset:1024
	ds_read_b128 v[188:191], v155 offset:2048
	ds_read_b128 v[196:199], v155 offset:3072
	s_add_u32 s36, s34, 0xfffc0080
	s_addc_u32 s37, s35, -1
	s_cmp_eq_u32 s56, 12
	s_cselect_b32 s39, s19, s37
	s_cselect_b32 s38, s52, s36
	s_cselect_b32 s37, s17, s55
	s_cselect_b32 s36, s53, s54
	v_lshl_add_u64 v[150:151], s[34:35], 0, v[138:139]
	s_add_i32 m0, s40, 0xc000
	ds_read_b128 v[200:203], v156
	ds_read_b128 v[204:207], v156 offset:1024
	ds_read_b128 v[208:211], v156 offset:2048
	ds_read_b128 v[212:215], v156 offset:3072
	ds_read_b128 v[216:219], v156 offset:4096
	ds_read_b128 v[220:223], v156 offset:5120
	ds_read_b128 v[224:227], v156 offset:6144
	ds_read_b128 v[228:231], v156 offset:7168
	global_load_lds_dwordx4 v[150:151], off
	v_lshl_add_u64 v[150:151], s[34:35], 0, v[140:141]
	s_add_i32 m0, s40, 0xe000
	s_nop 0
	global_load_lds_dwordx4 v[150:151], off
	s_waitcnt vmcnt(8)
	s_waitcnt lgkmcnt(0)
	s_barrier
	s_setprio 1
	v_mfma_f32_16x16x32_bf16 v[126:129], v[164:167], v[200:203], v[126:129]
	v_mfma_f32_16x16x32_bf16 v[122:125], v[172:175], v[200:203], v[122:125]
	v_mfma_f32_16x16x32_bf16 v[114:117], v[164:167], v[208:211], v[114:117]
	v_mfma_f32_16x16x32_bf16 v[106:109], v[172:175], v[208:211], v[106:109]
	v_mfma_f32_16x16x32_bf16 v[98:101], v[164:167], v[216:219], v[98:101]
	v_mfma_f32_16x16x32_bf16 v[90:93], v[172:175], v[216:219], v[90:93]
	v_mfma_f32_16x16x32_bf16 v[82:85], v[164:167], v[224:227], v[82:85]
	v_mfma_f32_16x16x32_bf16 v[74:77], v[172:175], v[224:227], v[74:77]
	v_mfma_f32_16x16x32_bf16 v[126:129], v[168:171], v[204:207], v[126:129]
	v_mfma_f32_16x16x32_bf16 v[122:125], v[176:179], v[204:207], v[122:125]
	v_mfma_f32_16x16x32_bf16 v[114:117], v[168:171], v[212:215], v[114:117]
	v_mfma_f32_16x16x32_bf16 v[106:109], v[176:179], v[212:215], v[106:109]
	v_mfma_f32_16x16x32_bf16 v[98:101], v[168:171], v[220:223], v[98:101]
	v_mfma_f32_16x16x32_bf16 v[90:93], v[176:179], v[220:223], v[90:93]
	v_mfma_f32_16x16x32_bf16 v[82:85], v[168:171], v[228:231], v[82:85]
	v_mfma_f32_16x16x32_bf16 v[74:77], v[176:179], v[228:231], v[74:77]
	s_setprio 0
	s_setprio 1
	v_mfma_f32_16x16x32_bf16 v[118:121], v[180:183], v[200:203], v[118:121]
	v_mfma_f32_16x16x32_bf16 v[110:113], v[188:191], v[200:203], v[110:113]
	v_mfma_f32_16x16x32_bf16 v[102:105], v[180:183], v[208:211], v[102:105]
	v_mfma_f32_16x16x32_bf16 v[94:97], v[188:191], v[208:211], v[94:97]
	v_mfma_f32_16x16x32_bf16 v[86:89], v[180:183], v[216:219], v[86:89]
	v_mfma_f32_16x16x32_bf16 v[78:81], v[188:191], v[216:219], v[78:81]
	v_mfma_f32_16x16x32_bf16 v[70:73], v[180:183], v[224:227], v[70:73]
	v_mfma_f32_16x16x32_bf16 v[66:69], v[188:191], v[224:227], v[66:69]
	v_mfma_f32_16x16x32_bf16 v[118:121], v[184:187], v[204:207], v[118:121]
	v_mfma_f32_16x16x32_bf16 v[110:113], v[196:199], v[204:207], v[110:113]
	v_mfma_f32_16x16x32_bf16 v[102:105], v[184:187], v[212:215], v[102:105]
	v_mfma_f32_16x16x32_bf16 v[94:97], v[196:199], v[212:215], v[94:97]
	v_mfma_f32_16x16x32_bf16 v[86:89], v[184:187], v[220:223], v[86:89]
	v_mfma_f32_16x16x32_bf16 v[78:81], v[196:199], v[220:223], v[78:81]
	v_mfma_f32_16x16x32_bf16 v[70:73], v[184:187], v[228:231], v[70:73]
	v_mfma_f32_16x16x32_bf16 v[66:69], v[196:199], v[228:231], v[66:69]
	s_setprio 0
	s_barrier
	s_add_i32 s57, s48, s3
	v_lshl_add_u64 v[150:151], s[36:37], 0, v[132:133]
	s_mov_b32 m0, s57
	ds_read_b128 v[200:203], v156 offset:16384
	ds_read_b128 v[204:207], v156 offset:17408
	ds_read_b128 v[208:211], v156 offset:18432
	ds_read_b128 v[212:215], v156 offset:19456
	ds_read_b128 v[216:219], v156 offset:20480
	ds_read_b128 v[220:223], v156 offset:21504
	ds_read_b128 v[224:227], v156 offset:22528
	ds_read_b128 v[228:231], v156 offset:23552
	global_load_lds_dwordx4 v[150:151], off
	s_add_i32 m0, s57, 0x2000
	s_add_u32 s58, s36, 0x40000
	v_lshl_add_u64 v[192:193], s[36:37], 0, v[136:137]
	s_addc_u32 s59, s37, 0
	s_add_i32 s57, s49, s3
	global_load_lds_dwordx4 v[192:193], off
	v_lshl_add_u64 v[232:233], s[58:59], 0, v[132:133]
	s_mov_b32 m0, s57
	v_lshl_add_u64 v[234:235], s[38:39], 0, v[134:135]
	global_load_lds_dwordx4 v[232:233], off
	v_lshl_add_u64 v[232:233], s[58:59], 0, v[136:137]
	s_add_i32 m0, s57, 0x2000
	s_nop 0
	global_load_lds_dwordx4 v[232:233], off
	v_lshl_add_u64 v[232:233], s[38:39], 0, v[130:131]
	s_mov_b32 m0, s40
	s_nop 0
	global_load_lds_dwordx4 v[232:233], off
	s_mov_b32 m0, s41
	s_nop 0
	global_load_lds_dwordx4 v[234:235], off
	s_waitcnt vmcnt(8)
	s_waitcnt lgkmcnt(0)
	s_barrier
; #define PG8_STAGE(bufoff, gbase, voff) do { _Pragma("unroll") for (int _i = 0; _i < 2; ++_i) \
;         __builtin_amdgcn_global_load_lds((const unsigned*)((const char*)(gbase) + (voff)[_i]), (PG8_LAS unsigned*)(lds + (bufoff) + ldsw + _i * 8192), 16, 0, 0); } while (0)
; #define PG8_LDA(dst, b, h) do { _Pragma("unroll") for (int m = 0; m < 4; ++m) _Pragma("unroll") for (int k = 0; k < 2; ++k) dst[m][k] = *(const PG8_LAS bf16x8*)(lds + PG8_SA(b, h) + aoff + m * 2048 + k * 1024); } while (0)
; #define PG8_LDB(dst, b, h) do { _Pragma("unroll") for (int n = 0; n < 2; ++n) _Pragma("unroll") for (int k = 0; k < 2; ++k) dst[n][k] = *(const PG8_LAS bf16x8*)(lds + PG8_SB(b, h) + boff + n * 2048 + k * 1024); } while (0)
; #define PG8_MMA(ai, bj, At, Bt) do { __builtin_amdgcn_s_setprio(1); _Pragma("unroll") for (int m = 0; m < 4; ++m) _Pragma("unroll") for (int n = 0; n < 2; ++n) _Pragma("unroll") for (int k = 0; k < 2; ++k) \
;         acc[ai][bj][m][n] = __builtin_amdgcn_mfma_f32_16x16x32_bf16(Bt[n][k], At[m][k], acc[ai][bj][m][n], 0, 0, 0); __builtin_amdgcn_s_setprio(0); } while (0)
; #define PG8_WAIT_V(n) asm volatile("s_waitcnt vmcnt(" #n ")" ::: "memory")
; #define PG8_WAIT_L(n) asm volatile("s_waitcnt lgkmcnt(" #n ")" ::: "memory")
; #define PG8_BAR __builtin_amdgcn_s_barrier()
; #define PG8_SCHED __builtin_amdgcn_sched_barrier(0)
; template <class Epi, class Sched, bool ALIGN_EPI = false, bool SP2 = false>
; __device__ __forceinline__ void gemm_phase(PG8_LAS unsigned char* lds, const Gemm g, const Sched& S, const Epi& E) {
;     ...
;             PG8_WAIT_V(8); PG8_WAIT_L(0); PG8_BAR; PG8_MMA(1, 0, At, B0); PG8_MMA(1, 1, At, B1); PG8_BAR; PG8_SCHED;
;             PG8_LDB(B0, 1, 0); PG8_LDB(B1, 1, 1); PG8_SCHED; PG8_LDA(At, 1, 0); PG8_STAGE(PG8_SA(0, 1), a2 + hstep, voffA);
;             PG8_WAIT_V(8); PG8_WAIT_L(0); PG8_BAR; PG8_MMA(0, 0, At, B0); PG8_MMA(0, 1, At, B1); PG8_BAR; PG8_SCHED;
	s_setprio 1
	v_mfma_f32_16x16x32_bf16 v[62:65], v[164:167], v[200:203], v[62:65]
	v_mfma_f32_16x16x32_bf16 v[58:61], v[172:175], v[200:203], v[58:61]
	v_mfma_f32_16x16x32_bf16 v[50:53], v[164:167], v[208:211], v[50:53]
	v_mfma_f32_16x16x32_bf16 v[42:45], v[172:175], v[208:211], v[42:45]
	v_mfma_f32_16x16x32_bf16 v[34:37], v[164:167], v[216:219], v[34:37]
	v_mfma_f32_16x16x32_bf16 v[26:29], v[172:175], v[216:219], v[26:29]
	v_mfma_f32_16x16x32_bf16 v[18:21], v[164:167], v[224:227], v[18:21]
	v_mfma_f32_16x16x32_bf16 v[10:13], v[172:175], v[224:227], v[10:13]
	v_mfma_f32_16x16x32_bf16 v[62:65], v[168:171], v[204:207], v[62:65]
	v_mfma_f32_16x16x32_bf16 v[58:61], v[176:179], v[204:207], v[58:61]
	v_mfma_f32_16x16x32_bf16 v[50:53], v[168:171], v[212:215], v[50:53]
	v_mfma_f32_16x16x32_bf16 v[42:45], v[176:179], v[212:215], v[42:45]
	v_mfma_f32_16x16x32_bf16 v[34:37], v[168:171], v[220:223], v[34:37]
	v_mfma_f32_16x16x32_bf16 v[26:29], v[176:179], v[220:223], v[26:29]
	v_mfma_f32_16x16x32_bf16 v[18:21], v[168:171], v[228:231], v[18:21]
	v_mfma_f32_16x16x32_bf16 v[10:13], v[176:179], v[228:231], v[10:13]
	s_setprio 0
	s_setprio 1
	v_mfma_f32_16x16x32_bf16 v[54:57], v[180:183], v[200:203], v[54:57]
	v_mfma_f32_16x16x32_bf16 v[46:49], v[188:191], v[200:203], v[46:49]
	v_mfma_f32_16x16x32_bf16 v[38:41], v[180:183], v[208:211], v[38:41]
	v_mfma_f32_16x16x32_bf16 v[30:33], v[188:191], v[208:211], v[30:33]
	v_mfma_f32_16x16x32_bf16 v[22:25], v[180:183], v[216:219], v[22:25]
	v_mfma_f32_16x16x32_bf16 v[14:17], v[188:191], v[216:219], v[14:17]
	v_mfma_f32_16x16x32_bf16 v[6:9], v[180:183], v[224:227], v[6:9]
	v_mfma_f32_16x16x32_bf16 v[2:5], v[188:191], v[224:227], v[2:5]
	v_mfma_f32_16x16x32_bf16 v[54:57], v[184:187], v[204:207], v[54:57]
	v_mfma_f32_16x16x32_bf16 v[46:49], v[196:199], v[204:207], v[46:49]
	v_mfma_f32_16x16x32_bf16 v[38:41], v[184:187], v[212:215], v[38:41]
	v_mfma_f32_16x16x32_bf16 v[30:33], v[196:199], v[212:215], v[30:33]
	v_mfma_f32_16x16x32_bf16 v[22:25], v[184:187], v[220:223], v[22:25]
	v_mfma_f32_16x16x32_bf16 v[14:17], v[196:199], v[220:223], v[14:17]
	v_mfma_f32_16x16x32_bf16 v[6:9], v[184:187], v[228:231], v[6:9]
	v_mfma_f32_16x16x32_bf16 v[2:5], v[196:199], v[228:231], v[2:5]
	s_setprio 0
	s_barrier
	s_add_i32 s57, 0, 0x18000
	v_add_u32_e32 v149, s57, v152
	s_add_i32 s58, 0, 0x1c000
	ds_read_b128 v[164:167], v149
	ds_read_b128 v[168:171], v149 offset:1024
	ds_read_b128 v[172:175], v149 offset:2048
	ds_read_b128 v[176:179], v149 offset:3072
	v_add_u32_e32 v149, s58, v152
	ds_read_b128 v[180:183], v149
	ds_read_b128 v[184:187], v149 offset:1024
	ds_read_b128 v[188:191], v149 offset:2048
	ds_read_b128 v[196:199], v149 offset:3072
	s_add_u32 s38, s38, 0x40000
	s_addc_u32 s39, s39, 0
	s_mov_b32 m0, s42
	v_lshl_add_u64 v[236:237], s[38:39], 0, v[130:131]
	ds_read_b128 v[200:203], v156 offset:32768
	ds_read_b128 v[204:207], v156 offset:33792
	ds_read_b128 v[208:211], v156 offset:34816
	ds_read_b128 v[212:215], v156 offset:35840
	ds_read_b128 v[216:219], v156 offset:36864
	ds_read_b128 v[220:223], v156 offset:37888
	ds_read_b128 v[224:227], v156 offset:38912
	ds_read_b128 v[228:231], v156 offset:39936
	global_load_lds_dwordx4 v[236:237], off
	v_lshl_add_u64 v[236:237], s[38:39], 0, v[134:135]
	s_mov_b32 m0, s43
	s_nop 0
	global_load_lds_dwordx4 v[236:237], off
	s_waitcnt vmcnt(8)
	s_waitcnt lgkmcnt(0)
	s_barrier
	s_setprio 1
	v_mfma_f32_16x16x32_bf16 v[126:129], v[164:167], v[200:203], v[126:129]
	v_mfma_f32_16x16x32_bf16 v[122:125], v[172:175], v[200:203], v[122:125]
	v_mfma_f32_16x16x32_bf16 v[114:117], v[164:167], v[208:211], v[114:117]
	v_mfma_f32_16x16x32_bf16 v[106:109], v[172:175], v[208:211], v[106:109]
	v_mfma_f32_16x16x32_bf16 v[98:101], v[164:167], v[216:219], v[98:101]
	v_mfma_f32_16x16x32_bf16 v[90:93], v[172:175], v[216:219], v[90:93]
	v_mfma_f32_16x16x32_bf16 v[82:85], v[164:167], v[224:227], v[82:85]
	v_mfma_f32_16x16x32_bf16 v[74:77], v[172:175], v[224:227], v[74:77]
	v_mfma_f32_16x16x32_bf16 v[126:129], v[168:171], v[204:207], v[126:129]
	v_mfma_f32_16x16x32_bf16 v[122:125], v[176:179], v[204:207], v[122:125]
	v_mfma_f32_16x16x32_bf16 v[114:117], v[168:171], v[212:215], v[114:117]
	v_mfma_f32_16x16x32_bf16 v[106:109], v[176:179], v[212:215], v[106:109]
	v_mfma_f32_16x16x32_bf16 v[98:101], v[168:171], v[220:223], v[98:101]
	v_mfma_f32_16x16x32_bf16 v[90:93], v[176:179], v[220:223], v[90:93]
	v_mfma_f32_16x16x32_bf16 v[82:85], v[168:171], v[228:231], v[82:85]
	v_mfma_f32_16x16x32_bf16 v[74:77], v[176:179], v[228:231], v[74:77]
	s_setprio 0
	s_setprio 1
	v_mfma_f32_16x16x32_bf16 v[118:121], v[180:183], v[200:203], v[118:121]
	v_mfma_f32_16x16x32_bf16 v[110:113], v[188:191], v[200:203], v[110:113]
	v_mfma_f32_16x16x32_bf16 v[102:105], v[180:183], v[208:211], v[102:105]
	v_mfma_f32_16x16x32_bf16 v[94:97], v[188:191], v[208:211], v[94:97]
	v_mfma_f32_16x16x32_bf16 v[86:89], v[180:183], v[216:219], v[86:89]
	v_mfma_f32_16x16x32_bf16 v[78:81], v[188:191], v[216:219], v[78:81]
	v_mfma_f32_16x16x32_bf16 v[70:73], v[180:183], v[224:227], v[70:73]
	v_mfma_f32_16x16x32_bf16 v[66:69], v[188:191], v[224:227], v[66:69]
	v_mfma_f32_16x16x32_bf16 v[118:121], v[184:187], v[204:207], v[118:121]
	v_mfma_f32_16x16x32_bf16 v[110:113], v[196:199], v[204:207], v[110:113]
	v_mfma_f32_16x16x32_bf16 v[102:105], v[184:187], v[212:215], v[102:105]
	v_mfma_f32_16x16x32_bf16 v[94:97], v[196:199], v[212:215], v[94:97]
	v_mfma_f32_16x16x32_bf16 v[86:89], v[184:187], v[220:223], v[86:89]
	v_mfma_f32_16x16x32_bf16 v[78:81], v[196:199], v[220:223], v[78:81]
	v_mfma_f32_16x16x32_bf16 v[70:73], v[184:187], v[228:231], v[70:73]
	v_mfma_f32_16x16x32_bf16 v[66:69], v[196:199], v[228:231], v[66:69]
	s_setprio 0
	s_barrier
; #define PG8_STAGE(bufoff, gbase, voff) do { _Pragma("unroll") for (int _i = 0; _i < 2; ++_i) \
;         __builtin_amdgcn_global_load_lds((const unsigned*)((const char*)(gbase) + (voff)[_i]), (PG8_LAS unsigned*)(lds + (bufoff) + ldsw + _i * 8192), 16, 0, 0); } while (0)
; #define PG8_LDA(dst, b, h) do { _Pragma("unroll") for (int m = 0; m < 4; ++m) _Pragma("unroll") for (int k = 0; k < 2; ++k) dst[m][k] = *(const PG8_LAS bf16x8*)(lds + PG8_SA(b, h) + aoff + m * 2048 + k * 1024); } while (0)
; #define PG8_MMA(ai, bj, At, Bt) do { __builtin_amdgcn_s_setprio(1); _Pragma("unroll") for (int m = 0; m < 4; ++m) _Pragma("unroll") for (int n = 0; n < 2; ++n) _Pragma("unroll") for (int k = 0; k < 2; ++k) \
;         acc[ai][bj][m][n] = __builtin_amdgcn_mfma_f32_16x16x32_bf16(Bt[n][k], At[m][k], acc[ai][bj][m][n], 0, 0, 0); __builtin_amdgcn_s_setprio(0); } while (0)
; #define PG8_WAIT_V(n) asm volatile("s_waitcnt vmcnt(" #n ")" ::: "memory")
; #define PG8_WAIT_L(n) asm volatile("s_waitcnt lgkmcnt(" #n ")" ::: "memory")
; #define PG8_BAR __builtin_amdgcn_s_barrier()
; #define PG8_SCHED __builtin_amdgcn_sched_barrier(0)
; template <class Epi, class Sched, bool ALIGN_EPI = false, bool SP2 = false>
; __device__ __forceinline__ void gemm_phase(PG8_LAS unsigned char* lds, const Gemm g, const Sched& S, const Epi& E) {
;     ...
;         for (int t = 0; t < nt; t += 2) {
;             const bool last = (t == nt - 2);
;             const char* a1 = cA + (size_t)(t + 1) * kstep;
;             const char* a2 = last ? nA : cA + (size_t)(t + 2) * kstep; const char* b2 = last ? nB : cB + (size_t)(t + 2) * kstep;
;             const char* a3 = a2 + kstep; const char* b3 = b2 + kstep;
;     ...
;             PG8_LDA(At, 1, 1); PG8_STAGE(PG8_SB(1, 0), b3, voffB); PG8_STAGE(PG8_SB(1, 1), b3 + hstep, voffB); PG8_STAGE(PG8_SA(1, 0), a3, voffA);
;             PG8_WAIT_V(8); PG8_WAIT_L(0); PG8_BAR; PG8_MMA(1, 0, At, B0); PG8_MMA(1, 1, At, B1); PG8_BAR; PG8_SCHED;
	s_add_i32 s38, s57, s3
	v_lshl_add_u64 v[150:151], v[150:151], 0, s[12:13]
	s_mov_b32 m0, s38
	ds_read_b128 v[200:203], v156 offset:49152
	ds_read_b128 v[204:207], v156 offset:50176
	ds_read_b128 v[208:211], v156 offset:51200
	ds_read_b128 v[212:215], v156 offset:52224
	ds_read_b128 v[216:219], v156 offset:53248
	ds_read_b128 v[220:223], v156 offset:54272
	ds_read_b128 v[224:227], v156 offset:55296
	ds_read_b128 v[228:231], v156 offset:56320
	global_load_lds_dwordx4 v[150:151], off
	s_add_i32 m0, s38, 0x2000
	s_add_u32 s36, s36, 0x40080
	v_lshl_add_u64 v[150:151], v[192:193], 0, s[12:13]
	s_addc_u32 s37, s37, 0
	s_add_i32 s38, s58, s3
	global_load_lds_dwordx4 v[150:151], off
	v_lshl_add_u64 v[150:151], s[36:37], 0, v[132:133]
	s_mov_b32 m0, s38
	s_nop 0
	global_load_lds_dwordx4 v[150:151], off
	v_lshl_add_u64 v[150:151], s[36:37], 0, v[136:137]
	s_add_i32 m0, s38, 0x2000
	s_nop 0
	global_load_lds_dwordx4 v[150:151], off
	v_lshl_add_u64 v[150:151], v[232:233], 0, s[12:13]
	s_mov_b32 m0, s45
	s_nop 0
	global_load_lds_dwordx4 v[150:151], off
	v_lshl_add_u64 v[150:151], v[234:235], 0, s[12:13]
	s_mov_b32 m0, s46
	s_nop 0
	global_load_lds_dwordx4 v[150:151], off
	s_waitcnt vmcnt(8)
	s_waitcnt lgkmcnt(0)
	s_barrier
	s_setprio 1
	v_mfma_f32_16x16x32_bf16 v[62:65], v[164:167], v[200:203], v[62:65]
	v_mfma_f32_16x16x32_bf16 v[58:61], v[172:175], v[200:203], v[58:61]
	v_mfma_f32_16x16x32_bf16 v[50:53], v[164:167], v[208:211], v[50:53]
	v_mfma_f32_16x16x32_bf16 v[42:45], v[172:175], v[208:211], v[42:45]
	v_mfma_f32_16x16x32_bf16 v[34:37], v[164:167], v[216:219], v[34:37]
	v_mfma_f32_16x16x32_bf16 v[26:29], v[172:175], v[216:219], v[26:29]
	v_mfma_f32_16x16x32_bf16 v[18:21], v[164:167], v[224:227], v[18:21]
	v_mfma_f32_16x16x32_bf16 v[10:13], v[172:175], v[224:227], v[10:13]
	v_mfma_f32_16x16x32_bf16 v[62:65], v[168:171], v[204:207], v[62:65]
	v_mfma_f32_16x16x32_bf16 v[58:61], v[176:179], v[204:207], v[58:61]
	v_mfma_f32_16x16x32_bf16 v[50:53], v[168:171], v[212:215], v[50:53]
	v_mfma_f32_16x16x32_bf16 v[42:45], v[176:179], v[212:215], v[42:45]
	v_mfma_f32_16x16x32_bf16 v[34:37], v[168:171], v[220:223], v[34:37]
	v_mfma_f32_16x16x32_bf16 v[26:29], v[176:179], v[220:223], v[26:29]
	v_mfma_f32_16x16x32_bf16 v[18:21], v[168:171], v[228:231], v[18:21]
	v_mfma_f32_16x16x32_bf16 v[10:13], v[176:179], v[228:231], v[10:13]
	s_setprio 0
	s_setprio 1
	v_mfma_f32_16x16x32_bf16 v[54:57], v[180:183], v[200:203], v[54:57]
	v_mfma_f32_16x16x32_bf16 v[46:49], v[188:191], v[200:203], v[46:49]
	v_mfma_f32_16x16x32_bf16 v[38:41], v[180:183], v[208:211], v[38:41]
	v_mfma_f32_16x16x32_bf16 v[30:33], v[188:191], v[208:211], v[30:33]
	v_mfma_f32_16x16x32_bf16 v[22:25], v[180:183], v[216:219], v[22:25]
	v_mfma_f32_16x16x32_bf16 v[14:17], v[188:191], v[216:219], v[14:17]
	v_mfma_f32_16x16x32_bf16 v[6:9], v[180:183], v[224:227], v[6:9]
	v_mfma_f32_16x16x32_bf16 v[2:5], v[188:191], v[224:227], v[2:5]
	v_mfma_f32_16x16x32_bf16 v[54:57], v[184:187], v[204:207], v[54:57]
	v_mfma_f32_16x16x32_bf16 v[46:49], v[196:199], v[204:207], v[46:49]
	v_mfma_f32_16x16x32_bf16 v[38:41], v[184:187], v[212:215], v[38:41]
	v_mfma_f32_16x16x32_bf16 v[30:33], v[196:199], v[212:215], v[30:33]
	v_mfma_f32_16x16x32_bf16 v[22:25], v[184:187], v[220:223], v[22:25]
	v_mfma_f32_16x16x32_bf16 v[14:17], v[196:199], v[220:223], v[14:17]
	v_mfma_f32_16x16x32_bf16 v[6:9], v[184:187], v[228:231], v[6:9]
	v_mfma_f32_16x16x32_bf16 v[2:5], v[196:199], v[228:231], v[2:5]
	s_setprio 0
	s_barrier
	s_add_i32 s56, s56, 2
	s_add_u32 s34, s34, 0x100
	s_addc_u32 s35, s35, 0
	s_add_u32 s54, s54, 0x100
	s_addc_u32 s55, s55, 0
	s_cmp_gt_u32 s56, 13
	s_cbranch_scc0 .LBB0_1406
	s_and_b64 vcc, exec, s[14:15]
	s_cbranch_vccz .LBB0_1409
	s_barrier

; #define PG8_STAGE(bufoff, gbase, voff) do { _Pragma("unroll") for (int _i = 0; _i < 2; ++_i) \
;         __builtin_amdgcn_global_load_lds((const unsigned*)((const char*)(gbase) + (voff)[_i]), (PG8_LAS unsigned*)(lds + (bufoff) + ldsw + _i * 8192), 16, 0, 0); } while (0)
; #define PG8_LDA(dst, b, h) do { _Pragma("unroll") for (int m = 0; m < 4; ++m) _Pragma("unroll") for (int k = 0; k < 2; ++k) dst[m][k] = *(const PG8_LAS bf16x8*)(lds + PG8_SA(b, h) + aoff + m * 2048 + k * 1024); } while (0)
; #define PG8_LDB(dst, b, h) do { _Pragma("unroll") for (int n = 0; n < 2; ++n) _Pragma("unroll") for (int k = 0; k < 2; ++k) dst[n][k] = *(const PG8_LAS bf16x8*)(lds + PG8_SB(b, h) + boff + n * 2048 + k * 1024); } while (0)
; #define PG8_MMA(ai, bj, At, Bt) do { __builtin_amdgcn_s_setprio(1); _Pragma("unroll") for (int m = 0; m < 4; ++m) _Pragma("unroll") for (int n = 0; n < 2; ++n) _Pragma("unroll") for (int k = 0; k < 2; ++k) \
;         acc[ai][bj][m][n] = __builtin_amdgcn_mfma_f32_16x16x32_bf16(Bt[n][k], At[m][k], acc[ai][bj][m][n], 0, 0, 0); __builtin_amdgcn_s_setprio(0); } while (0)
; #define PG8_WAIT_V(n) asm volatile("s_waitcnt vmcnt(" #n ")" ::: "memory")
; #define PG8_BAR __builtin_amdgcn_s_barrier()
; template <class Epi, class Sched, bool ALIGN_EPI = false, bool SP2 = false>
; __device__ __forceinline__ void gemm_phase(PG8_LAS unsigned char* lds, const Gemm g, const Sched& S, const Epi& E) {
;     ...
;         for (int t = 0; t < nt; t += 2) {
;             const bool last = (t == nt - 2);
;             const char* a1 = cA + (size_t)(t + 1) * kstep;
;             const char* a2 = last ? nA : cA + (size_t)(t + 2) * kstep; const char* b2 = last ? nB : cB + (size_t)(t + 2) * kstep;
;             const char* a3 = a2 + kstep; const char* b3 = b2 + kstep;
;             if (last && has_next) S.a_ready(nxt);
;             if constexpr (SP2) {
;             PG8_LDB(B0, 0, 0); PG8_LDB(B1, 0, 1); PG8_SCHED; PG8_LDA(At, 0, 0); PG8_STAGE(PG8_SA(1, 1), a1 + hstep, voffA);
;             PG8_WAIT_V(8); PG8_WAIT_L(0); PG8_BAR; PG8_MMA(0, 0, At, B0); PG8_MMA(0, 1, At, B1); PG8_BAR; PG8_SCHED;
;             PG8_LDA(At, 0, 1); PG8_STAGE(PG8_SB(0, 0), b2, voffB); PG8_STAGE(PG8_SB(0, 1), b2 + hstep, voffB); PG8_STAGE(PG8_SA(0, 0), a2, voffA);
;             PG8_WAIT_V(8); PG8_WAIT_L(0); PG8_BAR; PG8_MMA(1, 0, At, B0); PG8_MMA(1, 1, At, B1); PG8_BAR; PG8_SCHED;
.LBB0_1948:
	ds_read_b128 v[146:149], v152
	ds_read_b128 v[156:159], v152 offset:1024
	ds_read_b128 v[160:163], v152 offset:2048
	ds_read_b128 v[164:167], v152 offset:3072
	ds_read_b128 v[168:171], v153
	ds_read_b128 v[172:175], v153 offset:1024
	ds_read_b128 v[176:179], v153 offset:2048
	ds_read_b128 v[180:183], v153 offset:3072
	s_add_u32 s38, s36, 0xfffc0080
	s_addc_u32 s39, s37, -1
	s_cmp_eq_u32 s55, 12
	s_cselect_b32 s41, s21, s39
	s_cselect_b32 s40, s27, s38
	s_cselect_b32 s39, s19, s54
	s_cselect_b32 s38, s52, s53
	v_lshl_add_u64 v[216:217], s[36:37], 0, v[138:139]
	s_add_i32 m0, s3, 0xc000
	ds_read_b128 v[184:187], v154
	ds_read_b128 v[188:191], v154 offset:1024
	ds_read_b128 v[192:195], v154 offset:2048
	ds_read_b128 v[196:199], v154 offset:3072
	ds_read_b128 v[200:203], v154 offset:4096
	ds_read_b128 v[204:207], v154 offset:5120
	ds_read_b128 v[208:211], v154 offset:6144
	ds_read_b128 v[212:215], v154 offset:7168
	global_load_lds_dwordx4 v[216:217], off
	v_lshl_add_u64 v[216:217], s[36:37], 0, v[140:141]
	s_add_i32 m0, s3, 0xe000
	s_nop 0
	global_load_lds_dwordx4 v[216:217], off
	s_waitcnt vmcnt(8)
	s_waitcnt lgkmcnt(0)
	s_barrier
	s_setprio 1
	v_mfma_f32_16x16x32_bf16 v[126:129], v[146:149], v[184:187], v[126:129]
	v_mfma_f32_16x16x32_bf16 v[122:125], v[160:163], v[184:187], v[122:125]
	v_mfma_f32_16x16x32_bf16 v[110:113], v[146:149], v[192:195], v[110:113]
	v_mfma_f32_16x16x32_bf16 v[106:109], v[160:163], v[192:195], v[106:109]
	v_mfma_f32_16x16x32_bf16 v[94:97], v[146:149], v[200:203], v[94:97]
	v_mfma_f32_16x16x32_bf16 v[90:93], v[160:163], v[200:203], v[90:93]
	v_mfma_f32_16x16x32_bf16 v[78:81], v[146:149], v[208:211], v[78:81]
	v_mfma_f32_16x16x32_bf16 v[74:77], v[160:163], v[208:211], v[74:77]
	v_mfma_f32_16x16x32_bf16 v[126:129], v[156:159], v[188:191], v[126:129]
	v_mfma_f32_16x16x32_bf16 v[122:125], v[164:167], v[188:191], v[122:125]
	v_mfma_f32_16x16x32_bf16 v[110:113], v[156:159], v[196:199], v[110:113]
	v_mfma_f32_16x16x32_bf16 v[106:109], v[164:167], v[196:199], v[106:109]
	v_mfma_f32_16x16x32_bf16 v[94:97], v[156:159], v[204:207], v[94:97]
	v_mfma_f32_16x16x32_bf16 v[90:93], v[164:167], v[204:207], v[90:93]
	v_mfma_f32_16x16x32_bf16 v[78:81], v[156:159], v[212:215], v[78:81]
	v_mfma_f32_16x16x32_bf16 v[74:77], v[164:167], v[212:215], v[74:77]
	s_setprio 0
	s_setprio 1
	v_mfma_f32_16x16x32_bf16 v[118:121], v[168:171], v[184:187], v[118:121]
	v_mfma_f32_16x16x32_bf16 v[114:117], v[176:179], v[184:187], v[114:117]
	v_mfma_f32_16x16x32_bf16 v[102:105], v[168:171], v[192:195], v[102:105]
	v_mfma_f32_16x16x32_bf16 v[98:101], v[176:179], v[192:195], v[98:101]
	v_mfma_f32_16x16x32_bf16 v[86:89], v[168:171], v[200:203], v[86:89]
	v_mfma_f32_16x16x32_bf16 v[82:85], v[176:179], v[200:203], v[82:85]
	v_mfma_f32_16x16x32_bf16 v[70:73], v[168:171], v[208:211], v[70:73]
	v_mfma_f32_16x16x32_bf16 v[66:69], v[176:179], v[208:211], v[66:69]
	v_mfma_f32_16x16x32_bf16 v[118:121], v[172:175], v[188:191], v[118:121]
	v_mfma_f32_16x16x32_bf16 v[114:117], v[180:183], v[188:191], v[114:117]
	v_mfma_f32_16x16x32_bf16 v[102:105], v[172:175], v[196:199], v[102:105]
	v_mfma_f32_16x16x32_bf16 v[98:101], v[180:183], v[196:199], v[98:101]
	v_mfma_f32_16x16x32_bf16 v[86:89], v[172:175], v[204:207], v[86:89]
	v_mfma_f32_16x16x32_bf16 v[82:85], v[180:183], v[204:207], v[82:85]
	v_mfma_f32_16x16x32_bf16 v[70:73], v[172:175], v[212:215], v[70:73]
	v_mfma_f32_16x16x32_bf16 v[66:69], v[180:183], v[212:215], v[66:69]
	s_setprio 0
	s_barrier
	s_add_i32 s56, s49, s2
	v_lshl_add_u64 v[216:217], s[38:39], 0, v[132:133]
	s_mov_b32 m0, s56
	ds_read_b128 v[184:187], v154 offset:16384
	ds_read_b128 v[188:191], v154 offset:17408
	ds_read_b128 v[192:195], v154 offset:18432
	ds_read_b128 v[196:199], v154 offset:19456
	ds_read_b128 v[200:203], v154 offset:20480
	ds_read_b128 v[204:207], v154 offset:21504
	ds_read_b128 v[208:211], v154 offset:22528
	ds_read_b128 v[212:215], v154 offset:23552
	global_load_lds_dwordx4 v[216:217], off
	s_add_i32 m0, s56, 0x2000
	s_add_u32 s56, s38, 0x40000
	v_lshl_add_u64 v[218:219], s[38:39], 0, v[136:137]
	s_addc_u32 s57, s39, 0
	s_add_i32 s58, s50, s2
	global_load_lds_dwordx4 v[218:219], off
	v_lshl_add_u64 v[220:221], s[56:57], 0, v[132:133]
	s_mov_b32 m0, s58
	v_lshl_add_u64 v[222:223], s[40:41], 0, v[134:135]
	global_load_lds_dwordx4 v[220:221], off
	v_lshl_add_u64 v[220:221], s[56:57], 0, v[136:137]
	s_add_i32 m0, s58, 0x2000
	s_nop 0
	global_load_lds_dwordx4 v[220:221], off
	v_lshl_add_u64 v[220:221], s[40:41], 0, v[130:131]
	s_mov_b32 m0, s3
	s_nop 0
	global_load_lds_dwordx4 v[220:221], off
	s_mov_b32 m0, s35
	s_nop 0
	global_load_lds_dwordx4 v[222:223], off
	s_waitcnt vmcnt(8)
	s_waitcnt lgkmcnt(0)
	s_barrier
; #define PG8_STAGE(bufoff, gbase, voff) do { _Pragma("unroll") for (int _i = 0; _i < 2; ++_i) \
;         __builtin_amdgcn_global_load_lds((const unsigned*)((const char*)(gbase) + (voff)[_i]), (PG8_LAS unsigned*)(lds + (bufoff) + ldsw + _i * 8192), 16, 0, 0); } while (0)
; #define PG8_LDA(dst, b, h) do { _Pragma("unroll") for (int m = 0; m < 4; ++m) _Pragma("unroll") for (int k = 0; k < 2; ++k) dst[m][k] = *(const PG8_LAS bf16x8*)(lds + PG8_SA(b, h) + aoff + m * 2048 + k * 1024); } while (0)
; #define PG8_LDB(dst, b, h) do { _Pragma("unroll") for (int n = 0; n < 2; ++n) _Pragma("unroll") for (int k = 0; k < 2; ++k) dst[n][k] = *(const PG8_LAS bf16x8*)(lds + PG8_SB(b, h) + boff + n * 2048 + k * 1024); } while (0)
; #define PG8_MMA(ai, bj, At, Bt) do { __builtin_amdgcn_s_setprio(1); _Pragma("unroll") for (int m = 0; m < 4; ++m) _Pragma("unroll") for (int n = 0; n < 2; ++n) _Pragma("unroll") for (int k = 0; k < 2; ++k) \
;         acc[ai][bj][m][n] = __builtin_amdgcn_mfma_f32_16x16x32_bf16(Bt[n][k], At[m][k], acc[ai][bj][m][n], 0, 0, 0); __builtin_amdgcn_s_setprio(0); } while (0)
; #define PG8_WAIT_V(n) asm volatile("s_waitcnt vmcnt(" #n ")" ::: "memory")
; #define PG8_WAIT_L(n) asm volatile("s_waitcnt lgkmcnt(" #n ")" ::: "memory")
; #define PG8_BAR __builtin_amdgcn_s_barrier()
; #define PG8_SCHED __builtin_amdgcn_sched_barrier(0)
; template <class Epi, class Sched, bool ALIGN_EPI = false, bool SP2 = false>
; __device__ __forceinline__ void gemm_phase(PG8_LAS unsigned char* lds, const Gemm g, const Sched& S, const Epi& E) {
;     ...
;             PG8_WAIT_V(8); PG8_WAIT_L(0); PG8_BAR; PG8_MMA(1, 0, At, B0); PG8_MMA(1, 1, At, B1); PG8_BAR; PG8_SCHED;
;             PG8_LDB(B0, 1, 0); PG8_LDB(B1, 1, 1); PG8_SCHED; PG8_LDA(At, 1, 0); PG8_STAGE(PG8_SA(0, 1), a2 + hstep, voffA);
;             PG8_WAIT_V(8); PG8_WAIT_L(0); PG8_BAR; PG8_MMA(0, 0, At, B0); PG8_MMA(0, 1, At, B1); PG8_BAR; PG8_SCHED;
	s_setprio 1
	v_mfma_f32_16x16x32_bf16 v[62:65], v[146:149], v[184:187], v[62:65]
	v_mfma_f32_16x16x32_bf16 v[58:61], v[160:163], v[184:187], v[58:61]
	v_mfma_f32_16x16x32_bf16 v[46:49], v[146:149], v[192:195], v[46:49]
	v_mfma_f32_16x16x32_bf16 v[42:45], v[160:163], v[192:195], v[42:45]
	v_mfma_f32_16x16x32_bf16 v[30:33], v[146:149], v[200:203], v[30:33]
	v_mfma_f32_16x16x32_bf16 v[26:29], v[160:163], v[200:203], v[26:29]
	v_mfma_f32_16x16x32_bf16 v[14:17], v[146:149], v[208:211], v[14:17]
	v_mfma_f32_16x16x32_bf16 v[10:13], v[160:163], v[208:211], v[10:13]
	v_mfma_f32_16x16x32_bf16 v[62:65], v[156:159], v[188:191], v[62:65]
	v_mfma_f32_16x16x32_bf16 v[58:61], v[164:167], v[188:191], v[58:61]
	v_mfma_f32_16x16x32_bf16 v[46:49], v[156:159], v[196:199], v[46:49]
	v_mfma_f32_16x16x32_bf16 v[42:45], v[164:167], v[196:199], v[42:45]
	v_mfma_f32_16x16x32_bf16 v[30:33], v[156:159], v[204:207], v[30:33]
	v_mfma_f32_16x16x32_bf16 v[26:29], v[164:167], v[204:207], v[26:29]
	v_mfma_f32_16x16x32_bf16 v[14:17], v[156:159], v[212:215], v[14:17]
	v_mfma_f32_16x16x32_bf16 v[10:13], v[164:167], v[212:215], v[10:13]
	s_setprio 0
	s_setprio 1
	v_mfma_f32_16x16x32_bf16 v[54:57], v[168:171], v[184:187], v[54:57]
	v_mfma_f32_16x16x32_bf16 v[50:53], v[176:179], v[184:187], v[50:53]
	v_mfma_f32_16x16x32_bf16 v[38:41], v[168:171], v[192:195], v[38:41]
	v_mfma_f32_16x16x32_bf16 v[34:37], v[176:179], v[192:195], v[34:37]
	v_mfma_f32_16x16x32_bf16 v[22:25], v[168:171], v[200:203], v[22:25]
	v_mfma_f32_16x16x32_bf16 v[18:21], v[176:179], v[200:203], v[18:21]
	v_mfma_f32_16x16x32_bf16 v[6:9], v[168:171], v[208:211], v[6:9]
	v_mfma_f32_16x16x32_bf16 v[2:5], v[176:179], v[208:211], v[2:5]
	v_mfma_f32_16x16x32_bf16 v[54:57], v[172:175], v[188:191], v[54:57]
	v_mfma_f32_16x16x32_bf16 v[50:53], v[180:183], v[188:191], v[50:53]
	v_mfma_f32_16x16x32_bf16 v[38:41], v[172:175], v[196:199], v[38:41]
	v_mfma_f32_16x16x32_bf16 v[34:37], v[180:183], v[196:199], v[34:37]
	v_mfma_f32_16x16x32_bf16 v[22:25], v[172:175], v[204:207], v[22:25]
	v_mfma_f32_16x16x32_bf16 v[18:21], v[180:183], v[204:207], v[18:21]
	v_mfma_f32_16x16x32_bf16 v[6:9], v[172:175], v[212:215], v[6:9]
	v_mfma_f32_16x16x32_bf16 v[2:5], v[180:183], v[212:215], v[2:5]
	s_setprio 0
	s_barrier
	s_add_i32 s56, 0, 0x18000
	s_add_i32 s57, 0, 0x1c000
	v_add_u32_e32 v164, s56, v150
	v_add_u32_e32 v180, s57, v150
	ds_read_b128 v[146:149], v164
	ds_read_b128 v[156:159], v164 offset:1024
	ds_read_b128 v[160:163], v164 offset:2048
	ds_read_b128 v[164:167], v164 offset:3072
	ds_read_b128 v[168:171], v180
	ds_read_b128 v[172:175], v180 offset:1024
	ds_read_b128 v[176:179], v180 offset:2048
	ds_read_b128 v[180:183], v180 offset:3072
	s_add_u32 s40, s40, 0x40000
	s_addc_u32 s41, s41, 0
	s_mov_b32 m0, s42
	v_lshl_add_u64 v[224:225], s[40:41], 0, v[130:131]
	ds_read_b128 v[184:187], v154 offset:32768
	ds_read_b128 v[188:191], v154 offset:33792
	ds_read_b128 v[192:195], v154 offset:34816
	ds_read_b128 v[196:199], v154 offset:35840
	ds_read_b128 v[200:203], v154 offset:36864
	ds_read_b128 v[204:207], v154 offset:37888
	ds_read_b128 v[208:211], v154 offset:38912
	ds_read_b128 v[212:215], v154 offset:39936
	global_load_lds_dwordx4 v[224:225], off
	v_lshl_add_u64 v[224:225], s[40:41], 0, v[134:135]
	s_mov_b32 m0, s43
	s_nop 0
	global_load_lds_dwordx4 v[224:225], off
	s_waitcnt vmcnt(8)
	s_waitcnt lgkmcnt(0)
	s_barrier
	s_setprio 1
	v_mfma_f32_16x16x32_bf16 v[126:129], v[146:149], v[184:187], v[126:129]
	v_mfma_f32_16x16x32_bf16 v[122:125], v[160:163], v[184:187], v[122:125]
	v_mfma_f32_16x16x32_bf16 v[110:113], v[146:149], v[192:195], v[110:113]
	v_mfma_f32_16x16x32_bf16 v[106:109], v[160:163], v[192:195], v[106:109]
	v_mfma_f32_16x16x32_bf16 v[94:97], v[146:149], v[200:203], v[94:97]
	v_mfma_f32_16x16x32_bf16 v[90:93], v[160:163], v[200:203], v[90:93]
	v_mfma_f32_16x16x32_bf16 v[78:81], v[146:149], v[208:211], v[78:81]
	v_mfma_f32_16x16x32_bf16 v[74:77], v[160:163], v[208:211], v[74:77]
	v_mfma_f32_16x16x32_bf16 v[126:129], v[156:159], v[188:191], v[126:129]
	v_mfma_f32_16x16x32_bf16 v[122:125], v[164:167], v[188:191], v[122:125]
	v_mfma_f32_16x16x32_bf16 v[110:113], v[156:159], v[196:199], v[110:113]
	v_mfma_f32_16x16x32_bf16 v[106:109], v[164:167], v[196:199], v[106:109]
	v_mfma_f32_16x16x32_bf16 v[94:97], v[156:159], v[204:207], v[94:97]
	v_mfma_f32_16x16x32_bf16 v[90:93], v[164:167], v[204:207], v[90:93]
	v_mfma_f32_16x16x32_bf16 v[78:81], v[156:159], v[212:215], v[78:81]
	v_mfma_f32_16x16x32_bf16 v[74:77], v[164:167], v[212:215], v[74:77]
	s_setprio 0
	s_setprio 1
	v_mfma_f32_16x16x32_bf16 v[118:121], v[168:171], v[184:187], v[118:121]
	v_mfma_f32_16x16x32_bf16 v[114:117], v[176:179], v[184:187], v[114:117]
	v_mfma_f32_16x16x32_bf16 v[102:105], v[168:171], v[192:195], v[102:105]
	v_mfma_f32_16x16x32_bf16 v[98:101], v[176:179], v[192:195], v[98:101]
	v_mfma_f32_16x16x32_bf16 v[86:89], v[168:171], v[200:203], v[86:89]
	v_mfma_f32_16x16x32_bf16 v[82:85], v[176:179], v[200:203], v[82:85]
	v_mfma_f32_16x16x32_bf16 v[70:73], v[168:171], v[208:211], v[70:73]
	v_mfma_f32_16x16x32_bf16 v[66:69], v[176:179], v[208:211], v[66:69]
	v_mfma_f32_16x16x32_bf16 v[118:121], v[172:175], v[188:191], v[118:121]
	v_mfma_f32_16x16x32_bf16 v[114:117], v[180:183], v[188:191], v[114:117]
	v_mfma_f32_16x16x32_bf16 v[102:105], v[172:175], v[196:199], v[102:105]
	v_mfma_f32_16x16x32_bf16 v[98:101], v[180:183], v[196:199], v[98:101]
	v_mfma_f32_16x16x32_bf16 v[86:89], v[172:175], v[204:207], v[86:89]
	v_mfma_f32_16x16x32_bf16 v[82:85], v[180:183], v[204:207], v[82:85]
	v_mfma_f32_16x16x32_bf16 v[70:73], v[172:175], v[212:215], v[70:73]
	v_mfma_f32_16x16x32_bf16 v[66:69], v[180:183], v[212:215], v[66:69]
	s_setprio 0
	s_barrier
; #define PG8_STAGE(bufoff, gbase, voff) do { _Pragma("unroll") for (int _i = 0; _i < 2; ++_i) \
;         __builtin_amdgcn_global_load_lds((const unsigned*)((const char*)(gbase) + (voff)[_i]), (PG8_LAS unsigned*)(lds + (bufoff) + ldsw + _i * 8192), 16, 0, 0); } while (0)
; #define PG8_LDA(dst, b, h) do { _Pragma("unroll") for (int m = 0; m < 4; ++m) _Pragma("unroll") for (int k = 0; k < 2; ++k) dst[m][k] = *(const PG8_LAS bf16x8*)(lds + PG8_SA(b, h) + aoff + m * 2048 + k * 1024); } while (0)
; #define PG8_MMA(ai, bj, At, Bt) do { __builtin_amdgcn_s_setprio(1); _Pragma("unroll") for (int m = 0; m < 4; ++m) _Pragma("unroll") for (int n = 0; n < 2; ++n) _Pragma("unroll") for (int k = 0; k < 2; ++k) \
;         acc[ai][bj][m][n] = __builtin_amdgcn_mfma_f32_16x16x32_bf16(Bt[n][k], At[m][k], acc[ai][bj][m][n], 0, 0, 0); __builtin_amdgcn_s_setprio(0); } while (0)
; #define PG8_WAIT_V(n) asm volatile("s_waitcnt vmcnt(" #n ")" ::: "memory")
; #define PG8_WAIT_L(n) asm volatile("s_waitcnt lgkmcnt(" #n ")" ::: "memory")
; #define PG8_BAR __builtin_amdgcn_s_barrier()
; #define PG8_SCHED __builtin_amdgcn_sched_barrier(0)
; template <class Epi, class Sched, bool ALIGN_EPI = false, bool SP2 = false>
; __device__ __forceinline__ void gemm_phase(PG8_LAS unsigned char* lds, const Gemm g, const Sched& S, const Epi& E) {
;     ...
;         for (int t = 0; t < nt; t += 2) {
;             const bool last = (t == nt - 2);
;             const char* a1 = cA + (size_t)(t + 1) * kstep;
;             const char* a2 = last ? nA : cA + (size_t)(t + 2) * kstep; const char* b2 = last ? nB : cB + (size_t)(t + 2) * kstep;
;             const char* a3 = a2 + kstep; const char* b3 = b2 + kstep;
;     ...
;             PG8_LDA(At, 1, 1); PG8_STAGE(PG8_SB(1, 0), b3, voffB); PG8_STAGE(PG8_SB(1, 1), b3 + hstep, voffB); PG8_STAGE(PG8_SA(1, 0), a3, voffA);
;             PG8_WAIT_V(8); PG8_WAIT_L(0); PG8_BAR; PG8_MMA(1, 0, At, B0); PG8_MMA(1, 1, At, B1); PG8_BAR; PG8_SCHED;
	s_add_i32 s40, s56, s2
	v_lshl_add_u64 v[216:217], v[216:217], 0, s[14:15]
	s_mov_b32 m0, s40
	ds_read_b128 v[184:187], v154 offset:49152
	ds_read_b128 v[188:191], v154 offset:50176
	ds_read_b128 v[192:195], v154 offset:51200
	ds_read_b128 v[196:199], v154 offset:52224
	ds_read_b128 v[200:203], v154 offset:53248
	ds_read_b128 v[204:207], v154 offset:54272
	ds_read_b128 v[208:211], v154 offset:55296
	ds_read_b128 v[212:215], v154 offset:56320
	global_load_lds_dwordx4 v[216:217], off
	s_add_i32 m0, s40, 0x2000
	s_add_u32 s38, s38, 0x40080
	v_lshl_add_u64 v[216:217], v[218:219], 0, s[14:15]
	s_addc_u32 s39, s39, 0
	s_add_i32 s40, s57, s2
	global_load_lds_dwordx4 v[216:217], off
	v_lshl_add_u64 v[216:217], s[38:39], 0, v[132:133]
	s_mov_b32 m0, s40
	s_nop 0
	global_load_lds_dwordx4 v[216:217], off
	v_lshl_add_u64 v[216:217], s[38:39], 0, v[136:137]
	s_add_i32 m0, s40, 0x2000
	s_nop 0
	global_load_lds_dwordx4 v[216:217], off
	v_lshl_add_u64 v[216:217], v[220:221], 0, s[14:15]
	s_mov_b32 m0, s45
	s_nop 0
	global_load_lds_dwordx4 v[216:217], off
	v_lshl_add_u64 v[216:217], v[222:223], 0, s[14:15]
	s_mov_b32 m0, s46
	s_nop 0
	global_load_lds_dwordx4 v[216:217], off
	s_waitcnt vmcnt(8)
	s_waitcnt lgkmcnt(0)
	s_barrier
	s_setprio 1
	v_mfma_f32_16x16x32_bf16 v[62:65], v[146:149], v[184:187], v[62:65]
	v_mfma_f32_16x16x32_bf16 v[58:61], v[160:163], v[184:187], v[58:61]
	v_mfma_f32_16x16x32_bf16 v[46:49], v[146:149], v[192:195], v[46:49]
	v_mfma_f32_16x16x32_bf16 v[42:45], v[160:163], v[192:195], v[42:45]
	v_mfma_f32_16x16x32_bf16 v[30:33], v[146:149], v[200:203], v[30:33]
	v_mfma_f32_16x16x32_bf16 v[26:29], v[160:163], v[200:203], v[26:29]
	v_mfma_f32_16x16x32_bf16 v[14:17], v[146:149], v[208:211], v[14:17]
	v_mfma_f32_16x16x32_bf16 v[10:13], v[160:163], v[208:211], v[10:13]
	v_mfma_f32_16x16x32_bf16 v[62:65], v[156:159], v[188:191], v[62:65]
	v_mfma_f32_16x16x32_bf16 v[58:61], v[164:167], v[188:191], v[58:61]
	v_mfma_f32_16x16x32_bf16 v[46:49], v[156:159], v[196:199], v[46:49]
	v_mfma_f32_16x16x32_bf16 v[42:45], v[164:167], v[196:199], v[42:45]
	v_mfma_f32_16x16x32_bf16 v[30:33], v[156:159], v[204:207], v[30:33]
	v_mfma_f32_16x16x32_bf16 v[26:29], v[164:167], v[204:207], v[26:29]
	v_mfma_f32_16x16x32_bf16 v[14:17], v[156:159], v[212:215], v[14:17]
	v_mfma_f32_16x16x32_bf16 v[10:13], v[164:167], v[212:215], v[10:13]
	s_setprio 0
	s_setprio 1
	v_mfma_f32_16x16x32_bf16 v[54:57], v[168:171], v[184:187], v[54:57]
	v_mfma_f32_16x16x32_bf16 v[50:53], v[176:179], v[184:187], v[50:53]
	v_mfma_f32_16x16x32_bf16 v[38:41], v[168:171], v[192:195], v[38:41]
	v_mfma_f32_16x16x32_bf16 v[34:37], v[176:179], v[192:195], v[34:37]
	v_mfma_f32_16x16x32_bf16 v[22:25], v[168:171], v[200:203], v[22:25]
	v_mfma_f32_16x16x32_bf16 v[18:21], v[176:179], v[200:203], v[18:21]
	v_mfma_f32_16x16x32_bf16 v[6:9], v[168:171], v[208:211], v[6:9]
	v_mfma_f32_16x16x32_bf16 v[2:5], v[176:179], v[208:211], v[2:5]
	v_mfma_f32_16x16x32_bf16 v[54:57], v[172:175], v[188:191], v[54:57]
	v_mfma_f32_16x16x32_bf16 v[50:53], v[180:183], v[188:191], v[50:53]
	v_mfma_f32_16x16x32_bf16 v[38:41], v[172:175], v[196:199], v[38:41]
	v_mfma_f32_16x16x32_bf16 v[34:37], v[180:183], v[196:199], v[34:37]
	v_mfma_f32_16x16x32_bf16 v[22:25], v[172:175], v[204:207], v[22:25]
	v_mfma_f32_16x16x32_bf16 v[18:21], v[180:183], v[204:207], v[18:21]
	v_mfma_f32_16x16x32_bf16 v[6:9], v[172:175], v[212:215], v[6:9]
	v_mfma_f32_16x16x32_bf16 v[2:5], v[180:183], v[212:215], v[2:5]
	s_setprio 0
	s_barrier
	s_add_i32 s55, s55, 2
	s_add_u32 s36, s36, 0x100
	s_addc_u32 s37, s37, 0
	s_add_u32 s53, s53, 0x100
	s_addc_u32 s54, s54, 0
	s_cmp_gt_u32 s55, 13
	s_cbranch_scc0 .LBB0_1948
	s_and_b64 vcc, exec, s[16:17]
	s_cbranch_vccz .LBB0_1951
	s_barrier

; #define PG8_STAGE(bufoff, gbase, voff) do { _Pragma("unroll") for (int _i = 0; _i < 2; ++_i) \
;         __builtin_amdgcn_global_load_lds((const unsigned*)((const char*)(gbase) + (voff)[_i]), (PG8_LAS unsigned*)(lds + (bufoff) + ldsw + _i * 8192), 16, 0, 0); } while (0)
; #define PG8_LDA(dst, b, h) do { _Pragma("unroll") for (int m = 0; m < 4; ++m) _Pragma("unroll") for (int k = 0; k < 2; ++k) dst[m][k] = *(const PG8_LAS bf16x8*)(lds + PG8_SA(b, h) + aoff + m * 2048 + k * 1024); } while (0)
; #define PG8_LDB(dst, b, h) do { _Pragma("unroll") for (int n = 0; n < 2; ++n) _Pragma("unroll") for (int k = 0; k < 2; ++k) dst[n][k] = *(const PG8_LAS bf16x8*)(lds + PG8_SB(b, h) + boff + n * 2048 + k * 1024); } while (0)
; #define PG8_MMA(ai, bj, At, Bt) do { __builtin_amdgcn_s_setprio(1); _Pragma("unroll") for (int m = 0; m < 4; ++m) _Pragma("unroll") for (int n = 0; n < 2; ++n) _Pragma("unroll") for (int k = 0; k < 2; ++k) \
;         acc[ai][bj][m][n] = __builtin_amdgcn_mfma_f32_16x16x32_bf16(Bt[n][k], At[m][k], acc[ai][bj][m][n], 0, 0, 0); __builtin_amdgcn_s_setprio(0); } while (0)
; #define PG8_WAIT_V(n) asm volatile("s_waitcnt vmcnt(" #n ")" ::: "memory")
; #define PG8_WAIT_L(n) asm volatile("s_waitcnt lgkmcnt(" #n ")" ::: "memory")
; #define PG8_BAR __builtin_amdgcn_s_barrier()
; #define PG8_SCHED __builtin_amdgcn_sched_barrier(0)
; template <class Epi, class Sched, bool ALIGN_EPI = false, bool SP2 = false>
; __device__ __forceinline__ void gemm_phase(PG8_LAS unsigned char* lds, const Gemm g, const Sched& S, const Epi& E) {
;     ...
;             PG8_LDB(B0, 0, 0); PG8_LDB(B1, 0, 1); PG8_SCHED; PG8_LDA(At, 0, 0); PG8_STAGE(PG8_SA(1, 1), a1 + hstep, voffA);
;             PG8_WAIT_V(8); PG8_WAIT_L(0); PG8_BAR; PG8_MMA(0, 0, At, B0); PG8_MMA(0, 1, At, B1); PG8_BAR; PG8_SCHED;
;             PG8_LDA(At, 0, 1); PG8_STAGE(PG8_SB(0, 0), b2, voffB); PG8_STAGE(PG8_SB(0, 1), b2 + hstep, voffB); PG8_STAGE(PG8_SA(0, 0), a2, voffA);
.LBB0_2086:
	ds_read_b128 v[166:169], v154
	ds_read_b128 v[170:173], v154 offset:1024
	ds_read_b128 v[174:177], v154 offset:2048
	ds_read_b128 v[178:181], v154 offset:3072
	ds_read_b128 v[182:185], v155
	ds_read_b128 v[186:189], v155 offset:1024
	ds_read_b128 v[190:193], v155 offset:2048
	ds_read_b128 v[194:197], v155 offset:3072
	s_add_u32 s26, s24, 0xfffc0080
	s_addc_u32 s27, s25, -1
	s_cmp_eq_u32 s54, 12
	s_cselect_b32 s35, s19, s27
	s_cselect_b32 s34, s50, s26
	s_cselect_b32 s27, s17, s53
	s_cselect_b32 s26, s51, s52
	v_lshl_add_u64 v[150:151], s[24:25], 0, v[138:139]
	s_add_i32 m0, s36, 0xc000
	ds_read_b128 v[198:201], v156
	ds_read_b128 v[202:205], v156 offset:1024
	ds_read_b128 v[206:209], v156 offset:2048
	ds_read_b128 v[210:213], v156 offset:3072
	ds_read_b128 v[214:217], v156 offset:4096
	ds_read_b128 v[218:221], v156 offset:5120
	ds_read_b128 v[222:225], v156 offset:6144
	ds_read_b128 v[226:229], v156 offset:7168
	global_load_lds_dwordx4 v[150:151], off
	v_lshl_add_u64 v[150:151], s[24:25], 0, v[140:141]
	s_add_i32 m0, s36, 0xe000
	s_nop 0
	global_load_lds_dwordx4 v[150:151], off
	s_waitcnt vmcnt(8)
	s_waitcnt lgkmcnt(0)
	s_barrier
	s_setprio 1
	v_mfma_f32_16x16x32_bf16 v[126:129], v[166:169], v[198:201], v[126:129]
	v_mfma_f32_16x16x32_bf16 v[122:125], v[174:177], v[198:201], v[122:125]
	v_mfma_f32_16x16x32_bf16 v[110:113], v[166:169], v[206:209], v[110:113]
	v_mfma_f32_16x16x32_bf16 v[106:109], v[174:177], v[206:209], v[106:109]
	v_mfma_f32_16x16x32_bf16 v[94:97], v[166:169], v[214:217], v[94:97]
	v_mfma_f32_16x16x32_bf16 v[90:93], v[174:177], v[214:217], v[90:93]
	v_mfma_f32_16x16x32_bf16 v[78:81], v[166:169], v[222:225], v[78:81]
	v_mfma_f32_16x16x32_bf16 v[74:77], v[174:177], v[222:225], v[74:77]
	v_mfma_f32_16x16x32_bf16 v[126:129], v[170:173], v[202:205], v[126:129]
	v_mfma_f32_16x16x32_bf16 v[122:125], v[178:181], v[202:205], v[122:125]
	v_mfma_f32_16x16x32_bf16 v[110:113], v[170:173], v[210:213], v[110:113]
	v_mfma_f32_16x16x32_bf16 v[106:109], v[178:181], v[210:213], v[106:109]
	v_mfma_f32_16x16x32_bf16 v[94:97], v[170:173], v[218:221], v[94:97]
	v_mfma_f32_16x16x32_bf16 v[90:93], v[178:181], v[218:221], v[90:93]
	v_mfma_f32_16x16x32_bf16 v[78:81], v[170:173], v[226:229], v[78:81]
	v_mfma_f32_16x16x32_bf16 v[74:77], v[178:181], v[226:229], v[74:77]
	s_setprio 0
	s_setprio 1
	v_mfma_f32_16x16x32_bf16 v[118:121], v[182:185], v[198:201], v[118:121]
	v_mfma_f32_16x16x32_bf16 v[114:117], v[190:193], v[198:201], v[114:117]
	v_mfma_f32_16x16x32_bf16 v[102:105], v[182:185], v[206:209], v[102:105]
	v_mfma_f32_16x16x32_bf16 v[98:101], v[190:193], v[206:209], v[98:101]
	v_mfma_f32_16x16x32_bf16 v[86:89], v[182:185], v[214:217], v[86:89]
	v_mfma_f32_16x16x32_bf16 v[82:85], v[190:193], v[214:217], v[82:85]
	v_mfma_f32_16x16x32_bf16 v[70:73], v[182:185], v[222:225], v[70:73]
	v_mfma_f32_16x16x32_bf16 v[66:69], v[190:193], v[222:225], v[66:69]
	v_mfma_f32_16x16x32_bf16 v[118:121], v[186:189], v[202:205], v[118:121]
	v_mfma_f32_16x16x32_bf16 v[114:117], v[194:197], v[202:205], v[114:117]
	v_mfma_f32_16x16x32_bf16 v[102:105], v[186:189], v[210:213], v[102:105]
	v_mfma_f32_16x16x32_bf16 v[98:101], v[194:197], v[210:213], v[98:101]
	v_mfma_f32_16x16x32_bf16 v[86:89], v[186:189], v[218:221], v[86:89]
	v_mfma_f32_16x16x32_bf16 v[82:85], v[194:197], v[218:221], v[82:85]
	v_mfma_f32_16x16x32_bf16 v[70:73], v[186:189], v[226:229], v[70:73]
	v_mfma_f32_16x16x32_bf16 v[66:69], v[194:197], v[226:229], v[66:69]
	s_setprio 0
	s_barrier
	s_add_i32 s55, s44, s3
	v_lshl_add_u64 v[150:151], s[26:27], 0, v[132:133]
	s_mov_b32 m0, s55
	ds_read_b128 v[198:201], v156 offset:16384
	ds_read_b128 v[202:205], v156 offset:17408
	ds_read_b128 v[206:209], v156 offset:18432
	ds_read_b128 v[210:213], v156 offset:19456
	ds_read_b128 v[214:217], v156 offset:20480
	ds_read_b128 v[218:221], v156 offset:21504
	ds_read_b128 v[222:225], v156 offset:22528
	ds_read_b128 v[226:229], v156 offset:23552
	global_load_lds_dwordx4 v[150:151], off
	s_add_i32 m0, s55, 0x2000
	s_add_u32 s56, s26, 0x40000
	v_lshl_add_u64 v[230:231], s[26:27], 0, v[136:137]
	s_addc_u32 s57, s27, 0
	s_add_i32 s55, s45, s3
	global_load_lds_dwordx4 v[230:231], off
	v_lshl_add_u64 v[232:233], s[56:57], 0, v[132:133]
	s_mov_b32 m0, s55
	v_lshl_add_u64 v[234:235], s[34:35], 0, v[134:135]
	global_load_lds_dwordx4 v[232:233], off
	v_lshl_add_u64 v[232:233], s[56:57], 0, v[136:137]
	s_add_i32 m0, s55, 0x2000
	s_nop 0
	global_load_lds_dwordx4 v[232:233], off
	v_lshl_add_u64 v[232:233], s[34:35], 0, v[130:131]
	s_mov_b32 m0, s36
	s_nop 0
	global_load_lds_dwordx4 v[232:233], off
	s_mov_b32 m0, s37
	s_nop 0
	global_load_lds_dwordx4 v[234:235], off
	s_waitcnt vmcnt(8)
	s_waitcnt lgkmcnt(0)
	s_barrier
; #define PG8_STAGE(bufoff, gbase, voff) do { _Pragma("unroll") for (int _i = 0; _i < 2; ++_i) \
;         __builtin_amdgcn_global_load_lds((const unsigned*)((const char*)(gbase) + (voff)[_i]), (PG8_LAS unsigned*)(lds + (bufoff) + ldsw + _i * 8192), 16, 0, 0); } while (0)
; #define PG8_LDA(dst, b, h) do { _Pragma("unroll") for (int m = 0; m < 4; ++m) _Pragma("unroll") for (int k = 0; k < 2; ++k) dst[m][k] = *(const PG8_LAS bf16x8*)(lds + PG8_SA(b, h) + aoff + m * 2048 + k * 1024); } while (0)
; #define PG8_LDB(dst, b, h) do { _Pragma("unroll") for (int n = 0; n < 2; ++n) _Pragma("unroll") for (int k = 0; k < 2; ++k) dst[n][k] = *(const PG8_LAS bf16x8*)(lds + PG8_SB(b, h) + boff + n * 2048 + k * 1024); } while (0)
; #define PG8_MMA(ai, bj, At, Bt) do { __builtin_amdgcn_s_setprio(1); _Pragma("unroll") for (int m = 0; m < 4; ++m) _Pragma("unroll") for (int n = 0; n < 2; ++n) _Pragma("unroll") for (int k = 0; k < 2; ++k) \
;         acc[ai][bj][m][n] = __builtin_amdgcn_mfma_f32_16x16x32_bf16(Bt[n][k], At[m][k], acc[ai][bj][m][n], 0, 0, 0); __builtin_amdgcn_s_setprio(0); } while (0)
; #define PG8_WAIT_V(n) asm volatile("s_waitcnt vmcnt(" #n ")" ::: "memory")
; #define PG8_WAIT_L(n) asm volatile("s_waitcnt lgkmcnt(" #n ")" ::: "memory")
; #define PG8_BAR __builtin_amdgcn_s_barrier()
; #define PG8_SCHED __builtin_amdgcn_sched_barrier(0)
; template <class Epi, class Sched, bool ALIGN_EPI = false, bool SP2 = false>
; __device__ __forceinline__ void gemm_phase(PG8_LAS unsigned char* lds, const Gemm g, const Sched& S, const Epi& E) {
;     ...
;             PG8_WAIT_V(8); PG8_WAIT_L(0); PG8_BAR; PG8_MMA(1, 0, At, B0); PG8_MMA(1, 1, At, B1); PG8_BAR; PG8_SCHED;
;             PG8_LDB(B0, 1, 0); PG8_LDB(B1, 1, 1); PG8_SCHED; PG8_LDA(At, 1, 0); PG8_STAGE(PG8_SA(0, 1), a2 + hstep, voffA);
;             PG8_WAIT_V(8); PG8_WAIT_L(0); PG8_BAR; PG8_MMA(0, 0, At, B0); PG8_MMA(0, 1, At, B1); PG8_BAR; PG8_SCHED;
	s_setprio 1
	v_mfma_f32_16x16x32_bf16 v[62:65], v[166:169], v[198:201], v[62:65]
	v_mfma_f32_16x16x32_bf16 v[58:61], v[174:177], v[198:201], v[58:61]
	v_mfma_f32_16x16x32_bf16 v[46:49], v[166:169], v[206:209], v[46:49]
	v_mfma_f32_16x16x32_bf16 v[42:45], v[174:177], v[206:209], v[42:45]
	v_mfma_f32_16x16x32_bf16 v[30:33], v[166:169], v[214:217], v[30:33]
	v_mfma_f32_16x16x32_bf16 v[26:29], v[174:177], v[214:217], v[26:29]
	v_mfma_f32_16x16x32_bf16 v[14:17], v[166:169], v[222:225], v[14:17]
	v_mfma_f32_16x16x32_bf16 v[10:13], v[174:177], v[222:225], v[10:13]
	v_mfma_f32_16x16x32_bf16 v[62:65], v[170:173], v[202:205], v[62:65]
	v_mfma_f32_16x16x32_bf16 v[58:61], v[178:181], v[202:205], v[58:61]
	v_mfma_f32_16x16x32_bf16 v[46:49], v[170:173], v[210:213], v[46:49]
	v_mfma_f32_16x16x32_bf16 v[42:45], v[178:181], v[210:213], v[42:45]
	v_mfma_f32_16x16x32_bf16 v[30:33], v[170:173], v[218:221], v[30:33]
	v_mfma_f32_16x16x32_bf16 v[26:29], v[178:181], v[218:221], v[26:29]
	v_mfma_f32_16x16x32_bf16 v[14:17], v[170:173], v[226:229], v[14:17]
	v_mfma_f32_16x16x32_bf16 v[10:13], v[178:181], v[226:229], v[10:13]
	s_setprio 0
	s_setprio 1
	v_mfma_f32_16x16x32_bf16 v[54:57], v[182:185], v[198:201], v[54:57]
	v_mfma_f32_16x16x32_bf16 v[50:53], v[190:193], v[198:201], v[50:53]
	v_mfma_f32_16x16x32_bf16 v[38:41], v[182:185], v[206:209], v[38:41]
	v_mfma_f32_16x16x32_bf16 v[34:37], v[190:193], v[206:209], v[34:37]
	v_mfma_f32_16x16x32_bf16 v[22:25], v[182:185], v[214:217], v[22:25]
	v_mfma_f32_16x16x32_bf16 v[18:21], v[190:193], v[214:217], v[18:21]
	v_mfma_f32_16x16x32_bf16 v[6:9], v[182:185], v[222:225], v[6:9]
	v_mfma_f32_16x16x32_bf16 v[2:5], v[190:193], v[222:225], v[2:5]
	v_mfma_f32_16x16x32_bf16 v[54:57], v[186:189], v[202:205], v[54:57]
	v_mfma_f32_16x16x32_bf16 v[50:53], v[194:197], v[202:205], v[50:53]
	v_mfma_f32_16x16x32_bf16 v[38:41], v[186:189], v[210:213], v[38:41]
	v_mfma_f32_16x16x32_bf16 v[34:37], v[194:197], v[210:213], v[34:37]
	v_mfma_f32_16x16x32_bf16 v[22:25], v[186:189], v[218:221], v[22:25]
	v_mfma_f32_16x16x32_bf16 v[18:21], v[194:197], v[218:221], v[18:21]
	v_mfma_f32_16x16x32_bf16 v[6:9], v[186:189], v[226:229], v[6:9]
	v_mfma_f32_16x16x32_bf16 v[2:5], v[194:197], v[226:229], v[2:5]
	s_setprio 0
	s_barrier
	s_add_i32 s55, 0, 0x18000
	v_add_u32_e32 v149, s55, v152
	s_add_i32 s56, 0, 0x1c000
	ds_read_b128 v[166:169], v149
	ds_read_b128 v[170:173], v149 offset:1024
	ds_read_b128 v[174:177], v149 offset:2048
	ds_read_b128 v[178:181], v149 offset:3072
	v_add_u32_e32 v149, s56, v152
	ds_read_b128 v[182:185], v149
	ds_read_b128 v[186:189], v149 offset:1024
	ds_read_b128 v[190:193], v149 offset:2048
	ds_read_b128 v[194:197], v149 offset:3072
	s_add_u32 s34, s34, 0x40000
	s_addc_u32 s35, s35, 0
	s_mov_b32 m0, s38
	v_lshl_add_u64 v[236:237], s[34:35], 0, v[130:131]
	ds_read_b128 v[198:201], v156 offset:32768
	ds_read_b128 v[202:205], v156 offset:33792
	ds_read_b128 v[206:209], v156 offset:34816
	ds_read_b128 v[210:213], v156 offset:35840
	ds_read_b128 v[214:217], v156 offset:36864
	ds_read_b128 v[218:221], v156 offset:37888
	ds_read_b128 v[222:225], v156 offset:38912
	ds_read_b128 v[226:229], v156 offset:39936
	global_load_lds_dwordx4 v[236:237], off
	v_lshl_add_u64 v[236:237], s[34:35], 0, v[134:135]
	s_mov_b32 m0, s39
	s_nop 0
	global_load_lds_dwordx4 v[236:237], off
	s_waitcnt vmcnt(8)
	s_waitcnt lgkmcnt(0)
	s_barrier
	s_setprio 1
	v_mfma_f32_16x16x32_bf16 v[126:129], v[166:169], v[198:201], v[126:129]
	v_mfma_f32_16x16x32_bf16 v[122:125], v[174:177], v[198:201], v[122:125]
	v_mfma_f32_16x16x32_bf16 v[110:113], v[166:169], v[206:209], v[110:113]
	v_mfma_f32_16x16x32_bf16 v[106:109], v[174:177], v[206:209], v[106:109]
	v_mfma_f32_16x16x32_bf16 v[94:97], v[166:169], v[214:217], v[94:97]
	v_mfma_f32_16x16x32_bf16 v[90:93], v[174:177], v[214:217], v[90:93]
	v_mfma_f32_16x16x32_bf16 v[78:81], v[166:169], v[222:225], v[78:81]
	v_mfma_f32_16x16x32_bf16 v[74:77], v[174:177], v[222:225], v[74:77]
	v_mfma_f32_16x16x32_bf16 v[126:129], v[170:173], v[202:205], v[126:129]
	v_mfma_f32_16x16x32_bf16 v[122:125], v[178:181], v[202:205], v[122:125]
	v_mfma_f32_16x16x32_bf16 v[110:113], v[170:173], v[210:213], v[110:113]
	v_mfma_f32_16x16x32_bf16 v[106:109], v[178:181], v[210:213], v[106:109]
	v_mfma_f32_16x16x32_bf16 v[94:97], v[170:173], v[218:221], v[94:97]
	v_mfma_f32_16x16x32_bf16 v[90:93], v[178:181], v[218:221], v[90:93]
	v_mfma_f32_16x16x32_bf16 v[78:81], v[170:173], v[226:229], v[78:81]
	v_mfma_f32_16x16x32_bf16 v[74:77], v[178:181], v[226:229], v[74:77]
	s_setprio 0
	s_setprio 1
	v_mfma_f32_16x16x32_bf16 v[118:121], v[182:185], v[198:201], v[118:121]
	v_mfma_f32_16x16x32_bf16 v[114:117], v[190:193], v[198:201], v[114:117]
	v_mfma_f32_16x16x32_bf16 v[102:105], v[182:185], v[206:209], v[102:105]
	v_mfma_f32_16x16x32_bf16 v[98:101], v[190:193], v[206:209], v[98:101]
	v_mfma_f32_16x16x32_bf16 v[86:89], v[182:185], v[214:217], v[86:89]
	v_mfma_f32_16x16x32_bf16 v[82:85], v[190:193], v[214:217], v[82:85]
	v_mfma_f32_16x16x32_bf16 v[70:73], v[182:185], v[222:225], v[70:73]
	v_mfma_f32_16x16x32_bf16 v[66:69], v[190:193], v[222:225], v[66:69]
	v_mfma_f32_16x16x32_bf16 v[118:121], v[186:189], v[202:205], v[118:121]
	v_mfma_f32_16x16x32_bf16 v[114:117], v[194:197], v[202:205], v[114:117]
	v_mfma_f32_16x16x32_bf16 v[102:105], v[186:189], v[210:213], v[102:105]
	v_mfma_f32_16x16x32_bf16 v[98:101], v[194:197], v[210:213], v[98:101]
	v_mfma_f32_16x16x32_bf16 v[86:89], v[186:189], v[218:221], v[86:89]
	v_mfma_f32_16x16x32_bf16 v[82:85], v[194:197], v[218:221], v[82:85]
	v_mfma_f32_16x16x32_bf16 v[70:73], v[186:189], v[226:229], v[70:73]
	v_mfma_f32_16x16x32_bf16 v[66:69], v[194:197], v[226:229], v[66:69]
	s_setprio 0
	s_barrier
; #define PG8_STAGE(bufoff, gbase, voff) do { _Pragma("unroll") for (int _i = 0; _i < 2; ++_i) \
;         __builtin_amdgcn_global_load_lds((const unsigned*)((const char*)(gbase) + (voff)[_i]), (PG8_LAS unsigned*)(lds + (bufoff) + ldsw + _i * 8192), 16, 0, 0); } while (0)
; #define PG8_LDA(dst, b, h) do { _Pragma("unroll") for (int m = 0; m < 4; ++m) _Pragma("unroll") for (int k = 0; k < 2; ++k) dst[m][k] = *(const PG8_LAS bf16x8*)(lds + PG8_SA(b, h) + aoff + m * 2048 + k * 1024); } while (0)
; #define PG8_MMA(ai, bj, At, Bt) do { __builtin_amdgcn_s_setprio(1); _Pragma("unroll") for (int m = 0; m < 4; ++m) _Pragma("unroll") for (int n = 0; n < 2; ++n) _Pragma("unroll") for (int k = 0; k < 2; ++k) \
;         acc[ai][bj][m][n] = __builtin_amdgcn_mfma_f32_16x16x32_bf16(Bt[n][k], At[m][k], acc[ai][bj][m][n], 0, 0, 0); __builtin_amdgcn_s_setprio(0); } while (0)
; #define PG8_WAIT_V(n) asm volatile("s_waitcnt vmcnt(" #n ")" ::: "memory")
; #define PG8_WAIT_L(n) asm volatile("s_waitcnt lgkmcnt(" #n ")" ::: "memory")
; #define PG8_BAR __builtin_amdgcn_s_barrier()
; #define PG8_SCHED __builtin_amdgcn_sched_barrier(0)
; template <class Epi, class Sched, bool ALIGN_EPI = false, bool SP2 = false>
; __device__ __forceinline__ void gemm_phase(PG8_LAS unsigned char* lds, const Gemm g, const Sched& S, const Epi& E) {
;     ...
;         for (int t = 0; t < nt; t += 2) {
;             const bool last = (t == nt - 2);
;             const char* a1 = cA + (size_t)(t + 1) * kstep;
;             const char* a2 = last ? nA : cA + (size_t)(t + 2) * kstep; const char* b2 = last ? nB : cB + (size_t)(t + 2) * kstep;
;     ...
;             PG8_LDA(At, 1, 1); PG8_STAGE(PG8_SB(1, 0), b3, voffB); PG8_STAGE(PG8_SB(1, 1), b3 + hstep, voffB); PG8_STAGE(PG8_SA(1, 0), a3, voffA);
;             PG8_WAIT_V(8); PG8_WAIT_L(0); PG8_BAR; PG8_MMA(1, 0, At, B0); PG8_MMA(1, 1, At, B1); PG8_BAR; PG8_SCHED;
	s_add_i32 s34, s55, s3
	v_lshl_add_u64 v[150:151], v[150:151], 0, s[12:13]
	s_mov_b32 m0, s34
	ds_read_b128 v[198:201], v156 offset:49152
	ds_read_b128 v[202:205], v156 offset:50176
	ds_read_b128 v[206:209], v156 offset:51200
	ds_read_b128 v[210:213], v156 offset:52224
	ds_read_b128 v[214:217], v156 offset:53248
	ds_read_b128 v[218:221], v156 offset:54272
	ds_read_b128 v[222:225], v156 offset:55296
	ds_read_b128 v[226:229], v156 offset:56320
	global_load_lds_dwordx4 v[150:151], off
	s_add_i32 m0, s34, 0x2000
	s_add_u32 s26, s26, 0x40080
	v_lshl_add_u64 v[150:151], v[230:231], 0, s[12:13]
	s_addc_u32 s27, s27, 0
	s_add_i32 s34, s56, s3
	global_load_lds_dwordx4 v[150:151], off
	v_lshl_add_u64 v[150:151], s[26:27], 0, v[132:133]
	s_mov_b32 m0, s34
	s_nop 0
	global_load_lds_dwordx4 v[150:151], off
	v_lshl_add_u64 v[150:151], s[26:27], 0, v[136:137]
	s_add_i32 m0, s34, 0x2000
	s_nop 0
	global_load_lds_dwordx4 v[150:151], off
	v_lshl_add_u64 v[150:151], v[232:233], 0, s[12:13]
	s_mov_b32 m0, s41
	s_nop 0
	global_load_lds_dwordx4 v[150:151], off
	v_lshl_add_u64 v[150:151], v[234:235], 0, s[12:13]
	s_mov_b32 m0, s42
	s_nop 0
	global_load_lds_dwordx4 v[150:151], off
	s_waitcnt vmcnt(8)
	s_waitcnt lgkmcnt(0)
	s_barrier
	s_setprio 1
	v_mfma_f32_16x16x32_bf16 v[62:65], v[166:169], v[198:201], v[62:65]
	v_mfma_f32_16x16x32_bf16 v[58:61], v[174:177], v[198:201], v[58:61]
	v_mfma_f32_16x16x32_bf16 v[46:49], v[166:169], v[206:209], v[46:49]
	v_mfma_f32_16x16x32_bf16 v[42:45], v[174:177], v[206:209], v[42:45]
	v_mfma_f32_16x16x32_bf16 v[30:33], v[166:169], v[214:217], v[30:33]
	v_mfma_f32_16x16x32_bf16 v[26:29], v[174:177], v[214:217], v[26:29]
	v_mfma_f32_16x16x32_bf16 v[14:17], v[166:169], v[222:225], v[14:17]
	v_mfma_f32_16x16x32_bf16 v[10:13], v[174:177], v[222:225], v[10:13]
	v_mfma_f32_16x16x32_bf16 v[62:65], v[170:173], v[202:205], v[62:65]
	v_mfma_f32_16x16x32_bf16 v[58:61], v[178:181], v[202:205], v[58:61]
	v_mfma_f32_16x16x32_bf16 v[46:49], v[170:173], v[210:213], v[46:49]
	v_mfma_f32_16x16x32_bf16 v[42:45], v[178:181], v[210:213], v[42:45]
	v_mfma_f32_16x16x32_bf16 v[30:33], v[170:173], v[218:221], v[30:33]
	v_mfma_f32_16x16x32_bf16 v[26:29], v[178:181], v[218:221], v[26:29]
	v_mfma_f32_16x16x32_bf16 v[14:17], v[170:173], v[226:229], v[14:17]
	v_mfma_f32_16x16x32_bf16 v[10:13], v[178:181], v[226:229], v[10:13]
	s_setprio 0
	s_setprio 1
	v_mfma_f32_16x16x32_bf16 v[54:57], v[182:185], v[198:201], v[54:57]
	v_mfma_f32_16x16x32_bf16 v[50:53], v[190:193], v[198:201], v[50:53]
	v_mfma_f32_16x16x32_bf16 v[38:41], v[182:185], v[206:209], v[38:41]
	v_mfma_f32_16x16x32_bf16 v[34:37], v[190:193], v[206:209], v[34:37]
	v_mfma_f32_16x16x32_bf16 v[22:25], v[182:185], v[214:217], v[22:25]
	v_mfma_f32_16x16x32_bf16 v[18:21], v[190:193], v[214:217], v[18:21]
	v_mfma_f32_16x16x32_bf16 v[6:9], v[182:185], v[222:225], v[6:9]
	v_mfma_f32_16x16x32_bf16 v[2:5], v[190:193], v[222:225], v[2:5]
	v_mfma_f32_16x16x32_bf16 v[54:57], v[186:189], v[202:205], v[54:57]
	v_mfma_f32_16x16x32_bf16 v[50:53], v[194:197], v[202:205], v[50:53]
	v_mfma_f32_16x16x32_bf16 v[38:41], v[186:189], v[210:213], v[38:41]
	v_mfma_f32_16x16x32_bf16 v[34:37], v[194:197], v[210:213], v[34:37]
	v_mfma_f32_16x16x32_bf16 v[22:25], v[186:189], v[218:221], v[22:25]
	v_mfma_f32_16x16x32_bf16 v[18:21], v[194:197], v[218:221], v[18:21]
	v_mfma_f32_16x16x32_bf16 v[6:9], v[186:189], v[226:229], v[6:9]
	v_mfma_f32_16x16x32_bf16 v[2:5], v[194:197], v[226:229], v[2:5]
	s_setprio 0
	s_barrier
	s_add_i32 s54, s54, 2
	s_add_u32 s24, s24, 0x100
	s_addc_u32 s25, s25, 0
	s_add_u32 s52, s52, 0x100
	s_addc_u32 s53, s53, 0
	s_cmp_gt_u32 s54, 13
	s_cbranch_scc0 .LBB0_2086
	s_and_b64 vcc, exec, s[14:15]
	s_cbranch_vccz .LBB0_2089
	s_barrier

; #define PG8_STAGE(bufoff, gbase, voff) do { _Pragma("unroll") for (int _i = 0; _i < 2; ++_i) \
;         __builtin_amdgcn_global_load_lds((const unsigned*)((const char*)(gbase) + (voff)[_i]), (PG8_LAS unsigned*)(lds + (bufoff) + ldsw + _i * 8192), 16, 0, 0); } while (0)
; #define PG8_LDA(dst, b, h) do { _Pragma("unroll") for (int m = 0; m < 4; ++m) _Pragma("unroll") for (int k = 0; k < 2; ++k) dst[m][k] = *(const PG8_LAS bf16x8*)(lds + PG8_SA(b, h) + aoff + m * 2048 + k * 1024); } while (0)
; #define PG8_LDB(dst, b, h) do { _Pragma("unroll") for (int n = 0; n < 2; ++n) _Pragma("unroll") for (int k = 0; k < 2; ++k) dst[n][k] = *(const PG8_LAS bf16x8*)(lds + PG8_SB(b, h) + boff + n * 2048 + k * 1024); } while (0)
; #define PG8_MMA(ai, bj, At, Bt) do { __builtin_amdgcn_s_setprio(1); _Pragma("unroll") for (int m = 0; m < 4; ++m) _Pragma("unroll") for (int n = 0; n < 2; ++n) _Pragma("unroll") for (int k = 0; k < 2; ++k) \
;         acc[ai][bj][m][n] = __builtin_amdgcn_mfma_f32_16x16x32_bf16(Bt[n][k], At[m][k], acc[ai][bj][m][n], 0, 0, 0); __builtin_amdgcn_s_setprio(0); } while (0)
; #define PG8_WAIT_V(n) asm volatile("s_waitcnt vmcnt(" #n ")" ::: "memory")
; #define PG8_WAIT_L(n) asm volatile("s_waitcnt lgkmcnt(" #n ")" ::: "memory")
; #define PG8_BAR __builtin_amdgcn_s_barrier()
; #define PG8_SCHED __builtin_amdgcn_sched_barrier(0)
; template <class Epi, class Sched, bool ALIGN_EPI = false, bool SP2 = false>
; __device__ __forceinline__ void gemm_phase(PG8_LAS unsigned char* lds, const Gemm g, const Sched& S, const Epi& E) {
;     ...
;             PG8_LDB(B0, 0, 0); PG8_LDB(B1, 0, 1); PG8_SCHED; PG8_LDA(At, 0, 0); PG8_STAGE(PG8_SA(1, 1), a1 + hstep, voffA);
;             PG8_WAIT_V(8); PG8_WAIT_L(0); PG8_BAR; PG8_MMA(0, 0, At, B0); PG8_MMA(0, 1, At, B1); PG8_BAR; PG8_SCHED;
;             PG8_LDA(At, 0, 1); PG8_STAGE(PG8_SB(0, 0), b2, voffB); PG8_STAGE(PG8_SB(0, 1), b2 + hstep, voffB); PG8_STAGE(PG8_SA(0, 0), a2, voffA);
.LBB0_2176:
	ds_read_b128 v[146:149], v154
	ds_read_b128 v[158:161], v154 offset:1024
	ds_read_b128 v[162:165], v154 offset:2048
	ds_read_b128 v[166:169], v154 offset:3072
	ds_read_b128 v[170:173], v155
	ds_read_b128 v[174:177], v155 offset:1024
	ds_read_b128 v[178:181], v155 offset:2048
	ds_read_b128 v[182:185], v155 offset:3072
	s_add_u32 s40, s38, 0xfff80080
	s_addc_u32 s41, s39, -1
	s_cmp_eq_u32 s58, 28
	s_cselect_b32 s43, s25, s41
	s_cselect_b32 s42, s54, s40
	s_cselect_b32 s41, s23, s57
	s_cselect_b32 s40, s55, s56
	v_lshl_add_u64 v[150:151], s[38:39], 0, v[138:139]
	s_add_i32 m0, s37, 0xc000
	ds_read_b128 v[186:189], v156
	ds_read_b128 v[190:193], v156 offset:1024
	ds_read_b128 v[194:197], v156 offset:2048
	ds_read_b128 v[198:201], v156 offset:3072
	ds_read_b128 v[202:205], v156 offset:4096
	ds_read_b128 v[206:209], v156 offset:5120
	ds_read_b128 v[210:213], v156 offset:6144
	ds_read_b128 v[214:217], v156 offset:7168
	global_load_lds_dwordx4 v[150:151], off
	v_lshl_add_u64 v[150:151], s[38:39], 0, v[140:141]
	s_add_i32 m0, s37, 0xe000
	s_nop 0
	global_load_lds_dwordx4 v[150:151], off
	s_waitcnt vmcnt(8)
	s_waitcnt lgkmcnt(0)
	s_barrier
	s_setprio 1
	v_mfma_f32_16x16x32_bf16 v[126:129], v[146:149], v[186:189], v[126:129]
	v_mfma_f32_16x16x32_bf16 v[122:125], v[162:165], v[186:189], v[122:125]
	v_mfma_f32_16x16x32_bf16 v[110:113], v[146:149], v[194:197], v[110:113]
	v_mfma_f32_16x16x32_bf16 v[106:109], v[162:165], v[194:197], v[106:109]
	v_mfma_f32_16x16x32_bf16 v[94:97], v[146:149], v[202:205], v[94:97]
	v_mfma_f32_16x16x32_bf16 v[90:93], v[162:165], v[202:205], v[90:93]
	v_mfma_f32_16x16x32_bf16 v[78:81], v[146:149], v[210:213], v[78:81]
	v_mfma_f32_16x16x32_bf16 v[74:77], v[162:165], v[210:213], v[74:77]
	v_mfma_f32_16x16x32_bf16 v[126:129], v[158:161], v[190:193], v[126:129]
	v_mfma_f32_16x16x32_bf16 v[122:125], v[166:169], v[190:193], v[122:125]
	v_mfma_f32_16x16x32_bf16 v[110:113], v[158:161], v[198:201], v[110:113]
	v_mfma_f32_16x16x32_bf16 v[106:109], v[166:169], v[198:201], v[106:109]
	v_mfma_f32_16x16x32_bf16 v[94:97], v[158:161], v[206:209], v[94:97]
	v_mfma_f32_16x16x32_bf16 v[90:93], v[166:169], v[206:209], v[90:93]
	v_mfma_f32_16x16x32_bf16 v[78:81], v[158:161], v[214:217], v[78:81]
	v_mfma_f32_16x16x32_bf16 v[74:77], v[166:169], v[214:217], v[74:77]
	s_setprio 0
	s_setprio 1
	v_mfma_f32_16x16x32_bf16 v[118:121], v[170:173], v[186:189], v[118:121]
	v_mfma_f32_16x16x32_bf16 v[114:117], v[178:181], v[186:189], v[114:117]
	v_mfma_f32_16x16x32_bf16 v[102:105], v[170:173], v[194:197], v[102:105]
	v_mfma_f32_16x16x32_bf16 v[98:101], v[178:181], v[194:197], v[98:101]
	v_mfma_f32_16x16x32_bf16 v[86:89], v[170:173], v[202:205], v[86:89]
	v_mfma_f32_16x16x32_bf16 v[82:85], v[178:181], v[202:205], v[82:85]
	v_mfma_f32_16x16x32_bf16 v[70:73], v[170:173], v[210:213], v[70:73]
	v_mfma_f32_16x16x32_bf16 v[66:69], v[178:181], v[210:213], v[66:69]
	v_mfma_f32_16x16x32_bf16 v[118:121], v[174:177], v[190:193], v[118:121]
	v_mfma_f32_16x16x32_bf16 v[114:117], v[182:185], v[190:193], v[114:117]
	v_mfma_f32_16x16x32_bf16 v[102:105], v[174:177], v[198:201], v[102:105]
	v_mfma_f32_16x16x32_bf16 v[98:101], v[182:185], v[198:201], v[98:101]
	v_mfma_f32_16x16x32_bf16 v[86:89], v[174:177], v[206:209], v[86:89]
	v_mfma_f32_16x16x32_bf16 v[82:85], v[182:185], v[206:209], v[82:85]
	v_mfma_f32_16x16x32_bf16 v[70:73], v[174:177], v[214:217], v[70:73]
	v_mfma_f32_16x16x32_bf16 v[66:69], v[182:185], v[214:217], v[66:69]
	s_setprio 0
	s_barrier
	s_add_i32 s59, s51, s3
	v_lshl_add_u64 v[150:151], s[40:41], 0, v[132:133]
	s_mov_b32 m0, s59
	ds_read_b128 v[186:189], v156 offset:16384
	ds_read_b128 v[190:193], v156 offset:17408
	ds_read_b128 v[194:197], v156 offset:18432
	ds_read_b128 v[198:201], v156 offset:19456
	ds_read_b128 v[202:205], v156 offset:20480
	ds_read_b128 v[206:209], v156 offset:21504
	ds_read_b128 v[210:213], v156 offset:22528
	ds_read_b128 v[214:217], v156 offset:23552
	global_load_lds_dwordx4 v[150:151], off
	s_add_i32 m0, s59, 0x2000
	s_add_u32 s60, s40, 0x80000
	v_lshl_add_u64 v[218:219], s[40:41], 0, v[136:137]
	s_addc_u32 s61, s41, 0
	s_add_i32 s59, s52, s3
	global_load_lds_dwordx4 v[218:219], off
	v_lshl_add_u64 v[220:221], s[60:61], 0, v[132:133]
	s_mov_b32 m0, s59
	v_lshl_add_u64 v[222:223], s[42:43], 0, v[134:135]
	global_load_lds_dwordx4 v[220:221], off
	v_lshl_add_u64 v[220:221], s[60:61], 0, v[136:137]
	s_add_i32 m0, s59, 0x2000
	s_nop 0
	global_load_lds_dwordx4 v[220:221], off
	v_lshl_add_u64 v[220:221], s[42:43], 0, v[130:131]
	s_mov_b32 m0, s37
	s_nop 0
	global_load_lds_dwordx4 v[220:221], off
	s_mov_b32 m0, s44
	s_nop 0
	global_load_lds_dwordx4 v[222:223], off
	s_waitcnt vmcnt(8)
	s_waitcnt lgkmcnt(0)
	s_barrier
; #define PG8_STAGE(bufoff, gbase, voff) do { _Pragma("unroll") for (int _i = 0; _i < 2; ++_i) \
;         __builtin_amdgcn_global_load_lds((const unsigned*)((const char*)(gbase) + (voff)[_i]), (PG8_LAS unsigned*)(lds + (bufoff) + ldsw + _i * 8192), 16, 0, 0); } while (0)
; #define PG8_LDA(dst, b, h) do { _Pragma("unroll") for (int m = 0; m < 4; ++m) _Pragma("unroll") for (int k = 0; k < 2; ++k) dst[m][k] = *(const PG8_LAS bf16x8*)(lds + PG8_SA(b, h) + aoff + m * 2048 + k * 1024); } while (0)
; #define PG8_LDB(dst, b, h) do { _Pragma("unroll") for (int n = 0; n < 2; ++n) _Pragma("unroll") for (int k = 0; k < 2; ++k) dst[n][k] = *(const PG8_LAS bf16x8*)(lds + PG8_SB(b, h) + boff + n * 2048 + k * 1024); } while (0)
; #define PG8_MMA(ai, bj, At, Bt) do { __builtin_amdgcn_s_setprio(1); _Pragma("unroll") for (int m = 0; m < 4; ++m) _Pragma("unroll") for (int n = 0; n < 2; ++n) _Pragma("unroll") for (int k = 0; k < 2; ++k) \
;         acc[ai][bj][m][n] = __builtin_amdgcn_mfma_f32_16x16x32_bf16(Bt[n][k], At[m][k], acc[ai][bj][m][n], 0, 0, 0); __builtin_amdgcn_s_setprio(0); } while (0)
; #define PG8_WAIT_V(n) asm volatile("s_waitcnt vmcnt(" #n ")" ::: "memory")
; #define PG8_WAIT_L(n) asm volatile("s_waitcnt lgkmcnt(" #n ")" ::: "memory")
; #define PG8_BAR __builtin_amdgcn_s_barrier()
; #define PG8_SCHED __builtin_amdgcn_sched_barrier(0)
; template <class Epi, class Sched, bool ALIGN_EPI = false, bool SP2 = false>
; __device__ __forceinline__ void gemm_phase(PG8_LAS unsigned char* lds, const Gemm g, const Sched& S, const Epi& E) {
;     ...
;             PG8_WAIT_V(8); PG8_WAIT_L(0); PG8_BAR; PG8_MMA(1, 0, At, B0); PG8_MMA(1, 1, At, B1); PG8_BAR; PG8_SCHED;
;             PG8_LDB(B0, 1, 0); PG8_LDB(B1, 1, 1); PG8_SCHED; PG8_LDA(At, 1, 0); PG8_STAGE(PG8_SA(0, 1), a2 + hstep, voffA);
;             PG8_WAIT_V(8); PG8_WAIT_L(0); PG8_BAR; PG8_MMA(0, 0, At, B0); PG8_MMA(0, 1, At, B1); PG8_BAR; PG8_SCHED;
	s_setprio 1
	v_mfma_f32_16x16x32_bf16 v[62:65], v[146:149], v[186:189], v[62:65]
	v_mfma_f32_16x16x32_bf16 v[58:61], v[162:165], v[186:189], v[58:61]
	v_mfma_f32_16x16x32_bf16 v[46:49], v[146:149], v[194:197], v[46:49]
	v_mfma_f32_16x16x32_bf16 v[42:45], v[162:165], v[194:197], v[42:45]
	v_mfma_f32_16x16x32_bf16 v[30:33], v[146:149], v[202:205], v[30:33]
	v_mfma_f32_16x16x32_bf16 v[26:29], v[162:165], v[202:205], v[26:29]
	v_mfma_f32_16x16x32_bf16 v[14:17], v[146:149], v[210:213], v[14:17]
	v_mfma_f32_16x16x32_bf16 v[10:13], v[162:165], v[210:213], v[10:13]
	v_mfma_f32_16x16x32_bf16 v[62:65], v[158:161], v[190:193], v[62:65]
	v_mfma_f32_16x16x32_bf16 v[58:61], v[166:169], v[190:193], v[58:61]
	v_mfma_f32_16x16x32_bf16 v[46:49], v[158:161], v[198:201], v[46:49]
	v_mfma_f32_16x16x32_bf16 v[42:45], v[166:169], v[198:201], v[42:45]
	v_mfma_f32_16x16x32_bf16 v[30:33], v[158:161], v[206:209], v[30:33]
	v_mfma_f32_16x16x32_bf16 v[26:29], v[166:169], v[206:209], v[26:29]
	v_mfma_f32_16x16x32_bf16 v[14:17], v[158:161], v[214:217], v[14:17]
	v_mfma_f32_16x16x32_bf16 v[10:13], v[166:169], v[214:217], v[10:13]
	s_setprio 0
	s_setprio 1
	v_mfma_f32_16x16x32_bf16 v[54:57], v[170:173], v[186:189], v[54:57]
	v_mfma_f32_16x16x32_bf16 v[50:53], v[178:181], v[186:189], v[50:53]
	v_mfma_f32_16x16x32_bf16 v[38:41], v[170:173], v[194:197], v[38:41]
	v_mfma_f32_16x16x32_bf16 v[34:37], v[178:181], v[194:197], v[34:37]
	v_mfma_f32_16x16x32_bf16 v[22:25], v[170:173], v[202:205], v[22:25]
	v_mfma_f32_16x16x32_bf16 v[18:21], v[178:181], v[202:205], v[18:21]
	v_mfma_f32_16x16x32_bf16 v[6:9], v[170:173], v[210:213], v[6:9]
	v_mfma_f32_16x16x32_bf16 v[2:5], v[178:181], v[210:213], v[2:5]
	v_mfma_f32_16x16x32_bf16 v[54:57], v[174:177], v[190:193], v[54:57]
	v_mfma_f32_16x16x32_bf16 v[50:53], v[182:185], v[190:193], v[50:53]
	v_mfma_f32_16x16x32_bf16 v[38:41], v[174:177], v[198:201], v[38:41]
	v_mfma_f32_16x16x32_bf16 v[34:37], v[182:185], v[198:201], v[34:37]
	v_mfma_f32_16x16x32_bf16 v[22:25], v[174:177], v[206:209], v[22:25]
	v_mfma_f32_16x16x32_bf16 v[18:21], v[182:185], v[206:209], v[18:21]
	v_mfma_f32_16x16x32_bf16 v[6:9], v[174:177], v[214:217], v[6:9]
	v_mfma_f32_16x16x32_bf16 v[2:5], v[182:185], v[214:217], v[2:5]
	s_setprio 0
	s_barrier
	s_add_i32 s59, 0, 0x18000
	v_add_u32_e32 v157, s59, v152
	s_add_i32 s60, 0, 0x1c000
	ds_read_b128 v[146:149], v157
	ds_read_b128 v[158:161], v157 offset:1024
	ds_read_b128 v[162:165], v157 offset:2048
	ds_read_b128 v[166:169], v157 offset:3072
	v_add_u32_e32 v157, s60, v152
	ds_read_b128 v[170:173], v157
	ds_read_b128 v[174:177], v157 offset:1024
	ds_read_b128 v[178:181], v157 offset:2048
	ds_read_b128 v[182:185], v157 offset:3072
	s_add_u32 s42, s42, 0x80000
	s_addc_u32 s43, s43, 0
	s_mov_b32 m0, s45
	v_lshl_add_u64 v[224:225], s[42:43], 0, v[130:131]
	ds_read_b128 v[186:189], v156 offset:32768
	ds_read_b128 v[190:193], v156 offset:33792
	ds_read_b128 v[194:197], v156 offset:34816
	ds_read_b128 v[198:201], v156 offset:35840
	ds_read_b128 v[202:205], v156 offset:36864
	ds_read_b128 v[206:209], v156 offset:37888
	ds_read_b128 v[210:213], v156 offset:38912
	ds_read_b128 v[214:217], v156 offset:39936
	global_load_lds_dwordx4 v[224:225], off
	v_lshl_add_u64 v[224:225], s[42:43], 0, v[134:135]
	s_mov_b32 m0, s46
	s_nop 0
	global_load_lds_dwordx4 v[224:225], off
	s_waitcnt vmcnt(8)
	s_waitcnt lgkmcnt(0)
	s_barrier
	s_setprio 1
	v_mfma_f32_16x16x32_bf16 v[126:129], v[146:149], v[186:189], v[126:129]
	v_mfma_f32_16x16x32_bf16 v[122:125], v[162:165], v[186:189], v[122:125]
	v_mfma_f32_16x16x32_bf16 v[110:113], v[146:149], v[194:197], v[110:113]
	v_mfma_f32_16x16x32_bf16 v[106:109], v[162:165], v[194:197], v[106:109]
	v_mfma_f32_16x16x32_bf16 v[94:97], v[146:149], v[202:205], v[94:97]
	v_mfma_f32_16x16x32_bf16 v[90:93], v[162:165], v[202:205], v[90:93]
	v_mfma_f32_16x16x32_bf16 v[78:81], v[146:149], v[210:213], v[78:81]
	v_mfma_f32_16x16x32_bf16 v[74:77], v[162:165], v[210:213], v[74:77]
	v_mfma_f32_16x16x32_bf16 v[126:129], v[158:161], v[190:193], v[126:129]
	v_mfma_f32_16x16x32_bf16 v[122:125], v[166:169], v[190:193], v[122:125]
	v_mfma_f32_16x16x32_bf16 v[110:113], v[158:161], v[198:201], v[110:113]
	v_mfma_f32_16x16x32_bf16 v[106:109], v[166:169], v[198:201], v[106:109]
	v_mfma_f32_16x16x32_bf16 v[94:97], v[158:161], v[206:209], v[94:97]
	v_mfma_f32_16x16x32_bf16 v[90:93], v[166:169], v[206:209], v[90:93]
	v_mfma_f32_16x16x32_bf16 v[78:81], v[158:161], v[214:217], v[78:81]
	v_mfma_f32_16x16x32_bf16 v[74:77], v[166:169], v[214:217], v[74:77]
	s_setprio 0
	s_setprio 1
	v_mfma_f32_16x16x32_bf16 v[118:121], v[170:173], v[186:189], v[118:121]
	v_mfma_f32_16x16x32_bf16 v[114:117], v[178:181], v[186:189], v[114:117]
	v_mfma_f32_16x16x32_bf16 v[102:105], v[170:173], v[194:197], v[102:105]
	v_mfma_f32_16x16x32_bf16 v[98:101], v[178:181], v[194:197], v[98:101]
	v_mfma_f32_16x16x32_bf16 v[86:89], v[170:173], v[202:205], v[86:89]
	v_mfma_f32_16x16x32_bf16 v[82:85], v[178:181], v[202:205], v[82:85]
	v_mfma_f32_16x16x32_bf16 v[70:73], v[170:173], v[210:213], v[70:73]
	v_mfma_f32_16x16x32_bf16 v[66:69], v[178:181], v[210:213], v[66:69]
	v_mfma_f32_16x16x32_bf16 v[118:121], v[174:177], v[190:193], v[118:121]
	v_mfma_f32_16x16x32_bf16 v[114:117], v[182:185], v[190:193], v[114:117]
	v_mfma_f32_16x16x32_bf16 v[102:105], v[174:177], v[198:201], v[102:105]
	v_mfma_f32_16x16x32_bf16 v[98:101], v[182:185], v[198:201], v[98:101]
	v_mfma_f32_16x16x32_bf16 v[86:89], v[174:177], v[206:209], v[86:89]
	v_mfma_f32_16x16x32_bf16 v[82:85], v[182:185], v[206:209], v[82:85]
	v_mfma_f32_16x16x32_bf16 v[70:73], v[174:177], v[214:217], v[70:73]
	v_mfma_f32_16x16x32_bf16 v[66:69], v[182:185], v[214:217], v[66:69]
	s_setprio 0
	s_barrier
; #define PG8_STAGE(bufoff, gbase, voff) do { _Pragma("unroll") for (int _i = 0; _i < 2; ++_i) \
;         __builtin_amdgcn_global_load_lds((const unsigned*)((const char*)(gbase) + (voff)[_i]), (PG8_LAS unsigned*)(lds + (bufoff) + ldsw + _i * 8192), 16, 0, 0); } while (0)
; #define PG8_LDA(dst, b, h) do { _Pragma("unroll") for (int m = 0; m < 4; ++m) _Pragma("unroll") for (int k = 0; k < 2; ++k) dst[m][k] = *(const PG8_LAS bf16x8*)(lds + PG8_SA(b, h) + aoff + m * 2048 + k * 1024); } while (0)
; #define PG8_MMA(ai, bj, At, Bt) do { __builtin_amdgcn_s_setprio(1); _Pragma("unroll") for (int m = 0; m < 4; ++m) _Pragma("unroll") for (int n = 0; n < 2; ++n) _Pragma("unroll") for (int k = 0; k < 2; ++k) \
;         acc[ai][bj][m][n] = __builtin_amdgcn_mfma_f32_16x16x32_bf16(Bt[n][k], At[m][k], acc[ai][bj][m][n], 0, 0, 0); __builtin_amdgcn_s_setprio(0); } while (0)
; #define PG8_WAIT_V(n) asm volatile("s_waitcnt vmcnt(" #n ")" ::: "memory")
; #define PG8_WAIT_L(n) asm volatile("s_waitcnt lgkmcnt(" #n ")" ::: "memory")
; #define PG8_BAR __builtin_amdgcn_s_barrier()
; #define PG8_SCHED __builtin_amdgcn_sched_barrier(0)
; template <class Epi, class Sched, bool ALIGN_EPI = false, bool SP2 = false>
; __device__ __forceinline__ void gemm_phase(PG8_LAS unsigned char* lds, const Gemm g, const Sched& S, const Epi& E) {
;     ...
;         for (int t = 0; t < nt; t += 2) {
;             const bool last = (t == nt - 2);
;             const char* a1 = cA + (size_t)(t + 1) * kstep;
;             const char* a2 = last ? nA : cA + (size_t)(t + 2) * kstep; const char* b2 = last ? nB : cB + (size_t)(t + 2) * kstep;
;     ...
;             PG8_LDA(At, 1, 1); PG8_STAGE(PG8_SB(1, 0), b3, voffB); PG8_STAGE(PG8_SB(1, 1), b3 + hstep, voffB); PG8_STAGE(PG8_SA(1, 0), a3, voffA);
;             PG8_WAIT_V(8); PG8_WAIT_L(0); PG8_BAR; PG8_MMA(1, 0, At, B0); PG8_MMA(1, 1, At, B1); PG8_BAR; PG8_SCHED;
	s_add_i32 s42, s59, s3
	v_lshl_add_u64 v[150:151], v[150:151], 0, s[10:11]
	s_mov_b32 m0, s42
	ds_read_b128 v[186:189], v156 offset:49152
	ds_read_b128 v[190:193], v156 offset:50176
	ds_read_b128 v[194:197], v156 offset:51200
	ds_read_b128 v[198:201], v156 offset:52224
	ds_read_b128 v[202:205], v156 offset:53248
	ds_read_b128 v[206:209], v156 offset:54272
	ds_read_b128 v[210:213], v156 offset:55296
	ds_read_b128 v[214:217], v156 offset:56320
	global_load_lds_dwordx4 v[150:151], off
	s_add_i32 m0, s42, 0x2000
	s_add_u32 s40, s40, 0x80080
	v_lshl_add_u64 v[150:151], v[218:219], 0, s[10:11]
	s_addc_u32 s41, s41, 0
	s_add_i32 s42, s60, s3
	global_load_lds_dwordx4 v[150:151], off
	v_lshl_add_u64 v[150:151], s[40:41], 0, v[132:133]
	s_mov_b32 m0, s42
	s_nop 0
	global_load_lds_dwordx4 v[150:151], off
	v_lshl_add_u64 v[150:151], s[40:41], 0, v[136:137]
	s_add_i32 m0, s42, 0x2000
	s_nop 0
	global_load_lds_dwordx4 v[150:151], off
	v_lshl_add_u64 v[150:151], v[220:221], 0, s[10:11]
	s_mov_b32 m0, s48
	s_nop 0
	global_load_lds_dwordx4 v[150:151], off
	v_lshl_add_u64 v[150:151], v[222:223], 0, s[10:11]
	s_mov_b32 m0, s49
	s_nop 0
	global_load_lds_dwordx4 v[150:151], off
	s_waitcnt vmcnt(8)
	s_waitcnt lgkmcnt(0)
	s_barrier
	s_setprio 1
	v_mfma_f32_16x16x32_bf16 v[62:65], v[146:149], v[186:189], v[62:65]
	v_mfma_f32_16x16x32_bf16 v[58:61], v[162:165], v[186:189], v[58:61]
	v_mfma_f32_16x16x32_bf16 v[46:49], v[146:149], v[194:197], v[46:49]
	v_mfma_f32_16x16x32_bf16 v[42:45], v[162:165], v[194:197], v[42:45]
	v_mfma_f32_16x16x32_bf16 v[30:33], v[146:149], v[202:205], v[30:33]
	v_mfma_f32_16x16x32_bf16 v[26:29], v[162:165], v[202:205], v[26:29]
	v_mfma_f32_16x16x32_bf16 v[14:17], v[146:149], v[210:213], v[14:17]
	v_mfma_f32_16x16x32_bf16 v[10:13], v[162:165], v[210:213], v[10:13]
	v_mfma_f32_16x16x32_bf16 v[62:65], v[158:161], v[190:193], v[62:65]
	v_mfma_f32_16x16x32_bf16 v[58:61], v[166:169], v[190:193], v[58:61]
	v_mfma_f32_16x16x32_bf16 v[46:49], v[158:161], v[198:201], v[46:49]
	v_mfma_f32_16x16x32_bf16 v[42:45], v[166:169], v[198:201], v[42:45]
	v_mfma_f32_16x16x32_bf16 v[30:33], v[158:161], v[206:209], v[30:33]
	v_mfma_f32_16x16x32_bf16 v[26:29], v[166:169], v[206:209], v[26:29]
	v_mfma_f32_16x16x32_bf16 v[14:17], v[158:161], v[214:217], v[14:17]
	v_mfma_f32_16x16x32_bf16 v[10:13], v[166:169], v[214:217], v[10:13]
	s_setprio 0
	s_setprio 1
	v_mfma_f32_16x16x32_bf16 v[54:57], v[170:173], v[186:189], v[54:57]
	v_mfma_f32_16x16x32_bf16 v[50:53], v[178:181], v[186:189], v[50:53]
	v_mfma_f32_16x16x32_bf16 v[38:41], v[170:173], v[194:197], v[38:41]
	v_mfma_f32_16x16x32_bf16 v[34:37], v[178:181], v[194:197], v[34:37]
	v_mfma_f32_16x16x32_bf16 v[22:25], v[170:173], v[202:205], v[22:25]
	v_mfma_f32_16x16x32_bf16 v[18:21], v[178:181], v[202:205], v[18:21]
	v_mfma_f32_16x16x32_bf16 v[6:9], v[170:173], v[210:213], v[6:9]
	v_mfma_f32_16x16x32_bf16 v[2:5], v[178:181], v[210:213], v[2:5]
	v_mfma_f32_16x16x32_bf16 v[54:57], v[174:177], v[190:193], v[54:57]
	v_mfma_f32_16x16x32_bf16 v[50:53], v[182:185], v[190:193], v[50:53]
	v_mfma_f32_16x16x32_bf16 v[38:41], v[174:177], v[198:201], v[38:41]
	v_mfma_f32_16x16x32_bf16 v[34:37], v[182:185], v[198:201], v[34:37]
	v_mfma_f32_16x16x32_bf16 v[22:25], v[174:177], v[206:209], v[22:25]
	v_mfma_f32_16x16x32_bf16 v[18:21], v[182:185], v[206:209], v[18:21]
	v_mfma_f32_16x16x32_bf16 v[6:9], v[174:177], v[214:217], v[6:9]
	v_mfma_f32_16x16x32_bf16 v[2:5], v[182:185], v[214:217], v[2:5]
	s_setprio 0
	s_barrier
	s_add_i32 s58, s58, 2
	s_add_u32 s38, s38, 0x100
	s_addc_u32 s39, s39, 0
	s_add_u32 s56, s56, 0x100
	s_addc_u32 s57, s57, 0
	s_cmp_gt_u32 s58, 29
	s_cbranch_scc0 .LBB0_2176
	s_and_b64 vcc, exec, s[12:13]
	s_cbranch_vccz .LBB0_2179
	s_barrier
